# setprio1 before barrier, drop mid flips and redundant lgkmcnt, setprio0 after barrier in all GEMM K-loops
# speedup vs baseline: 1.0046x; 1.0046x over previous
; #define PG8_STAGE(bufoff, gbase, voff) do { _Pragma("unroll") for (int _i = 0; _i < 2; ++_i) \
;         __builtin_amdgcn_global_load_lds((const unsigned*)((const char*)(gbase) + (voff)[_i]), (PG8_LAS unsigned*)(lds + (bufoff) + ldsw + _i * 8192), 16, 0, 0); } while (0)
; #define PG8_LDA(dst, b, h) do { _Pragma("unroll") for (int m = 0; m < 4; ++m) _Pragma("unroll") for (int k = 0; k < 2; ++k) dst[m][k] = *(const PG8_LAS bf16x8*)(lds + PG8_SA(b, h) + aoff + m * 2048 + k * 1024); } while (0)
; #define PG8_LDB(dst, b, h) do { _Pragma("unroll") for (int n = 0; n < 2; ++n) _Pragma("unroll") for (int k = 0; k < 2; ++k) dst[n][k] = *(const PG8_LAS bf16x8*)(lds + PG8_SB(b, h) + boff + n * 2048 + k * 1024); } while (0)
; #define PG8_WAIT_V(n) asm volatile("s_waitcnt vmcnt(" #n ")" ::: "memory")
; #define PG8_WAIT_L(n) asm volatile("s_waitcnt lgkmcnt(" #n ")" ::: "memory")
; #define PG8_BAR __builtin_amdgcn_s_barrier()
; #define PG8_SCHED __builtin_amdgcn_sched_barrier(0)
; template <class Epi, class Sched, bool ALIGN_EPI = false, bool SP2 = false, bool F8 = false>
; __device__ __forceinline__ void gemm_phase(PG8_LAS unsigned char* lds, const Gemm g, const Sched& S, const Epi& E) {
;     ...
;             const char* a1 = cA + (size_t)(t + 1) * kstep;
;             const char* a2 = last ? nA : cA + (size_t)(t + 2) * kstep; const char* b2 = last ? nB : cB + (size_t)(t + 2) * kstep;
;             const char* a3 = a2 + kstep; const char* b3 = b2 + kstep;
;             if (last && has_next) S.a_ready(nxt);
;             if constexpr (SP2) {
;             PG8_LDB(B0, 0, 0); PG8_LDB(B1, 0, 1); PG8_SCHED; PG8_LDA(At, 0, 0); PG8_STAGE(PG8_SA(1, 1), a1 + hA, voffA);
;             PG8_WAIT_V(8); PG8_WAIT_L(0); PG8_BAR; PG8_MMA(0, 0, At, B0); PG8_MMA(0, 1, At, B1); PG8_BAR; PG8_SCHED;
;             PG8_LDA(At, 0, 1); PG8_STAGE(PG8_SB(0, 0), b2, voffB); PG8_STAGE(PG8_SB(0, 1), b2 + hB, voffB); PG8_STAGE(PG8_SA(0, 0), a2, voffA);
.LBB0_128:
	ds_read_b128 v[152:155], v149
	ds_read_b128 v[156:159], v149 offset:1024
	ds_read_b128 v[160:163], v149 offset:2048
	ds_read_b128 v[164:167], v149 offset:3072
	ds_read_b128 v[168:171], v150
	ds_read_b128 v[172:175], v150 offset:1024
	ds_read_b128 v[176:179], v150 offset:2048
	ds_read_b128 v[180:183], v150 offset:3072
	s_add_u32 s40, s38, 0xfff00080
	s_addc_u32 s41, s39, -1
	s_cmp_eq_u32 s66, 60
	s_cselect_b32 s43, s31, s41
	s_cselect_b32 s42, s62, s40
	s_cselect_b32 s41, s29, s65
	s_cselect_b32 s40, s63, s64
	v_lshl_add_u64 v[216:217], s[38:39], 0, v[140:141]
	s_add_i32 m0, s27, 0xc000
	ds_read_b128 v[184:187], v151
	ds_read_b128 v[188:191], v151 offset:1024
	ds_read_b128 v[192:195], v151 offset:2048
	ds_read_b128 v[196:199], v151 offset:3072
	ds_read_b128 v[200:203], v151 offset:4096
	ds_read_b128 v[204:207], v151 offset:5120
	ds_read_b128 v[208:211], v151 offset:6144
	ds_read_b128 v[212:215], v151 offset:7168
	global_load_lds_dwordx4 v[216:217], off
	v_lshl_add_u64 v[216:217], s[38:39], 0, v[138:139]
	s_add_i32 m0, s27, 0xe000
	s_nop 0
	global_load_lds_dwordx4 v[216:217], off
	s_waitcnt vmcnt(8)
	s_waitcnt lgkmcnt(0)
	s_setprio 1
	s_barrier
	v_mfma_f32_16x16x32_bf16 v[126:129], v[152:155], v[184:187], v[126:129]
	v_mfma_f32_16x16x32_bf16 v[122:125], v[160:163], v[184:187], v[122:125]
	v_mfma_f32_16x16x32_bf16 v[118:121], v[152:155], v[192:195], v[118:121]
	v_mfma_f32_16x16x32_bf16 v[114:117], v[160:163], v[192:195], v[114:117]
	v_mfma_f32_16x16x32_bf16 v[102:105], v[152:155], v[200:203], v[102:105]
	v_mfma_f32_16x16x32_bf16 v[98:101], v[160:163], v[200:203], v[98:101]
	v_mfma_f32_16x16x32_bf16 v[86:89], v[152:155], v[208:211], v[86:89]
	v_mfma_f32_16x16x32_bf16 v[82:85], v[160:163], v[208:211], v[82:85]
	v_mfma_f32_16x16x32_bf16 v[126:129], v[156:159], v[188:191], v[126:129]
	v_mfma_f32_16x16x32_bf16 v[122:125], v[164:167], v[188:191], v[122:125]
	v_mfma_f32_16x16x32_bf16 v[118:121], v[156:159], v[196:199], v[118:121]
	v_mfma_f32_16x16x32_bf16 v[114:117], v[164:167], v[196:199], v[114:117]
	v_mfma_f32_16x16x32_bf16 v[102:105], v[156:159], v[204:207], v[102:105]
	v_mfma_f32_16x16x32_bf16 v[98:101], v[164:167], v[204:207], v[98:101]
	v_mfma_f32_16x16x32_bf16 v[86:89], v[156:159], v[212:215], v[86:89]
	v_mfma_f32_16x16x32_bf16 v[82:85], v[164:167], v[212:215], v[82:85]
	v_mfma_f32_16x16x32_bf16 v[110:113], v[168:171], v[184:187], v[110:113]
	v_mfma_f32_16x16x32_bf16 v[106:109], v[176:179], v[184:187], v[106:109]
	v_mfma_f32_16x16x32_bf16 v[94:97], v[168:171], v[192:195], v[94:97]
	v_mfma_f32_16x16x32_bf16 v[90:93], v[176:179], v[192:195], v[90:93]
	v_mfma_f32_16x16x32_bf16 v[78:81], v[168:171], v[200:203], v[78:81]
	v_mfma_f32_16x16x32_bf16 v[74:77], v[176:179], v[200:203], v[74:77]
	v_mfma_f32_16x16x32_bf16 v[70:73], v[168:171], v[208:211], v[70:73]
	v_mfma_f32_16x16x32_bf16 v[66:69], v[176:179], v[208:211], v[66:69]
	v_mfma_f32_16x16x32_bf16 v[110:113], v[172:175], v[188:191], v[110:113]
	v_mfma_f32_16x16x32_bf16 v[106:109], v[180:183], v[188:191], v[106:109]
	v_mfma_f32_16x16x32_bf16 v[94:97], v[172:175], v[196:199], v[94:97]
	v_mfma_f32_16x16x32_bf16 v[90:93], v[180:183], v[196:199], v[90:93]
	v_mfma_f32_16x16x32_bf16 v[78:81], v[172:175], v[204:207], v[78:81]
	v_mfma_f32_16x16x32_bf16 v[74:77], v[180:183], v[204:207], v[74:77]
	v_mfma_f32_16x16x32_bf16 v[70:73], v[172:175], v[212:215], v[70:73]
	v_mfma_f32_16x16x32_bf16 v[66:69], v[180:183], v[212:215], v[66:69]
	s_barrier
	s_setprio 0
	s_add_i32 s67, s55, s45
	v_lshl_add_u64 v[216:217], s[40:41], 0, v[134:135]
	s_mov_b32 m0, s67
	ds_read_b128 v[184:187], v151 offset:16384
	ds_read_b128 v[188:191], v151 offset:17408
	ds_read_b128 v[192:195], v151 offset:18432
	ds_read_b128 v[196:199], v151 offset:19456
	ds_read_b128 v[200:203], v151 offset:20480
	ds_read_b128 v[204:207], v151 offset:21504
	ds_read_b128 v[208:211], v151 offset:22528
	ds_read_b128 v[212:215], v151 offset:23552
	global_load_lds_dwordx4 v[216:217], off
	s_add_i32 m0, s67, 0x2000
	s_add_u32 s70, s40, 0x100000
	v_lshl_add_u64 v[218:219], s[40:41], 0, v[130:131]
	s_addc_u32 s71, s41, 0
	s_add_i32 s67, s56, s45
	global_load_lds_dwordx4 v[218:219], off
	v_lshl_add_u64 v[220:221], s[70:71], 0, v[134:135]
	s_mov_b32 m0, s67
	v_lshl_add_u64 v[222:223], s[42:43], 0, v[132:133]
	global_load_lds_dwordx4 v[220:221], off
	v_lshl_add_u64 v[220:221], s[70:71], 0, v[130:131]
	s_add_i32 m0, s67, 0x2000
	s_nop 0
	global_load_lds_dwordx4 v[220:221], off
	v_lshl_add_u64 v[220:221], s[42:43], 0, v[136:137]
	s_mov_b32 m0, s27
	s_nop 0
	global_load_lds_dwordx4 v[220:221], off
	s_mov_b32 m0, s48
	s_nop 0
	global_load_lds_dwordx4 v[222:223], off
	s_waitcnt vmcnt(8)
	s_waitcnt lgkmcnt(0)
	s_setprio 1
	s_barrier
; #define PG8_STAGE(bufoff, gbase, voff) do { _Pragma("unroll") for (int _i = 0; _i < 2; ++_i) \
;         __builtin_amdgcn_global_load_lds((const unsigned*)((const char*)(gbase) + (voff)[_i]), (PG8_LAS unsigned*)(lds + (bufoff) + ldsw + _i * 8192), 16, 0, 0); } while (0)
; #define PG8_LDA(dst, b, h) do { _Pragma("unroll") for (int m = 0; m < 4; ++m) _Pragma("unroll") for (int k = 0; k < 2; ++k) dst[m][k] = *(const PG8_LAS bf16x8*)(lds + PG8_SA(b, h) + aoff + m * 2048 + k * 1024); } while (0)
; #define PG8_LDB(dst, b, h) do { _Pragma("unroll") for (int n = 0; n < 2; ++n) _Pragma("unroll") for (int k = 0; k < 2; ++k) dst[n][k] = *(const PG8_LAS bf16x8*)(lds + PG8_SB(b, h) + boff + n * 2048 + k * 1024); } while (0)
; #define PG8_WAIT_V(n) asm volatile("s_waitcnt vmcnt(" #n ")" ::: "memory")
; #define PG8_WAIT_L(n) asm volatile("s_waitcnt lgkmcnt(" #n ")" ::: "memory")
; #define PG8_BAR __builtin_amdgcn_s_barrier()
; #define PG8_SCHED __builtin_amdgcn_sched_barrier(0)
; template <class Epi, class Sched, bool ALIGN_EPI = false, bool SP2 = false, bool F8 = false>
; __device__ __forceinline__ void gemm_phase(PG8_LAS unsigned char* lds, const Gemm g, const Sched& S, const Epi& E) {
;     ...
;             PG8_LDA(At, 0, 1); PG8_STAGE(PG8_SB(0, 0), b2, voffB); PG8_STAGE(PG8_SB(0, 1), b2 + hB, voffB); PG8_STAGE(PG8_SA(0, 0), a2, voffA);
;             PG8_WAIT_V(8); PG8_WAIT_L(0); PG8_BAR; PG8_MMA(1, 0, At, B0); PG8_MMA(1, 1, At, B1); PG8_BAR; PG8_SCHED;
;             PG8_LDB(B0, 1, 0); PG8_LDB(B1, 1, 1); PG8_SCHED; PG8_LDA(At, 1, 0); PG8_STAGE(PG8_SA(0, 1), a2 + hA, voffA);
;             PG8_WAIT_V(8); PG8_WAIT_L(0); PG8_BAR; PG8_MMA(0, 0, At, B0); PG8_MMA(0, 1, At, B1); PG8_BAR; PG8_SCHED;
;             PG8_LDA(At, 1, 1); PG8_STAGE(PG8_SB(1, 0), b3, voffB); PG8_STAGE(PG8_SB(1, 1), b3 + hB, voffB); PG8_STAGE(PG8_SA(1, 0), a3, voffA);
	v_mfma_f32_16x16x32_bf16 v[62:65], v[152:155], v[184:187], v[62:65]
	v_mfma_f32_16x16x32_bf16 v[58:61], v[160:163], v[184:187], v[58:61]
	v_mfma_f32_16x16x32_bf16 v[54:57], v[152:155], v[192:195], v[54:57]
	v_mfma_f32_16x16x32_bf16 v[50:53], v[160:163], v[192:195], v[50:53]
	v_mfma_f32_16x16x32_bf16 v[38:41], v[152:155], v[200:203], v[38:41]
	v_mfma_f32_16x16x32_bf16 v[34:37], v[160:163], v[200:203], v[34:37]
	v_mfma_f32_16x16x32_bf16 v[22:25], v[152:155], v[208:211], v[22:25]
	v_mfma_f32_16x16x32_bf16 v[18:21], v[160:163], v[208:211], v[18:21]
	v_mfma_f32_16x16x32_bf16 v[62:65], v[156:159], v[188:191], v[62:65]
	v_mfma_f32_16x16x32_bf16 v[58:61], v[164:167], v[188:191], v[58:61]
	v_mfma_f32_16x16x32_bf16 v[54:57], v[156:159], v[196:199], v[54:57]
	v_mfma_f32_16x16x32_bf16 v[50:53], v[164:167], v[196:199], v[50:53]
	v_mfma_f32_16x16x32_bf16 v[38:41], v[156:159], v[204:207], v[38:41]
	v_mfma_f32_16x16x32_bf16 v[34:37], v[164:167], v[204:207], v[34:37]
	v_mfma_f32_16x16x32_bf16 v[22:25], v[156:159], v[212:215], v[22:25]
	v_mfma_f32_16x16x32_bf16 v[18:21], v[164:167], v[212:215], v[18:21]
	v_mfma_f32_16x16x32_bf16 v[46:49], v[168:171], v[184:187], v[46:49]
	v_mfma_f32_16x16x32_bf16 v[42:45], v[176:179], v[184:187], v[42:45]
	v_mfma_f32_16x16x32_bf16 v[30:33], v[168:171], v[192:195], v[30:33]
	v_mfma_f32_16x16x32_bf16 v[26:29], v[176:179], v[192:195], v[26:29]
	v_mfma_f32_16x16x32_bf16 v[14:17], v[168:171], v[200:203], v[14:17]
	v_mfma_f32_16x16x32_bf16 v[10:13], v[176:179], v[200:203], v[10:13]
	v_mfma_f32_16x16x32_bf16 v[6:9], v[168:171], v[208:211], v[6:9]
	v_mfma_f32_16x16x32_bf16 v[2:5], v[176:179], v[208:211], v[2:5]
	v_mfma_f32_16x16x32_bf16 v[46:49], v[172:175], v[188:191], v[46:49]
	v_mfma_f32_16x16x32_bf16 v[42:45], v[180:183], v[188:191], v[42:45]
	v_mfma_f32_16x16x32_bf16 v[30:33], v[172:175], v[196:199], v[30:33]
	v_mfma_f32_16x16x32_bf16 v[26:29], v[180:183], v[196:199], v[26:29]
	v_mfma_f32_16x16x32_bf16 v[14:17], v[172:175], v[204:207], v[14:17]
	v_mfma_f32_16x16x32_bf16 v[10:13], v[180:183], v[204:207], v[10:13]
	v_mfma_f32_16x16x32_bf16 v[6:9], v[172:175], v[212:215], v[6:9]
	v_mfma_f32_16x16x32_bf16 v[2:5], v[180:183], v[212:215], v[2:5]
	s_barrier
	s_setprio 0
	s_add_i32 s67, 0, 0x18000
	s_add_i32 s69, 0, 0x1c000
	v_add_u32_e32 v164, s67, v147
	v_add_u32_e32 v180, s69, v147
	ds_read_b128 v[152:155], v164
	ds_read_b128 v[156:159], v164 offset:1024
	ds_read_b128 v[160:163], v164 offset:2048
	ds_read_b128 v[164:167], v164 offset:3072
	ds_read_b128 v[168:171], v180
	ds_read_b128 v[172:175], v180 offset:1024
	ds_read_b128 v[176:179], v180 offset:2048
	ds_read_b128 v[180:183], v180 offset:3072
	s_add_u32 s42, s42, 0x100000
	s_addc_u32 s43, s43, 0
	s_mov_b32 m0, s49
	v_lshl_add_u64 v[224:225], s[42:43], 0, v[136:137]
	ds_read_b128 v[184:187], v151 offset:32768
	ds_read_b128 v[188:191], v151 offset:33792
	ds_read_b128 v[192:195], v151 offset:34816
	ds_read_b128 v[196:199], v151 offset:35840
	ds_read_b128 v[200:203], v151 offset:36864
	ds_read_b128 v[204:207], v151 offset:37888
	ds_read_b128 v[208:211], v151 offset:38912
	ds_read_b128 v[212:215], v151 offset:39936
	global_load_lds_dwordx4 v[224:225], off
	v_lshl_add_u64 v[224:225], s[42:43], 0, v[132:133]
	s_mov_b32 m0, s50
	s_nop 0
	global_load_lds_dwordx4 v[224:225], off
	s_waitcnt vmcnt(8)
	s_waitcnt lgkmcnt(0)
	s_setprio 1
	s_barrier
	v_mfma_f32_16x16x32_bf16 v[126:129], v[152:155], v[184:187], v[126:129]
	v_mfma_f32_16x16x32_bf16 v[122:125], v[160:163], v[184:187], v[122:125]
	v_mfma_f32_16x16x32_bf16 v[118:121], v[152:155], v[192:195], v[118:121]
	v_mfma_f32_16x16x32_bf16 v[114:117], v[160:163], v[192:195], v[114:117]
	v_mfma_f32_16x16x32_bf16 v[102:105], v[152:155], v[200:203], v[102:105]
	v_mfma_f32_16x16x32_bf16 v[98:101], v[160:163], v[200:203], v[98:101]
	v_mfma_f32_16x16x32_bf16 v[86:89], v[152:155], v[208:211], v[86:89]
	v_mfma_f32_16x16x32_bf16 v[82:85], v[160:163], v[208:211], v[82:85]
	v_mfma_f32_16x16x32_bf16 v[126:129], v[156:159], v[188:191], v[126:129]
	v_mfma_f32_16x16x32_bf16 v[122:125], v[164:167], v[188:191], v[122:125]
	v_mfma_f32_16x16x32_bf16 v[118:121], v[156:159], v[196:199], v[118:121]
	v_mfma_f32_16x16x32_bf16 v[114:117], v[164:167], v[196:199], v[114:117]
	v_mfma_f32_16x16x32_bf16 v[102:105], v[156:159], v[204:207], v[102:105]
	v_mfma_f32_16x16x32_bf16 v[98:101], v[164:167], v[204:207], v[98:101]
	v_mfma_f32_16x16x32_bf16 v[86:89], v[156:159], v[212:215], v[86:89]
	v_mfma_f32_16x16x32_bf16 v[82:85], v[164:167], v[212:215], v[82:85]
	v_mfma_f32_16x16x32_bf16 v[110:113], v[168:171], v[184:187], v[110:113]
	v_mfma_f32_16x16x32_bf16 v[106:109], v[176:179], v[184:187], v[106:109]
	v_mfma_f32_16x16x32_bf16 v[94:97], v[168:171], v[192:195], v[94:97]
	v_mfma_f32_16x16x32_bf16 v[90:93], v[176:179], v[192:195], v[90:93]
	v_mfma_f32_16x16x32_bf16 v[78:81], v[168:171], v[200:203], v[78:81]
	v_mfma_f32_16x16x32_bf16 v[74:77], v[176:179], v[200:203], v[74:77]
	v_mfma_f32_16x16x32_bf16 v[70:73], v[168:171], v[208:211], v[70:73]
	v_mfma_f32_16x16x32_bf16 v[66:69], v[176:179], v[208:211], v[66:69]
	v_mfma_f32_16x16x32_bf16 v[110:113], v[172:175], v[188:191], v[110:113]
	v_mfma_f32_16x16x32_bf16 v[106:109], v[180:183], v[188:191], v[106:109]
	v_mfma_f32_16x16x32_bf16 v[94:97], v[172:175], v[196:199], v[94:97]
	v_mfma_f32_16x16x32_bf16 v[90:93], v[180:183], v[196:199], v[90:93]
	v_mfma_f32_16x16x32_bf16 v[78:81], v[172:175], v[204:207], v[78:81]
	v_mfma_f32_16x16x32_bf16 v[74:77], v[180:183], v[204:207], v[74:77]
	v_mfma_f32_16x16x32_bf16 v[70:73], v[172:175], v[212:215], v[70:73]
	v_mfma_f32_16x16x32_bf16 v[66:69], v[180:183], v[212:215], v[66:69]
	s_barrier
; #define PG8_STAGE(bufoff, gbase, voff) do { _Pragma("unroll") for (int _i = 0; _i < 2; ++_i) \
;         __builtin_amdgcn_global_load_lds((const unsigned*)((const char*)(gbase) + (voff)[_i]), (PG8_LAS unsigned*)(lds + (bufoff) + ldsw + _i * 8192), 16, 0, 0); } while (0)
; #define PG8_LDA(dst, b, h) do { _Pragma("unroll") for (int m = 0; m < 4; ++m) _Pragma("unroll") for (int k = 0; k < 2; ++k) dst[m][k] = *(const PG8_LAS bf16x8*)(lds + PG8_SA(b, h) + aoff + m * 2048 + k * 1024); } while (0)
; #define PG8_WAIT_V(n) asm volatile("s_waitcnt vmcnt(" #n ")" ::: "memory")
; #define PG8_WAIT_L(n) asm volatile("s_waitcnt lgkmcnt(" #n ")" ::: "memory")
; #define PG8_BAR __builtin_amdgcn_s_barrier()
; #define PG8_SCHED __builtin_amdgcn_sched_barrier(0)
; template <class Epi, class Sched, bool ALIGN_EPI = false, bool SP2 = false, bool F8 = false>
; __device__ __forceinline__ void gemm_phase(PG8_LAS unsigned char* lds, const Gemm g, const Sched& S, const Epi& E) {
;     ...
;             PG8_LDA(At, 1, 1); PG8_STAGE(PG8_SB(1, 0), b3, voffB); PG8_STAGE(PG8_SB(1, 1), b3 + hB, voffB); PG8_STAGE(PG8_SA(1, 0), a3, voffA);
;             PG8_WAIT_V(8); PG8_WAIT_L(0); PG8_BAR; PG8_MMA(1, 0, At, B0); PG8_MMA(1, 1, At, B1); PG8_BAR; PG8_SCHED;
;     ...
;         if constexpr (ALIGN_EPI) { if (wr == 0) PG8_BAR; }
	s_setprio 0
	s_add_i32 s42, s67, s45
	v_lshl_add_u64 v[216:217], v[216:217], 0, s[12:13]
	s_mov_b32 m0, s42
	ds_read_b128 v[184:187], v151 offset:49152
	ds_read_b128 v[188:191], v151 offset:50176
	ds_read_b128 v[192:195], v151 offset:51200
	ds_read_b128 v[196:199], v151 offset:52224
	ds_read_b128 v[200:203], v151 offset:53248
	ds_read_b128 v[204:207], v151 offset:54272
	ds_read_b128 v[208:211], v151 offset:55296
	ds_read_b128 v[212:215], v151 offset:56320
	global_load_lds_dwordx4 v[216:217], off
	s_add_i32 m0, s42, 0x2000
	s_add_u32 s40, s40, 0x100080
	v_lshl_add_u64 v[216:217], v[218:219], 0, s[12:13]
	s_addc_u32 s41, s41, 0
	s_add_i32 s42, s69, s45
	global_load_lds_dwordx4 v[216:217], off
	v_lshl_add_u64 v[216:217], s[40:41], 0, v[134:135]
	s_mov_b32 m0, s42
	s_nop 0
	global_load_lds_dwordx4 v[216:217], off
	v_lshl_add_u64 v[216:217], s[40:41], 0, v[130:131]
	s_add_i32 m0, s42, 0x2000
	s_nop 0
	global_load_lds_dwordx4 v[216:217], off
	v_lshl_add_u64 v[216:217], v[220:221], 0, s[12:13]
	s_mov_b32 m0, s52
	s_nop 0
	global_load_lds_dwordx4 v[216:217], off
	v_lshl_add_u64 v[216:217], v[222:223], 0, s[12:13]
	s_mov_b32 m0, s53
	s_nop 0
	global_load_lds_dwordx4 v[216:217], off
	s_waitcnt vmcnt(8)
	s_waitcnt lgkmcnt(0)
	s_setprio 1
	s_barrier
	v_mfma_f32_16x16x32_bf16 v[62:65], v[152:155], v[184:187], v[62:65]
	v_mfma_f32_16x16x32_bf16 v[58:61], v[160:163], v[184:187], v[58:61]
	v_mfma_f32_16x16x32_bf16 v[54:57], v[152:155], v[192:195], v[54:57]
	v_mfma_f32_16x16x32_bf16 v[50:53], v[160:163], v[192:195], v[50:53]
	v_mfma_f32_16x16x32_bf16 v[38:41], v[152:155], v[200:203], v[38:41]
	v_mfma_f32_16x16x32_bf16 v[34:37], v[160:163], v[200:203], v[34:37]
	v_mfma_f32_16x16x32_bf16 v[22:25], v[152:155], v[208:211], v[22:25]
	v_mfma_f32_16x16x32_bf16 v[18:21], v[160:163], v[208:211], v[18:21]
	v_mfma_f32_16x16x32_bf16 v[62:65], v[156:159], v[188:191], v[62:65]
	v_mfma_f32_16x16x32_bf16 v[58:61], v[164:167], v[188:191], v[58:61]
	v_mfma_f32_16x16x32_bf16 v[54:57], v[156:159], v[196:199], v[54:57]
	v_mfma_f32_16x16x32_bf16 v[50:53], v[164:167], v[196:199], v[50:53]
	v_mfma_f32_16x16x32_bf16 v[38:41], v[156:159], v[204:207], v[38:41]
	v_mfma_f32_16x16x32_bf16 v[34:37], v[164:167], v[204:207], v[34:37]
	v_mfma_f32_16x16x32_bf16 v[22:25], v[156:159], v[212:215], v[22:25]
	v_mfma_f32_16x16x32_bf16 v[18:21], v[164:167], v[212:215], v[18:21]
	v_mfma_f32_16x16x32_bf16 v[46:49], v[168:171], v[184:187], v[46:49]
	v_mfma_f32_16x16x32_bf16 v[42:45], v[176:179], v[184:187], v[42:45]
	v_mfma_f32_16x16x32_bf16 v[30:33], v[168:171], v[192:195], v[30:33]
	v_mfma_f32_16x16x32_bf16 v[26:29], v[176:179], v[192:195], v[26:29]
	v_mfma_f32_16x16x32_bf16 v[14:17], v[168:171], v[200:203], v[14:17]
	v_mfma_f32_16x16x32_bf16 v[10:13], v[176:179], v[200:203], v[10:13]
	v_mfma_f32_16x16x32_bf16 v[6:9], v[168:171], v[208:211], v[6:9]
	v_mfma_f32_16x16x32_bf16 v[2:5], v[176:179], v[208:211], v[2:5]
	v_mfma_f32_16x16x32_bf16 v[46:49], v[172:175], v[188:191], v[46:49]
	v_mfma_f32_16x16x32_bf16 v[42:45], v[180:183], v[188:191], v[42:45]
	v_mfma_f32_16x16x32_bf16 v[30:33], v[172:175], v[196:199], v[30:33]
	v_mfma_f32_16x16x32_bf16 v[26:29], v[180:183], v[196:199], v[26:29]
	v_mfma_f32_16x16x32_bf16 v[14:17], v[172:175], v[204:207], v[14:17]
	v_mfma_f32_16x16x32_bf16 v[10:13], v[180:183], v[204:207], v[10:13]
	v_mfma_f32_16x16x32_bf16 v[6:9], v[172:175], v[212:215], v[6:9]
	v_mfma_f32_16x16x32_bf16 v[2:5], v[180:183], v[212:215], v[2:5]
	s_barrier
	s_setprio 0
	s_add_i32 s66, s66, 2
	s_add_u32 s64, s64, 0x100
	s_addc_u32 s65, s65, 0
	s_add_u32 s38, s38, 0x100
	s_addc_u32 s39, s39, 0
	s_cmp_gt_u32 s66, 61
	s_cbranch_scc0 .LBB0_128
	s_and_b64 vcc, exec, s[14:15]
	s_cbranch_vccz .LBB0_131
	s_barrier

; #define PG8_STAGE(bufoff, gbase, voff) do { _Pragma("unroll") for (int _i = 0; _i < 2; ++_i) \
;         __builtin_amdgcn_global_load_lds((const unsigned*)((const char*)(gbase) + (voff)[_i]), (PG8_LAS unsigned*)(lds + (bufoff) + ldsw + _i * 8192), 16, 0, 0); } while (0)
; #define PG8_LDA(dst, b, h) do { _Pragma("unroll") for (int m = 0; m < 4; ++m) _Pragma("unroll") for (int k = 0; k < 2; ++k) dst[m][k] = *(const PG8_LAS bf16x8*)(lds + PG8_SA(b, h) + aoff + m * 2048 + k * 1024); } while (0)
; #define PG8_LDB(dst, b, h) do { _Pragma("unroll") for (int n = 0; n < 2; ++n) _Pragma("unroll") for (int k = 0; k < 2; ++k) dst[n][k] = *(const PG8_LAS bf16x8*)(lds + PG8_SB(b, h) + boff + n * 2048 + k * 1024); } while (0)
; #define PG8_WAIT_V(n) asm volatile("s_waitcnt vmcnt(" #n ")" ::: "memory")
; #define PG8_WAIT_L(n) asm volatile("s_waitcnt lgkmcnt(" #n ")" ::: "memory")
; #define PG8_BAR __builtin_amdgcn_s_barrier()
; #define PG8_SCHED __builtin_amdgcn_sched_barrier(0)
; template <class Epi, class Sched, bool ALIGN_EPI = false, bool SP2 = false, bool F8 = false>
; __device__ __forceinline__ void gemm_phase(PG8_LAS unsigned char* lds, const Gemm g, const Sched& S, const Epi& E) {
;     ...
;         for (int t = 0; t < nt; t += 2) {
;             const bool last = (t == nt - 2);
;             const char* a1 = cA + (size_t)(t + 1) * kstep;
;             const char* a2 = last ? nA : cA + (size_t)(t + 2) * kstep; const char* b2 = last ? nB : cB + (size_t)(t + 2) * kstep;
;             const char* a3 = a2 + kstep; const char* b3 = b2 + kstep;
;             if (last && has_next) S.a_ready(nxt);
;             if constexpr (SP2) {
;             PG8_LDB(B0, 0, 0); PG8_LDB(B1, 0, 1); PG8_SCHED; PG8_LDA(At, 0, 0); PG8_STAGE(PG8_SA(1, 1), a1 + hA, voffA);
;             PG8_WAIT_V(8); PG8_WAIT_L(0); PG8_BAR; PG8_MMA(0, 0, At, B0); PG8_MMA(0, 1, At, B1); PG8_BAR; PG8_SCHED;
;             PG8_LDA(At, 0, 1); PG8_STAGE(PG8_SB(0, 0), b2, voffB); PG8_STAGE(PG8_SB(0, 1), b2 + hB, voffB); PG8_STAGE(PG8_SA(0, 0), a2, voffA);
;             PG8_WAIT_V(8); PG8_WAIT_L(0); PG8_BAR; PG8_MMA(1, 0, At, B0); PG8_MMA(1, 1, At, B1); PG8_BAR; PG8_SCHED;
.LBB0_146:
	ds_read_b128 v[26:29], v190
	ds_read_b128 v[30:33], v190 offset:1024
	ds_read_b128 v[18:21], v190 offset:2048
	ds_read_b128 v[22:25], v190 offset:3072
	ds_read_b128 v[10:13], v191
	ds_read_b128 v[14:17], v191 offset:1024
	ds_read_b128 v[2:5], v191 offset:2048
	ds_read_b128 v[6:9], v191 offset:3072
	s_add_u32 s40, s6, 0xfff80080
	s_addc_u32 s41, s7, -1
	s_cmp_eq_u32 s60, 28
	s_cselect_b32 s43, s29, s41
	s_cselect_b32 s42, s37, s40
	s_cselect_b32 s41, s27, s59
	s_cselect_b32 s40, s44, s45
	v_lshl_add_u64 v[218:219], s[6:7], 0, v[172:173]
	s_add_i32 m0, s39, 0xc000
	ds_read_b128 v[178:181], v192
	ds_read_b128 v[182:185], v192 offset:1024
	ds_read_b128 v[194:197], v192 offset:2048
	ds_read_b128 v[198:201], v192 offset:3072
	ds_read_b128 v[202:205], v192 offset:4096
	ds_read_b128 v[206:209], v192 offset:5120
	ds_read_b128 v[210:213], v192 offset:6144
	ds_read_b128 v[214:217], v192 offset:7168
	global_load_lds_dwordx4 v[218:219], off
	v_lshl_add_u64 v[218:219], s[6:7], 0, v[170:171]
	s_add_i32 m0, s39, 0xe000
	s_nop 0
	global_load_lds_dwordx4 v[218:219], off
	s_waitcnt vmcnt(8)
	s_waitcnt lgkmcnt(0)
	s_setprio 1
	s_barrier
	v_mfma_scale_f32_16x16x128_f8f6f4 v[158:161], v[26:33], v[178:185], v[158:161], v186, v186 op_sel_hi:[0,0,0]
	v_mfma_scale_f32_16x16x128_f8f6f4 v[154:157], v[18:25], v[178:185], v[154:157], v186, v186 op_sel_hi:[0,0,0]
	v_mfma_scale_f32_16x16x128_f8f6f4 v[142:145], v[26:33], v[194:201], v[142:145], v186, v186 op_sel_hi:[0,0,0]
	v_mfma_scale_f32_16x16x128_f8f6f4 v[138:141], v[18:25], v[194:201], v[138:141], v186, v186 op_sel_hi:[0,0,0]
	v_mfma_scale_f32_16x16x128_f8f6f4 v[126:129], v[26:33], v[202:209], v[126:129], v186, v186 op_sel_hi:[0,0,0]
	v_mfma_scale_f32_16x16x128_f8f6f4 v[122:125], v[18:25], v[202:209], v[122:125], v186, v186 op_sel_hi:[0,0,0]
	v_mfma_scale_f32_16x16x128_f8f6f4 v[110:113], v[26:33], v[210:217], v[110:113], v186, v186 op_sel_hi:[0,0,0]
	v_mfma_scale_f32_16x16x128_f8f6f4 v[106:109], v[18:25], v[210:217], v[106:109], v186, v186 op_sel_hi:[0,0,0]
	v_mfma_scale_f32_16x16x128_f8f6f4 v[150:153], v[10:17], v[178:185], v[150:153], v186, v186 op_sel_hi:[0,0,0]
	v_mfma_scale_f32_16x16x128_f8f6f4 v[146:149], v[2:9], v[178:185], v[146:149], v186, v186 op_sel_hi:[0,0,0]
	v_mfma_scale_f32_16x16x128_f8f6f4 v[134:137], v[10:17], v[194:201], v[134:137], v186, v186 op_sel_hi:[0,0,0]
	v_mfma_scale_f32_16x16x128_f8f6f4 v[130:133], v[2:9], v[194:201], v[130:133], v186, v186 op_sel_hi:[0,0,0]
	v_mfma_scale_f32_16x16x128_f8f6f4 v[118:121], v[10:17], v[202:209], v[118:121], v186, v186 op_sel_hi:[0,0,0]
	v_mfma_scale_f32_16x16x128_f8f6f4 v[114:117], v[2:9], v[202:209], v[114:117], v186, v186 op_sel_hi:[0,0,0]
	v_mfma_scale_f32_16x16x128_f8f6f4 v[102:105], v[10:17], v[210:217], v[102:105], v186, v186 op_sel_hi:[0,0,0]
	v_mfma_scale_f32_16x16x128_f8f6f4 v[98:101], v[2:9], v[210:217], v[98:101], v186, v186 op_sel_hi:[0,0,0]
	s_barrier
	s_setprio 0
	s_add_i32 s61, s57, s47
	v_lshl_add_u64 v[178:179], s[40:41], 0, v[164:165]
	s_mov_b32 m0, s61
	ds_read_b128 v[194:197], v192 offset:16384
	ds_read_b128 v[198:201], v192 offset:17408
	ds_read_b128 v[202:205], v192 offset:18432
	ds_read_b128 v[206:209], v192 offset:19456
	ds_read_b128 v[210:213], v192 offset:20480
	ds_read_b128 v[214:217], v192 offset:21504
	ds_read_b128 v[218:221], v192 offset:22528
	ds_read_b128 v[222:225], v192 offset:23552
	global_load_lds_dwordx4 v[178:179], off
	s_add_i32 m0, s61, 0x2000
	s_add_u32 s62, s40, 0x80000
	v_lshl_add_u64 v[180:181], s[40:41], 0, v[168:169]
	s_addc_u32 s63, s41, 0
	s_add_i32 s61, s58, s47
	global_load_lds_dwordx4 v[180:181], off
	v_lshl_add_u64 v[182:183], s[62:63], 0, v[164:165]
	s_mov_b32 m0, s61
	v_lshl_add_u64 v[184:185], s[42:43], 0, v[166:167]
	global_load_lds_dwordx4 v[182:183], off
	v_lshl_add_u64 v[182:183], s[62:63], 0, v[168:169]
	s_add_i32 m0, s61, 0x2000
	s_nop 0
	global_load_lds_dwordx4 v[182:183], off
	v_lshl_add_u64 v[182:183], s[42:43], 0, v[162:163]
	s_mov_b32 m0, s39
	s_nop 0
	global_load_lds_dwordx4 v[182:183], off
	s_mov_b32 m0, s48
	s_nop 0
	global_load_lds_dwordx4 v[184:185], off
	s_waitcnt vmcnt(8)
	s_waitcnt lgkmcnt(0)
	s_setprio 1
	s_barrier
	v_mfma_scale_f32_16x16x128_f8f6f4 v[94:97], v[26:33], v[194:201], v[94:97], v186, v186 op_sel_hi:[0,0,0]
	v_mfma_scale_f32_16x16x128_f8f6f4 v[90:93], v[18:25], v[194:201], v[90:93], v186, v186 op_sel_hi:[0,0,0]
	v_mfma_scale_f32_16x16x128_f8f6f4 v[78:81], v[26:33], v[202:209], v[78:81], v186, v186 op_sel_hi:[0,0,0]
	v_mfma_scale_f32_16x16x128_f8f6f4 v[74:77], v[18:25], v[202:209], v[74:77], v186, v186 op_sel_hi:[0,0,0]
	v_mfma_scale_f32_16x16x128_f8f6f4 v[62:65], v[26:33], v[210:217], v[62:65], v186, v186 op_sel_hi:[0,0,0]
	v_mfma_scale_f32_16x16x128_f8f6f4 v[58:61], v[18:25], v[210:217], v[58:61], v186, v186 op_sel_hi:[0,0,0]
	v_mfma_scale_f32_16x16x128_f8f6f4 v[46:49], v[26:33], v[218:225], v[46:49], v186, v186 op_sel_hi:[0,0,0]
	v_mfma_scale_f32_16x16x128_f8f6f4 v[42:45], v[18:25], v[218:225], v[42:45], v186, v186 op_sel_hi:[0,0,0]
	v_mfma_scale_f32_16x16x128_f8f6f4 v[86:89], v[10:17], v[194:201], v[86:89], v186, v186 op_sel_hi:[0,0,0]
	v_mfma_scale_f32_16x16x128_f8f6f4 v[82:85], v[2:9], v[194:201], v[82:85], v186, v186 op_sel_hi:[0,0,0]
	v_mfma_scale_f32_16x16x128_f8f6f4 v[70:73], v[10:17], v[202:209], v[70:73], v186, v186 op_sel_hi:[0,0,0]
	v_mfma_scale_f32_16x16x128_f8f6f4 v[66:69], v[2:9], v[202:209], v[66:69], v186, v186 op_sel_hi:[0,0,0]
	v_mfma_scale_f32_16x16x128_f8f6f4 v[54:57], v[10:17], v[210:217], v[54:57], v186, v186 op_sel_hi:[0,0,0]
	v_mfma_scale_f32_16x16x128_f8f6f4 v[50:53], v[2:9], v[210:217], v[50:53], v186, v186 op_sel_hi:[0,0,0]
	v_mfma_scale_f32_16x16x128_f8f6f4 v[38:41], v[10:17], v[218:225], v[38:41], v186, v186 op_sel_hi:[0,0,0]
	v_mfma_scale_f32_16x16x128_f8f6f4 v[34:37], v[2:9], v[218:225], v[34:37], v186, v186 op_sel_hi:[0,0,0]
	s_barrier
; #define PG8_STAGE(bufoff, gbase, voff) do { _Pragma("unroll") for (int _i = 0; _i < 2; ++_i) \
;         __builtin_amdgcn_global_load_lds((const unsigned*)((const char*)(gbase) + (voff)[_i]), (PG8_LAS unsigned*)(lds + (bufoff) + ldsw + _i * 8192), 16, 0, 0); } while (0)
; #define PG8_LDA(dst, b, h) do { _Pragma("unroll") for (int m = 0; m < 4; ++m) _Pragma("unroll") for (int k = 0; k < 2; ++k) dst[m][k] = *(const PG8_LAS bf16x8*)(lds + PG8_SA(b, h) + aoff + m * 2048 + k * 1024); } while (0)
; #define PG8_LDB(dst, b, h) do { _Pragma("unroll") for (int n = 0; n < 2; ++n) _Pragma("unroll") for (int k = 0; k < 2; ++k) dst[n][k] = *(const PG8_LAS bf16x8*)(lds + PG8_SB(b, h) + boff + n * 2048 + k * 1024); } while (0)
; #define PG8_WAIT_V(n) asm volatile("s_waitcnt vmcnt(" #n ")" ::: "memory")
; #define PG8_WAIT_L(n) asm volatile("s_waitcnt lgkmcnt(" #n ")" ::: "memory")
; #define PG8_BAR __builtin_amdgcn_s_barrier()
; #define PG8_SCHED __builtin_amdgcn_sched_barrier(0)
; template <class Epi, class Sched, bool ALIGN_EPI = false, bool SP2 = false, bool F8 = false>
; __device__ __forceinline__ void gemm_phase(PG8_LAS unsigned char* lds, const Gemm g, const Sched& S, const Epi& E) {
;     ...
;             PG8_WAIT_V(8); PG8_WAIT_L(0); PG8_BAR; PG8_MMA(1, 0, At, B0); PG8_MMA(1, 1, At, B1); PG8_BAR; PG8_SCHED;
;             PG8_LDB(B0, 1, 0); PG8_LDB(B1, 1, 1); PG8_SCHED; PG8_LDA(At, 1, 0); PG8_STAGE(PG8_SA(0, 1), a2 + hA, voffA);
;             PG8_WAIT_V(8); PG8_WAIT_L(0); PG8_BAR; PG8_MMA(0, 0, At, B0); PG8_MMA(0, 1, At, B1); PG8_BAR; PG8_SCHED;
;             PG8_LDA(At, 1, 1); PG8_STAGE(PG8_SB(1, 0), b3, voffB); PG8_STAGE(PG8_SB(1, 1), b3 + hB, voffB); PG8_STAGE(PG8_SA(1, 0), a3, voffA);
;             PG8_WAIT_V(8); PG8_WAIT_L(0); PG8_BAR; PG8_MMA(1, 0, At, B0); PG8_MMA(1, 1, At, B1); PG8_BAR; PG8_SCHED;
;     ...
;         if constexpr (ALIGN_EPI) { if (wr == 0) PG8_BAR; }
	s_setprio 0
	s_add_i32 s61, 0, 0x18000
	s_add_i32 s62, 0, 0x1c000
	v_add_u32_e32 v14, s61, v188
	v_add_u32_e32 v30, s62, v188
	ds_read_b128 v[2:5], v14
	ds_read_b128 v[6:9], v14 offset:1024
	ds_read_b128 v[10:13], v14 offset:2048
	ds_read_b128 v[14:17], v14 offset:3072
	ds_read_b128 v[18:21], v30
	ds_read_b128 v[22:25], v30 offset:1024
	ds_read_b128 v[26:29], v30 offset:2048
	ds_read_b128 v[30:33], v30 offset:3072
	s_add_u32 s42, s42, 0x80000
	s_addc_u32 s43, s43, 0
	s_mov_b32 m0, s49
	v_lshl_add_u64 v[226:227], s[42:43], 0, v[162:163]
	ds_read_b128 v[194:197], v192 offset:32768
	ds_read_b128 v[198:201], v192 offset:33792
	ds_read_b128 v[202:205], v192 offset:34816
	ds_read_b128 v[206:209], v192 offset:35840
	ds_read_b128 v[210:213], v192 offset:36864
	ds_read_b128 v[214:217], v192 offset:37888
	ds_read_b128 v[218:221], v192 offset:38912
	ds_read_b128 v[222:225], v192 offset:39936
	global_load_lds_dwordx4 v[226:227], off
	v_lshl_add_u64 v[226:227], s[42:43], 0, v[166:167]
	s_mov_b32 m0, s50
	s_nop 0
	global_load_lds_dwordx4 v[226:227], off
	s_waitcnt vmcnt(8)
	s_waitcnt lgkmcnt(0)
	s_setprio 1
	s_barrier
	v_mfma_scale_f32_16x16x128_f8f6f4 v[158:161], v[2:9], v[194:201], v[158:161], v186, v186 op_sel_hi:[0,0,0]
	v_mfma_scale_f32_16x16x128_f8f6f4 v[154:157], v[10:17], v[194:201], v[154:157], v186, v186 op_sel_hi:[0,0,0]
	v_mfma_scale_f32_16x16x128_f8f6f4 v[142:145], v[2:9], v[202:209], v[142:145], v186, v186 op_sel_hi:[0,0,0]
	v_mfma_scale_f32_16x16x128_f8f6f4 v[138:141], v[10:17], v[202:209], v[138:141], v186, v186 op_sel_hi:[0,0,0]
	v_mfma_scale_f32_16x16x128_f8f6f4 v[126:129], v[2:9], v[210:217], v[126:129], v186, v186 op_sel_hi:[0,0,0]
	v_mfma_scale_f32_16x16x128_f8f6f4 v[122:125], v[10:17], v[210:217], v[122:125], v186, v186 op_sel_hi:[0,0,0]
	v_mfma_scale_f32_16x16x128_f8f6f4 v[110:113], v[2:9], v[218:225], v[110:113], v186, v186 op_sel_hi:[0,0,0]
	v_mfma_scale_f32_16x16x128_f8f6f4 v[106:109], v[10:17], v[218:225], v[106:109], v186, v186 op_sel_hi:[0,0,0]
	v_mfma_scale_f32_16x16x128_f8f6f4 v[150:153], v[18:25], v[194:201], v[150:153], v186, v186 op_sel_hi:[0,0,0]
	v_mfma_scale_f32_16x16x128_f8f6f4 v[146:149], v[26:33], v[194:201], v[146:149], v186, v186 op_sel_hi:[0,0,0]
	v_mfma_scale_f32_16x16x128_f8f6f4 v[134:137], v[18:25], v[202:209], v[134:137], v186, v186 op_sel_hi:[0,0,0]
	v_mfma_scale_f32_16x16x128_f8f6f4 v[130:133], v[26:33], v[202:209], v[130:133], v186, v186 op_sel_hi:[0,0,0]
	v_mfma_scale_f32_16x16x128_f8f6f4 v[118:121], v[18:25], v[210:217], v[118:121], v186, v186 op_sel_hi:[0,0,0]
	v_mfma_scale_f32_16x16x128_f8f6f4 v[114:117], v[26:33], v[210:217], v[114:117], v186, v186 op_sel_hi:[0,0,0]
	v_mfma_scale_f32_16x16x128_f8f6f4 v[102:105], v[18:25], v[218:225], v[102:105], v186, v186 op_sel_hi:[0,0,0]
	v_mfma_scale_f32_16x16x128_f8f6f4 v[98:101], v[26:33], v[218:225], v[98:101], v186, v186 op_sel_hi:[0,0,0]
	s_barrier
	s_setprio 0
	s_add_i32 s42, s61, s47
	v_lshl_add_u64 v[178:179], v[178:179], 0, s[22:23]
	s_mov_b32 m0, s42
	ds_read_b128 v[194:197], v192 offset:49152
	ds_read_b128 v[198:201], v192 offset:50176
	ds_read_b128 v[202:205], v192 offset:51200
	ds_read_b128 v[206:209], v192 offset:52224
	ds_read_b128 v[210:213], v192 offset:53248
	ds_read_b128 v[214:217], v192 offset:54272
	ds_read_b128 v[218:221], v192 offset:55296
	ds_read_b128 v[222:225], v192 offset:56320
	global_load_lds_dwordx4 v[178:179], off
	s_add_i32 m0, s42, 0x2000
	s_add_u32 s40, s40, 0x80080
	v_lshl_add_u64 v[178:179], v[180:181], 0, s[22:23]
	s_addc_u32 s41, s41, 0
	s_add_i32 s42, s62, s47
	global_load_lds_dwordx4 v[178:179], off
	v_lshl_add_u64 v[178:179], s[40:41], 0, v[164:165]
	s_mov_b32 m0, s42
	s_nop 0
	global_load_lds_dwordx4 v[178:179], off
	v_lshl_add_u64 v[178:179], s[40:41], 0, v[168:169]
	s_add_i32 m0, s42, 0x2000
	s_nop 0
	global_load_lds_dwordx4 v[178:179], off
	v_lshl_add_u64 v[178:179], v[182:183], 0, s[22:23]
	s_mov_b32 m0, s52
	s_nop 0
	global_load_lds_dwordx4 v[178:179], off
	v_lshl_add_u64 v[178:179], v[184:185], 0, s[22:23]
	s_mov_b32 m0, s53
	s_nop 0
	global_load_lds_dwordx4 v[178:179], off
	s_waitcnt vmcnt(8)
	s_waitcnt lgkmcnt(0)
	s_setprio 1
	s_barrier
	v_mfma_scale_f32_16x16x128_f8f6f4 v[94:97], v[2:9], v[194:201], v[94:97], v186, v186 op_sel_hi:[0,0,0]
	v_mfma_scale_f32_16x16x128_f8f6f4 v[90:93], v[10:17], v[194:201], v[90:93], v186, v186 op_sel_hi:[0,0,0]
	v_mfma_scale_f32_16x16x128_f8f6f4 v[78:81], v[2:9], v[202:209], v[78:81], v186, v186 op_sel_hi:[0,0,0]
	v_mfma_scale_f32_16x16x128_f8f6f4 v[74:77], v[10:17], v[202:209], v[74:77], v186, v186 op_sel_hi:[0,0,0]
	v_mfma_scale_f32_16x16x128_f8f6f4 v[62:65], v[2:9], v[210:217], v[62:65], v186, v186 op_sel_hi:[0,0,0]
	v_mfma_scale_f32_16x16x128_f8f6f4 v[58:61], v[10:17], v[210:217], v[58:61], v186, v186 op_sel_hi:[0,0,0]
	v_mfma_scale_f32_16x16x128_f8f6f4 v[46:49], v[2:9], v[218:225], v[46:49], v186, v186 op_sel_hi:[0,0,0]
	v_mfma_scale_f32_16x16x128_f8f6f4 v[42:45], v[10:17], v[218:225], v[42:45], v186, v186 op_sel_hi:[0,0,0]
	v_mfma_scale_f32_16x16x128_f8f6f4 v[86:89], v[18:25], v[194:201], v[86:89], v186, v186 op_sel_hi:[0,0,0]
	v_mfma_scale_f32_16x16x128_f8f6f4 v[82:85], v[26:33], v[194:201], v[82:85], v186, v186 op_sel_hi:[0,0,0]
	v_mfma_scale_f32_16x16x128_f8f6f4 v[70:73], v[18:25], v[202:209], v[70:73], v186, v186 op_sel_hi:[0,0,0]
	v_mfma_scale_f32_16x16x128_f8f6f4 v[66:69], v[26:33], v[202:209], v[66:69], v186, v186 op_sel_hi:[0,0,0]
	v_mfma_scale_f32_16x16x128_f8f6f4 v[54:57], v[18:25], v[210:217], v[54:57], v186, v186 op_sel_hi:[0,0,0]
	v_mfma_scale_f32_16x16x128_f8f6f4 v[50:53], v[26:33], v[210:217], v[50:53], v186, v186 op_sel_hi:[0,0,0]
	v_mfma_scale_f32_16x16x128_f8f6f4 v[38:41], v[18:25], v[218:225], v[38:41], v186, v186 op_sel_hi:[0,0,0]
	v_mfma_scale_f32_16x16x128_f8f6f4 v[34:37], v[26:33], v[218:225], v[34:37], v186, v186 op_sel_hi:[0,0,0]
	s_barrier
	s_setprio 0
	s_add_i32 s60, s60, 2
	s_add_u32 s45, s45, 0x100
	s_addc_u32 s59, s59, 0
	s_add_u32 s6, s6, 0x100
	s_addc_u32 s7, s7, 0
	s_cmp_gt_u32 s60, 29
	s_cbranch_scc0 .LBB0_146
	s_and_b64 vcc, exec, s[24:25]
	s_cbranch_vccz .LBB0_149
	s_barrier

; #define PG8_STAGE(bufoff, gbase, voff) do { _Pragma("unroll") for (int _i = 0; _i < 2; ++_i) \
;         __builtin_amdgcn_global_load_lds((const unsigned*)((const char*)(gbase) + (voff)[_i]), (PG8_LAS unsigned*)(lds + (bufoff) + ldsw + _i * 8192), 16, 0, 0); } while (0)
; #define PG8_LDA(dst, b, h) do { _Pragma("unroll") for (int m = 0; m < 4; ++m) _Pragma("unroll") for (int k = 0; k < 2; ++k) dst[m][k] = *(const PG8_LAS bf16x8*)(lds + PG8_SA(b, h) + aoff + m * 2048 + k * 1024); } while (0)
; #define PG8_LDB(dst, b, h) do { _Pragma("unroll") for (int n = 0; n < 2; ++n) _Pragma("unroll") for (int k = 0; k < 2; ++k) dst[n][k] = *(const PG8_LAS bf16x8*)(lds + PG8_SB(b, h) + boff + n * 2048 + k * 1024); } while (0)
; #define PG8_WAIT_V(n) asm volatile("s_waitcnt vmcnt(" #n ")" ::: "memory")
; #define PG8_WAIT_L(n) asm volatile("s_waitcnt lgkmcnt(" #n ")" ::: "memory")
; #define PG8_BAR __builtin_amdgcn_s_barrier()
; #define PG8_SCHED __builtin_amdgcn_sched_barrier(0)
; template <class Epi, class Sched, bool ALIGN_EPI = false, bool SP2 = false, bool F8 = false>
; __device__ __forceinline__ void gemm_phase(PG8_LAS unsigned char* lds, const Gemm g, const Sched& S, const Epi& E) {
;     ...
;         for (int t = 0; t < nt; t += 2) {
;             const bool last = (t == nt - 2);
;             const char* a1 = cA + (size_t)(t + 1) * kstep;
;             const char* a2 = last ? nA : cA + (size_t)(t + 2) * kstep; const char* b2 = last ? nB : cB + (size_t)(t + 2) * kstep;
;             const char* a3 = a2 + kstep; const char* b3 = b2 + kstep;
;             if (last && has_next) S.a_ready(nxt);
;             if constexpr (SP2) {
;             PG8_LDB(B0, 0, 0); PG8_LDB(B1, 0, 1); PG8_SCHED; PG8_LDA(At, 0, 0); PG8_STAGE(PG8_SA(1, 1), a1 + hA, voffA);
;             PG8_WAIT_V(8); PG8_WAIT_L(0); PG8_BAR; PG8_MMA(0, 0, At, B0); PG8_MMA(0, 1, At, B1); PG8_BAR; PG8_SCHED;
;             PG8_LDA(At, 0, 1); PG8_STAGE(PG8_SB(0, 0), b2, voffB); PG8_STAGE(PG8_SB(0, 1), b2 + hB, voffB); PG8_STAGE(PG8_SA(0, 0), a2, voffA);
;             PG8_WAIT_V(8); PG8_WAIT_L(0); PG8_BAR; PG8_MMA(1, 0, At, B0); PG8_MMA(1, 1, At, B1); PG8_BAR; PG8_SCHED;
.LBB0_618:
	ds_read_b128 v[130:133], v185
	ds_read_b128 v[134:137], v185 offset:1024
	ds_read_b128 v[138:141], v185 offset:2048
	ds_read_b128 v[142:145], v185 offset:3072
	ds_read_b128 v[146:149], v186
	ds_read_b128 v[150:153], v186 offset:1024
	ds_read_b128 v[154:157], v186 offset:2048
	ds_read_b128 v[174:177], v186 offset:3072
	s_add_u32 s40, s38, 0xfff80080
	s_addc_u32 s41, s39, -1
	s_cmp_eq_u32 s59, 4
	s_cselect_b32 s43, s29, s41
	s_cselect_b32 s42, s55, s40
	s_cselect_b32 s41, s27, s58
	s_cselect_b32 s40, s56, s57
	v_lshl_add_u64 v[216:217], s[38:39], 0, v[168:169]
	s_add_i32 m0, s37, 0xc000
	ds_read_b128 v[178:181], v187
	ds_read_b128 v[188:191], v187 offset:1024
	ds_read_b128 v[192:195], v187 offset:2048
	ds_read_b128 v[196:199], v187 offset:3072
	ds_read_b128 v[200:203], v187 offset:4096
	ds_read_b128 v[204:207], v187 offset:5120
	ds_read_b128 v[208:211], v187 offset:6144
	ds_read_b128 v[212:215], v187 offset:7168
	global_load_lds_dwordx4 v[216:217], off
	v_lshl_add_u64 v[216:217], s[38:39], 0, v[166:167]
	s_add_i32 m0, s37, 0xe000
	s_nop 0
	global_load_lds_dwordx4 v[216:217], off
	s_waitcnt vmcnt(8)
	s_waitcnt lgkmcnt(0)
	s_setprio 1
	s_barrier
	v_mfma_f32_16x16x32_bf16 v[126:129], v[130:133], v[178:181], v[126:129]
	v_mfma_f32_16x16x32_bf16 v[122:125], v[138:141], v[178:181], v[122:125]
	v_mfma_f32_16x16x32_bf16 v[110:113], v[130:133], v[192:195], v[110:113]
	v_mfma_f32_16x16x32_bf16 v[106:109], v[138:141], v[192:195], v[106:109]
	v_mfma_f32_16x16x32_bf16 v[94:97], v[130:133], v[200:203], v[94:97]
	v_mfma_f32_16x16x32_bf16 v[90:93], v[138:141], v[200:203], v[90:93]
	v_mfma_f32_16x16x32_bf16 v[78:81], v[130:133], v[208:211], v[78:81]
	v_mfma_f32_16x16x32_bf16 v[74:77], v[138:141], v[208:211], v[74:77]
	v_mfma_f32_16x16x32_bf16 v[126:129], v[134:137], v[188:191], v[126:129]
	v_mfma_f32_16x16x32_bf16 v[122:125], v[142:145], v[188:191], v[122:125]
	v_mfma_f32_16x16x32_bf16 v[110:113], v[134:137], v[196:199], v[110:113]
	v_mfma_f32_16x16x32_bf16 v[106:109], v[142:145], v[196:199], v[106:109]
	v_mfma_f32_16x16x32_bf16 v[94:97], v[134:137], v[204:207], v[94:97]
	v_mfma_f32_16x16x32_bf16 v[90:93], v[142:145], v[204:207], v[90:93]
	v_mfma_f32_16x16x32_bf16 v[78:81], v[134:137], v[212:215], v[78:81]
	v_mfma_f32_16x16x32_bf16 v[74:77], v[142:145], v[212:215], v[74:77]
	v_mfma_f32_16x16x32_bf16 v[118:121], v[146:149], v[178:181], v[118:121]
	v_mfma_f32_16x16x32_bf16 v[114:117], v[154:157], v[178:181], v[114:117]
	v_mfma_f32_16x16x32_bf16 v[102:105], v[146:149], v[192:195], v[102:105]
	v_mfma_f32_16x16x32_bf16 v[98:101], v[154:157], v[192:195], v[98:101]
	v_mfma_f32_16x16x32_bf16 v[86:89], v[146:149], v[200:203], v[86:89]
	v_mfma_f32_16x16x32_bf16 v[82:85], v[154:157], v[200:203], v[82:85]
	v_mfma_f32_16x16x32_bf16 v[70:73], v[146:149], v[208:211], v[70:73]
	v_mfma_f32_16x16x32_bf16 v[66:69], v[154:157], v[208:211], v[66:69]
	v_mfma_f32_16x16x32_bf16 v[118:121], v[150:153], v[188:191], v[118:121]
	v_mfma_f32_16x16x32_bf16 v[114:117], v[174:177], v[188:191], v[114:117]
	v_mfma_f32_16x16x32_bf16 v[102:105], v[150:153], v[196:199], v[102:105]
	v_mfma_f32_16x16x32_bf16 v[98:101], v[174:177], v[196:199], v[98:101]
	v_mfma_f32_16x16x32_bf16 v[86:89], v[150:153], v[204:207], v[86:89]
	v_mfma_f32_16x16x32_bf16 v[82:85], v[174:177], v[204:207], v[82:85]
	v_mfma_f32_16x16x32_bf16 v[70:73], v[150:153], v[212:215], v[70:73]
	v_mfma_f32_16x16x32_bf16 v[66:69], v[174:177], v[212:215], v[66:69]
	s_barrier
	s_setprio 0
	s_add_i32 s60, s52, s19
	v_lshl_add_u64 v[216:217], s[40:41], 0, v[162:163]
	s_mov_b32 m0, s60
	ds_read_b128 v[178:181], v187 offset:16384
	ds_read_b128 v[188:191], v187 offset:17408
	ds_read_b128 v[192:195], v187 offset:18432
	ds_read_b128 v[196:199], v187 offset:19456
	ds_read_b128 v[200:203], v187 offset:20480
	ds_read_b128 v[204:207], v187 offset:21504
	ds_read_b128 v[208:211], v187 offset:22528
	ds_read_b128 v[212:215], v187 offset:23552
	global_load_lds_dwordx4 v[216:217], off
	s_add_i32 m0, s60, 0x2000
	s_add_u32 s60, s40, 0x20000
	v_lshl_add_u64 v[218:219], s[40:41], 0, v[158:159]
	s_addc_u32 s61, s41, 0
	s_add_i32 s62, s53, s19
	global_load_lds_dwordx4 v[218:219], off
	v_lshl_add_u64 v[220:221], s[60:61], 0, v[162:163]
	s_mov_b32 m0, s62
	v_lshl_add_u64 v[222:223], s[42:43], 0, v[160:161]
	global_load_lds_dwordx4 v[220:221], off
	v_lshl_add_u64 v[220:221], s[60:61], 0, v[158:159]
	s_add_i32 m0, s62, 0x2000
	s_nop 0
	global_load_lds_dwordx4 v[220:221], off
	v_lshl_add_u64 v[220:221], s[42:43], 0, v[164:165]
	s_mov_b32 m0, s37
	s_nop 0
	global_load_lds_dwordx4 v[220:221], off
	s_mov_b32 m0, s45
	s_nop 0
	global_load_lds_dwordx4 v[222:223], off
	s_waitcnt vmcnt(8)
	s_waitcnt lgkmcnt(0)
	s_setprio 1
	s_barrier
; #define PG8_STAGE(bufoff, gbase, voff) do { _Pragma("unroll") for (int _i = 0; _i < 2; ++_i) \
;         __builtin_amdgcn_global_load_lds((const unsigned*)((const char*)(gbase) + (voff)[_i]), (PG8_LAS unsigned*)(lds + (bufoff) + ldsw + _i * 8192), 16, 0, 0); } while (0)
; #define PG8_LDA(dst, b, h) do { _Pragma("unroll") for (int m = 0; m < 4; ++m) _Pragma("unroll") for (int k = 0; k < 2; ++k) dst[m][k] = *(const PG8_LAS bf16x8*)(lds + PG8_SA(b, h) + aoff + m * 2048 + k * 1024); } while (0)
; #define PG8_LDB(dst, b, h) do { _Pragma("unroll") for (int n = 0; n < 2; ++n) _Pragma("unroll") for (int k = 0; k < 2; ++k) dst[n][k] = *(const PG8_LAS bf16x8*)(lds + PG8_SB(b, h) + boff + n * 2048 + k * 1024); } while (0)
; #define PG8_WAIT_V(n) asm volatile("s_waitcnt vmcnt(" #n ")" ::: "memory")
; #define PG8_WAIT_L(n) asm volatile("s_waitcnt lgkmcnt(" #n ")" ::: "memory")
; #define PG8_BAR __builtin_amdgcn_s_barrier()
; #define PG8_SCHED __builtin_amdgcn_sched_barrier(0)
; template <class Epi, class Sched, bool ALIGN_EPI = false, bool SP2 = false, bool F8 = false>
; __device__ __forceinline__ void gemm_phase(PG8_LAS unsigned char* lds, const Gemm g, const Sched& S, const Epi& E) {
;     ...
;             PG8_LDA(At, 0, 1); PG8_STAGE(PG8_SB(0, 0), b2, voffB); PG8_STAGE(PG8_SB(0, 1), b2 + hB, voffB); PG8_STAGE(PG8_SA(0, 0), a2, voffA);
;             PG8_WAIT_V(8); PG8_WAIT_L(0); PG8_BAR; PG8_MMA(1, 0, At, B0); PG8_MMA(1, 1, At, B1); PG8_BAR; PG8_SCHED;
;             PG8_LDB(B0, 1, 0); PG8_LDB(B1, 1, 1); PG8_SCHED; PG8_LDA(At, 1, 0); PG8_STAGE(PG8_SA(0, 1), a2 + hA, voffA);
;             PG8_WAIT_V(8); PG8_WAIT_L(0); PG8_BAR; PG8_MMA(0, 0, At, B0); PG8_MMA(0, 1, At, B1); PG8_BAR; PG8_SCHED;
;             PG8_LDA(At, 1, 1); PG8_STAGE(PG8_SB(1, 0), b3, voffB); PG8_STAGE(PG8_SB(1, 1), b3 + hB, voffB); PG8_STAGE(PG8_SA(1, 0), a3, voffA);
	v_mfma_f32_16x16x32_bf16 v[62:65], v[130:133], v[178:181], v[62:65]
	v_mfma_f32_16x16x32_bf16 v[58:61], v[138:141], v[178:181], v[58:61]
	v_mfma_f32_16x16x32_bf16 v[46:49], v[130:133], v[192:195], v[46:49]
	v_mfma_f32_16x16x32_bf16 v[42:45], v[138:141], v[192:195], v[42:45]
	v_mfma_f32_16x16x32_bf16 v[30:33], v[130:133], v[200:203], v[30:33]
	v_mfma_f32_16x16x32_bf16 v[26:29], v[138:141], v[200:203], v[26:29]
	v_mfma_f32_16x16x32_bf16 v[14:17], v[130:133], v[208:211], v[14:17]
	v_mfma_f32_16x16x32_bf16 v[10:13], v[138:141], v[208:211], v[10:13]
	v_mfma_f32_16x16x32_bf16 v[62:65], v[134:137], v[188:191], v[62:65]
	v_mfma_f32_16x16x32_bf16 v[58:61], v[142:145], v[188:191], v[58:61]
	v_mfma_f32_16x16x32_bf16 v[46:49], v[134:137], v[196:199], v[46:49]
	v_mfma_f32_16x16x32_bf16 v[42:45], v[142:145], v[196:199], v[42:45]
	v_mfma_f32_16x16x32_bf16 v[30:33], v[134:137], v[204:207], v[30:33]
	v_mfma_f32_16x16x32_bf16 v[26:29], v[142:145], v[204:207], v[26:29]
	v_mfma_f32_16x16x32_bf16 v[14:17], v[134:137], v[212:215], v[14:17]
	v_mfma_f32_16x16x32_bf16 v[10:13], v[142:145], v[212:215], v[10:13]
	v_mfma_f32_16x16x32_bf16 v[54:57], v[146:149], v[178:181], v[54:57]
	v_mfma_f32_16x16x32_bf16 v[50:53], v[154:157], v[178:181], v[50:53]
	v_mfma_f32_16x16x32_bf16 v[38:41], v[146:149], v[192:195], v[38:41]
	v_mfma_f32_16x16x32_bf16 v[34:37], v[154:157], v[192:195], v[34:37]
	v_mfma_f32_16x16x32_bf16 v[22:25], v[146:149], v[200:203], v[22:25]
	v_mfma_f32_16x16x32_bf16 v[18:21], v[154:157], v[200:203], v[18:21]
	v_mfma_f32_16x16x32_bf16 v[6:9], v[146:149], v[208:211], v[6:9]
	v_mfma_f32_16x16x32_bf16 v[2:5], v[154:157], v[208:211], v[2:5]
	v_mfma_f32_16x16x32_bf16 v[54:57], v[150:153], v[188:191], v[54:57]
	v_mfma_f32_16x16x32_bf16 v[50:53], v[174:177], v[188:191], v[50:53]
	v_mfma_f32_16x16x32_bf16 v[38:41], v[150:153], v[196:199], v[38:41]
	v_mfma_f32_16x16x32_bf16 v[34:37], v[174:177], v[196:199], v[34:37]
	v_mfma_f32_16x16x32_bf16 v[22:25], v[150:153], v[204:207], v[22:25]
	v_mfma_f32_16x16x32_bf16 v[18:21], v[174:177], v[204:207], v[18:21]
	v_mfma_f32_16x16x32_bf16 v[6:9], v[150:153], v[212:215], v[6:9]
	v_mfma_f32_16x16x32_bf16 v[2:5], v[174:177], v[212:215], v[2:5]
	s_barrier
	s_setprio 0
	s_add_i32 s60, 0, 0x18000
	s_add_i32 s61, 0, 0x1c000
	v_add_u32_e32 v142, s60, v183
	v_add_u32_e32 v174, s61, v183
	ds_read_b128 v[130:133], v142
	ds_read_b128 v[134:137], v142 offset:1024
	ds_read_b128 v[138:141], v142 offset:2048
	ds_read_b128 v[142:145], v142 offset:3072
	ds_read_b128 v[146:149], v174
	ds_read_b128 v[150:153], v174 offset:1024
	ds_read_b128 v[154:157], v174 offset:2048
	ds_read_b128 v[174:177], v174 offset:3072
	s_add_u32 s42, s42, 0x80000
	s_addc_u32 s43, s43, 0
	s_mov_b32 m0, s46
	v_lshl_add_u64 v[224:225], s[42:43], 0, v[164:165]
	ds_read_b128 v[178:181], v187 offset:32768
	ds_read_b128 v[188:191], v187 offset:33792
	ds_read_b128 v[192:195], v187 offset:34816
	ds_read_b128 v[196:199], v187 offset:35840
	ds_read_b128 v[200:203], v187 offset:36864
	ds_read_b128 v[204:207], v187 offset:37888
	ds_read_b128 v[208:211], v187 offset:38912
	ds_read_b128 v[212:215], v187 offset:39936
	global_load_lds_dwordx4 v[224:225], off
	v_lshl_add_u64 v[224:225], s[42:43], 0, v[160:161]
	s_mov_b32 m0, s47
	s_nop 0
	global_load_lds_dwordx4 v[224:225], off
	s_waitcnt vmcnt(8)
	s_waitcnt lgkmcnt(0)
	s_setprio 1
	s_barrier
	v_mfma_f32_16x16x32_bf16 v[126:129], v[130:133], v[178:181], v[126:129]
	v_mfma_f32_16x16x32_bf16 v[122:125], v[138:141], v[178:181], v[122:125]
	v_mfma_f32_16x16x32_bf16 v[110:113], v[130:133], v[192:195], v[110:113]
	v_mfma_f32_16x16x32_bf16 v[106:109], v[138:141], v[192:195], v[106:109]
	v_mfma_f32_16x16x32_bf16 v[94:97], v[130:133], v[200:203], v[94:97]
	v_mfma_f32_16x16x32_bf16 v[90:93], v[138:141], v[200:203], v[90:93]
	v_mfma_f32_16x16x32_bf16 v[78:81], v[130:133], v[208:211], v[78:81]
	v_mfma_f32_16x16x32_bf16 v[74:77], v[138:141], v[208:211], v[74:77]
	v_mfma_f32_16x16x32_bf16 v[126:129], v[134:137], v[188:191], v[126:129]
	v_mfma_f32_16x16x32_bf16 v[122:125], v[142:145], v[188:191], v[122:125]
	v_mfma_f32_16x16x32_bf16 v[110:113], v[134:137], v[196:199], v[110:113]
	v_mfma_f32_16x16x32_bf16 v[106:109], v[142:145], v[196:199], v[106:109]
	v_mfma_f32_16x16x32_bf16 v[94:97], v[134:137], v[204:207], v[94:97]
	v_mfma_f32_16x16x32_bf16 v[90:93], v[142:145], v[204:207], v[90:93]
	v_mfma_f32_16x16x32_bf16 v[78:81], v[134:137], v[212:215], v[78:81]
	v_mfma_f32_16x16x32_bf16 v[74:77], v[142:145], v[212:215], v[74:77]
	v_mfma_f32_16x16x32_bf16 v[118:121], v[146:149], v[178:181], v[118:121]
	v_mfma_f32_16x16x32_bf16 v[114:117], v[154:157], v[178:181], v[114:117]
	v_mfma_f32_16x16x32_bf16 v[102:105], v[146:149], v[192:195], v[102:105]
	v_mfma_f32_16x16x32_bf16 v[98:101], v[154:157], v[192:195], v[98:101]
	v_mfma_f32_16x16x32_bf16 v[86:89], v[146:149], v[200:203], v[86:89]
	v_mfma_f32_16x16x32_bf16 v[82:85], v[154:157], v[200:203], v[82:85]
	v_mfma_f32_16x16x32_bf16 v[70:73], v[146:149], v[208:211], v[70:73]
	v_mfma_f32_16x16x32_bf16 v[66:69], v[154:157], v[208:211], v[66:69]
	v_mfma_f32_16x16x32_bf16 v[118:121], v[150:153], v[188:191], v[118:121]
	v_mfma_f32_16x16x32_bf16 v[114:117], v[174:177], v[188:191], v[114:117]
	v_mfma_f32_16x16x32_bf16 v[102:105], v[150:153], v[196:199], v[102:105]
	v_mfma_f32_16x16x32_bf16 v[98:101], v[174:177], v[196:199], v[98:101]
	v_mfma_f32_16x16x32_bf16 v[86:89], v[150:153], v[204:207], v[86:89]
	v_mfma_f32_16x16x32_bf16 v[82:85], v[174:177], v[204:207], v[82:85]
	v_mfma_f32_16x16x32_bf16 v[70:73], v[150:153], v[212:215], v[70:73]
	v_mfma_f32_16x16x32_bf16 v[66:69], v[174:177], v[212:215], v[66:69]
	s_barrier
; #define PG8_GAS __attribute__((address_space(1)))
; #define PG8_STAGE(bufoff, gbase, voff) do { _Pragma("unroll") for (int _i = 0; _i < 2; ++_i) \
;         __builtin_amdgcn_global_load_lds((const unsigned*)((const char*)(gbase) + (voff)[_i]), (PG8_LAS unsigned*)(lds + (bufoff) + ldsw + _i * 8192), 16, 0, 0); } while (0)
; #define PG8_LDA(dst, b, h) do { _Pragma("unroll") for (int m = 0; m < 4; ++m) _Pragma("unroll") for (int k = 0; k < 2; ++k) dst[m][k] = *(const PG8_LAS bf16x8*)(lds + PG8_SA(b, h) + aoff + m * 2048 + k * 1024); } while (0)
; #define PG8_LDB(dst, b, h) do { _Pragma("unroll") for (int n = 0; n < 2; ++n) _Pragma("unroll") for (int k = 0; k < 2; ++k) dst[n][k] = *(const PG8_LAS bf16x8*)(lds + PG8_SB(b, h) + boff + n * 2048 + k * 1024); } while (0)
; #define PG8_WAIT_V(n) asm volatile("s_waitcnt vmcnt(" #n ")" ::: "memory")
; #define PG8_BAR __builtin_amdgcn_s_barrier()
;     __device__ __forceinline__ void operator()(const f32x4 (&acc)[2][2][4][2], const Unit& un, int wr, int wc, int fr, int fq) const {
;         const int row0 = un.pm * BM + wr * 64 + fr, col0 = un.pn * BM + wc * 32 + 8 * fq;
;         f32x4 sc[2][2];
; #pragma unroll
;         for (int bj = 0; bj < 2; ++bj)
; #pragma unroll
;             for (int n = 0; n < 2; ++n) sc[bj][n] = *(const PG8_GAS f32x4*)(ps + col0 + bj * HALF + 4 * n);
; #pragma unroll
;         for (int ai = 0; ai < 2; ++ai) {
;             u32x4 gg[4][2];
; #pragma unroll
;             for (int m = 0; m < 4; ++m)
; #pragma unroll
;                 for (int bj = 0; bj < 2; ++bj) gg[m][bj] = *(const PG8_GAS u32x4*)(sp + (size_t)(row0 + ai * HALF + m * 16) * 4096 + col0 + bj * HALF);
; template <class Epi, class Sched, bool ALIGN_EPI = false, bool SP2 = false, bool F8 = false>
; __device__ __forceinline__ void gemm_phase(PG8_LAS unsigned char* lds, const Gemm g, const Sched& S, const Epi& E) {
;     ...
;             PG8_LDB(B0, 1, 0); PG8_LDB(B1, 1, 1); PG8_SCHED; PG8_LDA(At, 1, 0); PG8_STAGE(PG8_SA(0, 1), a2 + hA, voffA);
;             PG8_WAIT_V(8); PG8_WAIT_L(0); PG8_BAR; PG8_MMA(0, 0, At, B0); PG8_MMA(0, 1, At, B1); PG8_BAR; PG8_SCHED;
;             PG8_LDA(At, 1, 1); PG8_STAGE(PG8_SB(1, 0), b3, voffB); PG8_STAGE(PG8_SB(1, 1), b3 + hB, voffB); PG8_STAGE(PG8_SA(1, 0), a3, voffA);
;             PG8_WAIT_V(8); PG8_WAIT_L(0); PG8_BAR; PG8_MMA(1, 0, At, B0); PG8_MMA(1, 1, At, B1); PG8_BAR; PG8_SCHED;
	s_setprio 0
	s_add_i32 s42, s60, s19
	v_lshl_add_u64 v[216:217], v[216:217], 0, s[14:15]
	s_mov_b32 m0, s42
	ds_read_b128 v[178:181], v187 offset:49152
	ds_read_b128 v[188:191], v187 offset:50176
	ds_read_b128 v[192:195], v187 offset:51200
	ds_read_b128 v[196:199], v187 offset:52224
	ds_read_b128 v[200:203], v187 offset:53248
	ds_read_b128 v[204:207], v187 offset:54272
	ds_read_b128 v[208:211], v187 offset:55296
	ds_read_b128 v[212:215], v187 offset:56320
	global_load_lds_dwordx4 v[216:217], off
	s_add_i32 m0, s42, 0x2000
	s_add_u32 s40, s40, 0x20080
	v_lshl_add_u64 v[216:217], v[218:219], 0, s[14:15]
	s_addc_u32 s41, s41, 0
	s_add_i32 s42, s61, s19
	global_load_lds_dwordx4 v[216:217], off
	v_lshl_add_u64 v[216:217], s[40:41], 0, v[162:163]
	s_mov_b32 m0, s42
	s_nop 0
	global_load_lds_dwordx4 v[216:217], off
	v_lshl_add_u64 v[216:217], s[40:41], 0, v[158:159]
	s_add_i32 m0, s42, 0x2000
	s_nop 0
	global_load_lds_dwordx4 v[216:217], off
	v_lshl_add_u64 v[216:217], v[220:221], 0, s[14:15]
	s_mov_b32 m0, s49
	s_nop 0
	global_load_lds_dwordx4 v[216:217], off
	v_lshl_add_u64 v[216:217], v[222:223], 0, s[14:15]
	s_mov_b32 m0, s50
	s_nop 0
	global_load_lds_dwordx4 v[216:217], off
	s_waitcnt vmcnt(8)
	s_waitcnt lgkmcnt(0)
	s_setprio 1
	s_barrier
	v_mfma_f32_16x16x32_bf16 v[62:65], v[130:133], v[178:181], v[62:65]
	v_mfma_f32_16x16x32_bf16 v[58:61], v[138:141], v[178:181], v[58:61]
	v_mfma_f32_16x16x32_bf16 v[46:49], v[130:133], v[192:195], v[46:49]
	v_mfma_f32_16x16x32_bf16 v[42:45], v[138:141], v[192:195], v[42:45]
	v_mfma_f32_16x16x32_bf16 v[30:33], v[130:133], v[200:203], v[30:33]
	v_mfma_f32_16x16x32_bf16 v[26:29], v[138:141], v[200:203], v[26:29]
	v_mfma_f32_16x16x32_bf16 v[14:17], v[130:133], v[208:211], v[14:17]
	v_mfma_f32_16x16x32_bf16 v[10:13], v[138:141], v[208:211], v[10:13]
	v_mfma_f32_16x16x32_bf16 v[62:65], v[134:137], v[188:191], v[62:65]
	v_mfma_f32_16x16x32_bf16 v[58:61], v[142:145], v[188:191], v[58:61]
	v_mfma_f32_16x16x32_bf16 v[46:49], v[134:137], v[196:199], v[46:49]
	v_mfma_f32_16x16x32_bf16 v[42:45], v[142:145], v[196:199], v[42:45]
	v_mfma_f32_16x16x32_bf16 v[30:33], v[134:137], v[204:207], v[30:33]
	v_mfma_f32_16x16x32_bf16 v[26:29], v[142:145], v[204:207], v[26:29]
	v_mfma_f32_16x16x32_bf16 v[14:17], v[134:137], v[212:215], v[14:17]
	v_mfma_f32_16x16x32_bf16 v[10:13], v[142:145], v[212:215], v[10:13]
	v_mfma_f32_16x16x32_bf16 v[54:57], v[146:149], v[178:181], v[54:57]
	v_mfma_f32_16x16x32_bf16 v[50:53], v[154:157], v[178:181], v[50:53]
	v_mfma_f32_16x16x32_bf16 v[38:41], v[146:149], v[192:195], v[38:41]
	v_mfma_f32_16x16x32_bf16 v[34:37], v[154:157], v[192:195], v[34:37]
	v_mfma_f32_16x16x32_bf16 v[22:25], v[146:149], v[200:203], v[22:25]
	v_mfma_f32_16x16x32_bf16 v[18:21], v[154:157], v[200:203], v[18:21]
	v_mfma_f32_16x16x32_bf16 v[6:9], v[146:149], v[208:211], v[6:9]
	v_mfma_f32_16x16x32_bf16 v[2:5], v[154:157], v[208:211], v[2:5]
	v_mfma_f32_16x16x32_bf16 v[54:57], v[150:153], v[188:191], v[54:57]
	v_mfma_f32_16x16x32_bf16 v[50:53], v[174:177], v[188:191], v[50:53]
	v_mfma_f32_16x16x32_bf16 v[38:41], v[150:153], v[196:199], v[38:41]
	v_mfma_f32_16x16x32_bf16 v[34:37], v[174:177], v[196:199], v[34:37]
	v_mfma_f32_16x16x32_bf16 v[22:25], v[150:153], v[204:207], v[22:25]
	v_mfma_f32_16x16x32_bf16 v[18:21], v[174:177], v[204:207], v[18:21]
	v_mfma_f32_16x16x32_bf16 v[6:9], v[150:153], v[212:215], v[6:9]
	v_mfma_f32_16x16x32_bf16 v[2:5], v[174:177], v[212:215], v[2:5]
	s_barrier
	s_setprio 0
	s_add_i32 s59, s59, 2
	s_add_u32 s57, s57, 0x100
	s_addc_u32 s58, s58, 0
	s_add_u32 s38, s38, 0x100
	s_addc_u32 s39, s39, 0
	s_cmp_gt_u32 s59, 5
	s_cbranch_scc0 .LBB0_618
	v_lshl_or_b32 v146, s54, 8, v184
	v_ashrrev_i32_e32 v147, 31, v146
	v_lshl_add_u32 v148, s36, 8, v182
	v_ashrrev_i32_e32 v149, 31, v148
	v_lshlrev_b64 v[174:175], 1, v[146:147]
	v_lshlrev_b64 v[178:179], 13, v[148:149]
	v_lshl_add_u64 v[176:177], s[12:13], 0, v[174:175]
	v_lshl_add_u64 v[130:131], v[146:147], 2, s[10:11]
	v_lshl_add_u64 v[146:147], v[176:177], 0, v[178:179]
	global_load_dwordx4 v[142:145], v[130:131], off
	global_load_dwordx4 v[138:141], v[130:131], off offset:16
	global_load_dwordx4 v[134:137], v[130:131], off offset:512
	s_nop 0
	global_load_dwordx4 v[130:133], v[130:131], off offset:528
	s_nop 0
	global_load_dwordx4 v[188:191], v[146:147], off
	global_load_dwordx4 v[192:195], v[146:147], off offset:256
	v_or_b32_e32 v146, 16, v148
	v_ashrrev_i32_e32 v147, 31, v146
	v_lshlrev_b64 v[208:209], 13, v[146:147]
	v_lshl_add_u64 v[146:147], v[176:177], 0, v[208:209]
	global_load_dwordx4 v[196:199], v[146:147], off
	global_load_dwordx4 v[200:203], v[146:147], off offset:256
	v_or_b32_e32 v150, 32, v148
	v_or_b32_e32 v148, 48, v148
	v_ashrrev_i32_e32 v151, 31, v150
	v_ashrrev_i32_e32 v149, 31, v148
	v_lshlrev_b64 v[210:211], 13, v[150:151]
	v_lshlrev_b64 v[180:181], 13, v[148:149]
	v_lshl_add_u64 v[146:147], s[12:13], 0, v[178:179]
	v_lshl_add_u64 v[148:149], v[176:177], 0, v[210:211]
	v_lshl_add_u64 v[212:213], v[176:177], 0, v[180:181]
	v_lshl_add_u64 v[214:215], v[146:147], 0, v[174:175]
	global_load_dwordx4 v[204:207], v[148:149], off
	global_load_dwordx4 v[154:157], v[148:149], off offset:256
	global_load_dwordx4 v[150:153], v[212:213], off
	s_nop 0
	global_load_dwordx4 v[146:149], v[212:213], off offset:256
	s_and_b64 vcc, exec, s[8:9]
	s_mov_b32 s54, s26
	s_mov_b32 s36, s28
	s_mov_b64 s[38:39], s[34:35]
	s_mov_b64 s[40:41], s[30:31]
	s_waitcnt vmcnt(0)
; #define PG8_GAS __attribute__((address_space(1)))
; __device__ __forceinline__ unsigned cvt_pk_bf16(float lo, float hi) { const f32x2c v = {lo, hi}; return __builtin_bit_cast(unsigned, __builtin_convertvector(v, bf16x2c)); }
; __device__ __forceinline__ float bf_lo(unsigned w) { return __uint_as_float(w << 16); }
; __device__ __forceinline__ float bf_hi(unsigned w) { return __uint_as_float(w & 0xffff0000u); }
;     __device__ __forceinline__ void operator()(const f32x4 (&acc)[2][2][4][2], const Unit& un, int wr, int wc, int fr, int fq) const {
;     ...
;             for (int m = 0; m < 4; ++m)
; #pragma unroll
;                 for (int bj = 0; bj < 2; ++bj) { const u32x4 g = gg[m][bj];
;                     const f32x4 v0 = acc[ai][bj][m][0] * sc[bj][0], v1 = acc[ai][bj][m][1] * sc[bj][1];
;                     u32x4 w; w.x = cvt_pk_bf16(v0[0] * bf_lo(g.x), v0[1] * bf_hi(g.x)); w.y = cvt_pk_bf16(v0[2] * bf_lo(g.y), v0[3] * bf_hi(g.y));
;                     w.z = cvt_pk_bf16(v1[0] * bf_lo(g.z), v1[1] * bf_hi(g.z)); w.w = cvt_pk_bf16(v1[2] * bf_lo(g.w), v1[3] * bf_hi(g.w));
;                     *(PG8_GAS u32x4*)(sp + (size_t)(row0 + ai * HALF + m * 16) * 4096 + col0 + bj * HALF) = w; }
	v_pk_mul_f32 v[128:129], v[128:129], v[144:145]
	v_pk_mul_f32 v[126:127], v[126:127], v[142:143]
	v_pk_mul_f32 v[124:125], v[124:125], v[140:141]
	v_pk_mul_f32 v[122:123], v[122:123], v[138:139]
	v_pk_mul_f32 v[212:213], v[108:109], v[140:141]
	v_pk_mul_f32 v[216:217], v[106:107], v[138:139]
	v_lshlrev_b32_e32 v106, 16, v188
	v_and_b32_e32 v107, 0xffff0000, v188
	v_lshlrev_b32_e32 v108, 16, v189
	v_and_b32_e32 v109, 0xffff0000, v189
	v_lshlrev_b32_e32 v188, 16, v190
	v_and_b32_e32 v189, 0xffff0000, v190
	v_lshlrev_b32_e32 v190, 16, v191
	v_and_b32_e32 v191, 0xffff0000, v191
	v_pk_mul_f32 v[120:121], v[120:121], v[136:137]
	v_pk_mul_f32 v[118:119], v[118:119], v[134:135]
	v_pk_mul_f32 v[116:117], v[116:117], v[132:133]
	v_pk_mul_f32 v[114:115], v[114:115], v[130:131]
	v_lshlrev_b32_e32 v218, 16, v192
	v_and_b32_e32 v219, 0xffff0000, v192
	v_lshlrev_b32_e32 v192, 16, v193
	v_and_b32_e32 v193, 0xffff0000, v193
	v_lshlrev_b32_e32 v220, 16, v194
	v_and_b32_e32 v221, 0xffff0000, v194
	v_lshlrev_b32_e32 v194, 16, v195
	v_and_b32_e32 v195, 0xffff0000, v195
	v_pk_mul_f32 v[106:107], v[126:127], v[106:107]
	v_pk_mul_f32 v[108:109], v[128:129], v[108:109]
	v_pk_mul_f32 v[122:123], v[122:123], v[188:189]
	v_pk_mul_f32 v[124:125], v[124:125], v[190:191]
	v_pk_mul_f32 v[112:113], v[112:113], v[144:145]
	v_pk_mul_f32 v[110:111], v[110:111], v[142:143]
	v_lshlrev_b32_e32 v222, 16, v196
	v_and_b32_e32 v223, 0xffff0000, v196
	v_lshlrev_b32_e32 v196, 16, v197
	v_and_b32_e32 v197, 0xffff0000, v197
	v_pk_mul_f32 v[118:119], v[118:119], v[218:219]
	v_pk_mul_f32 v[120:121], v[120:121], v[192:193]
	v_pk_mul_f32 v[114:115], v[114:115], v[220:221]
	v_pk_mul_f32 v[116:117], v[116:117], v[194:195]
	v_cvt_pk_bf16_f32 v106, v106, v107
	v_cvt_pk_bf16_f32 v107, v108, v109
	v_cvt_pk_bf16_f32 v108, v122, v123
	v_cvt_pk_bf16_f32 v109, v124, v125
	v_pk_mul_f32 v[126:127], v[110:111], v[222:223]
	v_pk_mul_f32 v[128:129], v[112:113], v[196:197]
	v_cvt_pk_bf16_f32 v110, v118, v119
	v_cvt_pk_bf16_f32 v111, v120, v121
	v_cvt_pk_bf16_f32 v112, v114, v115
	v_cvt_pk_bf16_f32 v113, v116, v117
	global_store_dwordx4 v[214:215], v[106:109], off
	global_store_dwordx4 v[214:215], v[110:113], off offset:256
	v_pk_mul_f32 v[102:103], v[102:103], v[134:135]
	v_pk_mul_f32 v[108:109], v[100:101], v[132:133]
	v_pk_mul_f32 v[100:101], v[98:99], v[130:131]
	v_lshlrev_b32_e32 v98, 16, v200
	v_and_b32_e32 v99, 0xffff0000, v200
	v_lshlrev_b32_e32 v106, 16, v198
	v_and_b32_e32 v107, 0xffff0000, v198
	v_pk_mul_f32 v[104:105], v[104:105], v[136:137]
	v_pk_mul_f32 v[98:99], v[102:103], v[98:99]
	v_lshlrev_b32_e32 v102, 16, v201
	v_and_b32_e32 v103, 0xffff0000, v201
	v_pk_mul_f32 v[106:107], v[216:217], v[106:107]
	v_pk_mul_f32 v[102:103], v[104:105], v[102:103]
	v_cvt_pk_bf16_f32 v116, v106, v107
	v_lshlrev_b32_e32 v106, 16, v199
	v_and_b32_e32 v107, 0xffff0000, v199
	v_cvt_pk_bf16_f32 v98, v98, v99
	v_cvt_pk_bf16_f32 v99, v102, v103
	v_lshlrev_b32_e32 v102, 16, v202
	v_and_b32_e32 v103, 0xffff0000, v202
	v_pk_mul_f32 v[106:107], v[212:213], v[106:107]
	v_pk_mul_f32 v[100:101], v[100:101], v[102:103]
	v_lshlrev_b32_e32 v102, 16, v203
	v_and_b32_e32 v103, 0xffff0000, v203
	v_cvt_pk_bf16_f32 v117, v106, v107
	v_lshl_add_u64 v[106:107], s[12:13], 0, v[208:209]
	v_pk_mul_f32 v[102:103], v[108:109], v[102:103]
	v_lshl_add_u64 v[106:107], v[106:107], 0, v[174:175]
	v_cvt_pk_bf16_f32 v100, v100, v101
	v_cvt_pk_bf16_f32 v101, v102, v103
	global_store_dwordx4 v[106:107], v[98:101], off offset:256
	v_pk_mul_f32 v[94:95], v[94:95], v[142:143]
	v_pk_mul_f32 v[96:97], v[96:97], v[144:145]
	v_pk_mul_f32 v[98:99], v[92:93], v[140:141]
	v_pk_mul_f32 v[92:93], v[90:91], v[138:139]
	v_lshlrev_b32_e32 v90, 16, v204
	v_and_b32_e32 v91, 0xffff0000, v204
	v_pk_mul_f32 v[90:91], v[94:95], v[90:91]
	v_lshlrev_b32_e32 v94, 16, v205
	v_and_b32_e32 v95, 0xffff0000, v205
	v_pk_mul_f32 v[94:95], v[96:97], v[94:95]
	v_cvt_pk_bf16_f32 v90, v90, v91
	v_cvt_pk_bf16_f32 v91, v94, v95
	v_lshlrev_b32_e32 v94, 16, v206
	v_and_b32_e32 v95, 0xffff0000, v206
	v_pk_mul_f32 v[92:93], v[92:93], v[94:95]
	v_lshlrev_b32_e32 v94, 16, v207
	v_and_b32_e32 v95, 0xffff0000, v207
	v_pk_mul_f32 v[94:95], v[98:99], v[94:95]
	v_cvt_pk_bf16_f32 v92, v92, v93
	v_cvt_pk_bf16_f32 v93, v94, v95
	v_lshl_add_u64 v[94:95], s[12:13], 0, v[210:211]
	v_lshl_add_u64 v[102:103], v[178:179], 0, s[16:17]
	v_lshl_add_u64 v[94:95], v[94:95], 0, v[174:175]
	v_pk_mul_f32 v[86:87], v[86:87], v[134:135]
	v_lshl_add_u64 v[96:97], v[176:177], 0, v[102:103]
	v_lshlrev_b32_e32 v98, 16, v154
	v_and_b32_e32 v99, 0xffff0000, v154
	global_store_dwordx4 v[94:95], v[90:93], off
	v_pk_mul_f32 v[88:89], v[88:89], v[136:137]
	v_pk_mul_f32 v[86:87], v[86:87], v[98:99]
	v_pk_mul_f32 v[90:91], v[84:85], v[132:133]
	v_pk_mul_f32 v[92:93], v[82:83], v[130:131]
	global_load_dwordx4 v[82:85], v[96:97], off
	v_lshlrev_b32_e32 v98, 16, v155
	v_and_b32_e32 v99, 0xffff0000, v155
	v_pk_mul_f32 v[88:89], v[88:89], v[98:99]
	v_cvt_pk_bf16_f32 v86, v86, v87
	v_cvt_pk_bf16_f32 v87, v88, v89
	v_lshlrev_b32_e32 v88, 16, v156
	v_and_b32_e32 v89, 0xffff0000, v156
	v_pk_mul_f32 v[88:89], v[92:93], v[88:89]
	v_lshlrev_b32_e32 v92, 16, v157
	v_and_b32_e32 v93, 0xffff0000, v157
	v_pk_mul_f32 v[90:91], v[90:91], v[92:93]
	v_cvt_pk_bf16_f32 v88, v88, v89
	v_cvt_pk_bf16_f32 v89, v90, v91
	global_store_dwordx4 v[94:95], v[86:89], off offset:256
	v_pk_mul_f32 v[80:81], v[80:81], v[144:145]
	v_pk_mul_f32 v[90:91], v[76:77], v[140:141]
	v_pk_mul_f32 v[86:87], v[78:79], v[142:143]
	v_lshlrev_b32_e32 v88, 16, v150
	v_and_b32_e32 v89, 0xffff0000, v150
	v_pk_mul_f32 v[86:87], v[86:87], v[88:89]
	v_lshlrev_b32_e32 v88, 16, v151
; #define PG8_GAS __attribute__((address_space(1)))
; __device__ __forceinline__ unsigned cvt_pk_bf16(float lo, float hi) { const f32x2c v = {lo, hi}; return __builtin_bit_cast(unsigned, __builtin_convertvector(v, bf16x2c)); }
; __device__ __forceinline__ float bf_lo(unsigned w) { return __uint_as_float(w << 16); }
; __device__ __forceinline__ float bf_hi(unsigned w) { return __uint_as_float(w & 0xffff0000u); }
;     __device__ __forceinline__ void operator()(const f32x4 (&acc)[2][2][4][2], const Unit& un, int wr, int wc, int fr, int fq) const {
;     ...
;         for (int ai = 0; ai < 2; ++ai) {
;             u32x4 gg[4][2];
; #pragma unroll
;             for (int m = 0; m < 4; ++m)
; #pragma unroll
;                 for (int bj = 0; bj < 2; ++bj) gg[m][bj] = *(const PG8_GAS u32x4*)(sp + (size_t)(row0 + ai * HALF + m * 16) * 4096 + col0 + bj * HALF);
;             asm volatile("" ::: "memory");
; #pragma unroll
;             for (int m = 0; m < 4; ++m)
; #pragma unroll
;                 for (int bj = 0; bj < 2; ++bj) { const u32x4 g = gg[m][bj];
;                     const f32x4 v0 = acc[ai][bj][m][0] * sc[bj][0], v1 = acc[ai][bj][m][1] * sc[bj][1];
;                     u32x4 w; w.x = cvt_pk_bf16(v0[0] * bf_lo(g.x), v0[1] * bf_hi(g.x)); w.y = cvt_pk_bf16(v0[2] * bf_lo(g.y), v0[3] * bf_hi(g.y));
;                     w.z = cvt_pk_bf16(v1[0] * bf_lo(g.z), v1[1] * bf_hi(g.z)); w.w = cvt_pk_bf16(v1[2] * bf_lo(g.w), v1[3] * bf_hi(g.w));
;                     *(PG8_GAS u32x4*)(sp + (size_t)(row0 + ai * HALF + m * 16) * 4096 + col0 + bj * HALF) = w; }
	v_and_b32_e32 v89, 0xffff0000, v151
	global_load_dwordx4 v[76:79], v[96:97], off offset:256
	v_pk_mul_f32 v[80:81], v[80:81], v[88:89]
	v_pk_mul_f32 v[74:75], v[74:75], v[138:139]
	v_cvt_pk_bf16_f32 v86, v86, v87
	v_cvt_pk_bf16_f32 v87, v80, v81
	v_lshlrev_b32_e32 v80, 16, v152
	v_and_b32_e32 v81, 0xffff0000, v152
	v_pk_mul_f32 v[74:75], v[74:75], v[80:81]
	v_lshl_add_u64 v[80:81], v[178:179], 0, s[20:21]
	v_cvt_pk_bf16_f32 v88, v74, v75
	v_lshlrev_b32_e32 v74, 16, v153
	v_and_b32_e32 v75, 0xffff0000, v153
	v_pk_mul_f32 v[74:75], v[90:91], v[74:75]
	v_lshl_add_u64 v[90:91], v[176:177], 0, v[80:81]
	v_cvt_pk_bf16_f32 v89, v74, v75
	v_lshl_add_u64 v[74:75], s[12:13], 0, v[180:181]
	v_lshl_add_u64 v[74:75], v[74:75], 0, v[174:175]
	global_store_dwordx4 v[74:75], v[86:89], off
	global_load_dwordx4 v[86:89], v[90:91], off
	v_pk_mul_f32 v[70:71], v[70:71], v[134:135]
	v_pk_mul_f32 v[92:93], v[68:69], v[132:133]
	v_pk_mul_f32 v[68:69], v[66:67], v[130:131]
	v_lshlrev_b32_e32 v66, 16, v146
	v_and_b32_e32 v67, 0xffff0000, v146
	v_pk_mul_f32 v[72:73], v[72:73], v[136:137]
	v_pk_mul_f32 v[66:67], v[70:71], v[66:67]
	v_lshlrev_b32_e32 v70, 16, v147
	v_and_b32_e32 v71, 0xffff0000, v147
	v_pk_mul_f32 v[70:71], v[72:73], v[70:71]
	v_cvt_pk_bf16_f32 v66, v66, v67
	v_cvt_pk_bf16_f32 v67, v70, v71
	v_lshlrev_b32_e32 v70, 16, v148
	v_and_b32_e32 v71, 0xffff0000, v148
	v_pk_mul_f32 v[68:69], v[68:69], v[70:71]
	v_lshlrev_b32_e32 v70, 16, v149
	v_and_b32_e32 v71, 0xffff0000, v149
	v_pk_mul_f32 v[70:71], v[92:93], v[70:71]
	global_load_dwordx4 v[90:93], v[90:91], off offset:256
	v_cvt_pk_bf16_f32 v114, v126, v127
	v_cvt_pk_bf16_f32 v115, v128, v129
	v_cvt_pk_bf16_f32 v68, v68, v69
	v_cvt_pk_bf16_f32 v69, v70, v71
	v_lshl_add_u64 v[104:105], v[178:179], 0, s[22:23]
	global_store_dwordx4 v[106:107], v[114:117], off
	global_store_dwordx4 v[74:75], v[66:69], off offset:256
	v_lshl_add_u64 v[74:75], v[178:179], 0, s[24:25]
	v_pk_mul_f32 v[62:63], v[62:63], v[142:143]
	v_lshl_add_u64 v[66:67], v[176:177], 0, v[104:105]
	global_load_dwordx4 v[94:97], v[66:67], off
	global_load_dwordx4 v[98:101], v[66:67], off offset:256
	v_lshl_add_u64 v[66:67], v[176:177], 0, v[74:75]
	global_load_dwordx4 v[70:73], v[66:67], off
	s_nop 0
	global_load_dwordx4 v[66:69], v[66:67], off offset:256
	v_pk_mul_f32 v[106:107], v[60:61], v[140:141]
	v_pk_mul_f32 v[60:61], v[58:59], v[138:139]
	v_pk_mul_f32 v[64:65], v[64:65], v[144:145]
	v_pk_mul_f32 v[54:55], v[54:55], v[134:135]
	v_pk_mul_f32 v[56:57], v[56:57], v[136:137]
	s_waitcnt vmcnt(11)
	v_lshlrev_b32_e32 v58, 16, v82
	v_and_b32_e32 v59, 0xffff0000, v82
	v_pk_mul_f32 v[58:59], v[62:63], v[58:59]
	v_lshlrev_b32_e32 v62, 16, v83
	v_and_b32_e32 v63, 0xffff0000, v83
	v_pk_mul_f32 v[62:63], v[64:65], v[62:63]
	v_cvt_pk_bf16_f32 v58, v58, v59
	v_cvt_pk_bf16_f32 v59, v62, v63
	v_lshlrev_b32_e32 v62, 16, v84
	v_and_b32_e32 v63, 0xffff0000, v84
	v_pk_mul_f32 v[60:61], v[60:61], v[62:63]
	v_lshlrev_b32_e32 v62, 16, v85
	v_and_b32_e32 v63, 0xffff0000, v85
	v_pk_mul_f32 v[62:63], v[106:107], v[62:63]
	v_cvt_pk_bf16_f32 v60, v60, v61
	v_cvt_pk_bf16_f32 v61, v62, v63
	v_lshl_add_u64 v[62:63], s[12:13], 0, v[102:103]
	v_lshl_add_u64 v[62:63], v[62:63], 0, v[174:175]
	global_store_dwordx4 v[62:63], v[58:61], off
	v_pk_mul_f32 v[46:47], v[46:47], v[142:143]
	v_pk_mul_f32 v[48:49], v[48:49], v[144:145]
	v_pk_mul_f32 v[58:59], v[52:53], v[132:133]
	v_pk_mul_f32 v[52:53], v[50:51], v[130:131]
	s_waitcnt vmcnt(10)
	v_lshlrev_b32_e32 v50, 16, v76
	v_and_b32_e32 v51, 0xffff0000, v76
	v_pk_mul_f32 v[50:51], v[54:55], v[50:51]
	v_lshlrev_b32_e32 v54, 16, v77
	v_and_b32_e32 v55, 0xffff0000, v77
	v_pk_mul_f32 v[54:55], v[56:57], v[54:55]
	v_cvt_pk_bf16_f32 v50, v50, v51
	v_cvt_pk_bf16_f32 v51, v54, v55
	v_lshlrev_b32_e32 v54, 16, v78
	v_and_b32_e32 v55, 0xffff0000, v78
	v_pk_mul_f32 v[52:53], v[52:53], v[54:55]
	v_lshlrev_b32_e32 v54, 16, v79
	v_and_b32_e32 v55, 0xffff0000, v79
	v_pk_mul_f32 v[54:55], v[58:59], v[54:55]
	v_cvt_pk_bf16_f32 v52, v52, v53
	v_cvt_pk_bf16_f32 v53, v54, v55
	global_store_dwordx4 v[62:63], v[50:53], off offset:256
	v_pk_mul_f32 v[38:39], v[38:39], v[134:135]
	v_pk_mul_f32 v[40:41], v[40:41], v[136:137]
	v_pk_mul_f32 v[50:51], v[44:45], v[140:141]
	v_pk_mul_f32 v[44:45], v[42:43], v[138:139]
	s_waitcnt vmcnt(9)
; #define PG8_GAS __attribute__((address_space(1)))
; __device__ __forceinline__ unsigned cvt_pk_bf16(float lo, float hi) { const f32x2c v = {lo, hi}; return __builtin_bit_cast(unsigned, __builtin_convertvector(v, bf16x2c)); }
; __device__ __forceinline__ float bf_lo(unsigned w) { return __uint_as_float(w << 16); }
; __device__ __forceinline__ float bf_hi(unsigned w) { return __uint_as_float(w & 0xffff0000u); }
;     __device__ __forceinline__ void operator()(const f32x4 (&acc)[2][2][4][2], const Unit& un, int wr, int wc, int fr, int fq) const {
;     ...
;             for (int m = 0; m < 4; ++m)
; #pragma unroll
;                 for (int bj = 0; bj < 2; ++bj) { const u32x4 g = gg[m][bj];
;                     const f32x4 v0 = acc[ai][bj][m][0] * sc[bj][0], v1 = acc[ai][bj][m][1] * sc[bj][1];
;                     u32x4 w; w.x = cvt_pk_bf16(v0[0] * bf_lo(g.x), v0[1] * bf_hi(g.x)); w.y = cvt_pk_bf16(v0[2] * bf_lo(g.y), v0[3] * bf_hi(g.y));
;                     w.z = cvt_pk_bf16(v1[0] * bf_lo(g.z), v1[1] * bf_hi(g.z)); w.w = cvt_pk_bf16(v1[2] * bf_lo(g.w), v1[3] * bf_hi(g.w));
;                     *(PG8_GAS u32x4*)(sp + (size_t)(row0 + ai * HALF + m * 16) * 4096 + col0 + bj * HALF) = w; }
; template <class Epi, class Sched, bool ALIGN_EPI = false, bool SP2 = false, bool F8 = false>
; __device__ __forceinline__ void gemm_phase(PG8_LAS unsigned char* lds, const Gemm g, const Sched& S, const Epi& E) {
;     ...
;         if (!has_next) break;
	v_lshlrev_b32_e32 v42, 16, v86
	v_and_b32_e32 v43, 0xffff0000, v86
	v_pk_mul_f32 v[42:43], v[46:47], v[42:43]
	v_lshlrev_b32_e32 v46, 16, v87
	v_and_b32_e32 v47, 0xffff0000, v87
	v_pk_mul_f32 v[46:47], v[48:49], v[46:47]
	v_cvt_pk_bf16_f32 v42, v42, v43
	v_cvt_pk_bf16_f32 v43, v46, v47
	v_lshlrev_b32_e32 v46, 16, v88
	v_and_b32_e32 v47, 0xffff0000, v88
	v_pk_mul_f32 v[44:45], v[44:45], v[46:47]
	v_lshlrev_b32_e32 v46, 16, v89
	v_and_b32_e32 v47, 0xffff0000, v89
	v_pk_mul_f32 v[46:47], v[50:51], v[46:47]
	v_cvt_pk_bf16_f32 v44, v44, v45
	v_cvt_pk_bf16_f32 v45, v46, v47
	v_lshl_add_u64 v[46:47], s[12:13], 0, v[80:81]
	v_lshl_add_u64 v[46:47], v[46:47], 0, v[174:175]
	global_store_dwordx4 v[46:47], v[42:45], off
	v_pk_mul_f32 v[30:31], v[30:31], v[142:143]
	v_pk_mul_f32 v[32:33], v[32:33], v[144:145]
	v_pk_mul_f32 v[42:43], v[36:37], v[132:133]
	v_pk_mul_f32 v[36:37], v[34:35], v[130:131]
	s_waitcnt vmcnt(9)
	v_lshlrev_b32_e32 v34, 16, v90
	v_and_b32_e32 v35, 0xffff0000, v90
	v_pk_mul_f32 v[34:35], v[38:39], v[34:35]
	v_lshlrev_b32_e32 v38, 16, v91
	v_and_b32_e32 v39, 0xffff0000, v91
	v_pk_mul_f32 v[38:39], v[40:41], v[38:39]
	v_cvt_pk_bf16_f32 v34, v34, v35
	v_cvt_pk_bf16_f32 v35, v38, v39
	v_lshlrev_b32_e32 v38, 16, v92
	v_and_b32_e32 v39, 0xffff0000, v92
	v_pk_mul_f32 v[36:37], v[36:37], v[38:39]
	v_lshlrev_b32_e32 v38, 16, v93
	v_and_b32_e32 v39, 0xffff0000, v93
	v_pk_mul_f32 v[38:39], v[42:43], v[38:39]
	v_cvt_pk_bf16_f32 v36, v36, v37
	v_cvt_pk_bf16_f32 v37, v38, v39
	global_store_dwordx4 v[46:47], v[34:37], off offset:256
	v_pk_mul_f32 v[22:23], v[22:23], v[134:135]
	v_pk_mul_f32 v[24:25], v[24:25], v[136:137]
	v_pk_mul_f32 v[34:35], v[28:29], v[140:141]
	v_pk_mul_f32 v[28:29], v[26:27], v[138:139]
	s_waitcnt vmcnt(7)
	v_lshlrev_b32_e32 v26, 16, v94
	v_and_b32_e32 v27, 0xffff0000, v94
	v_pk_mul_f32 v[26:27], v[30:31], v[26:27]
	v_lshlrev_b32_e32 v30, 16, v95
	v_and_b32_e32 v31, 0xffff0000, v95
	v_pk_mul_f32 v[30:31], v[32:33], v[30:31]
	v_cvt_pk_bf16_f32 v26, v26, v27
	v_cvt_pk_bf16_f32 v27, v30, v31
	v_lshlrev_b32_e32 v30, 16, v96
	v_and_b32_e32 v31, 0xffff0000, v96
	v_pk_mul_f32 v[28:29], v[28:29], v[30:31]
	v_lshlrev_b32_e32 v30, 16, v97
	v_and_b32_e32 v31, 0xffff0000, v97
	v_pk_mul_f32 v[30:31], v[34:35], v[30:31]
	v_cvt_pk_bf16_f32 v28, v28, v29
	v_cvt_pk_bf16_f32 v29, v30, v31
	v_lshl_add_u64 v[30:31], s[12:13], 0, v[104:105]
	v_lshl_add_u64 v[30:31], v[30:31], 0, v[174:175]
	global_store_dwordx4 v[30:31], v[26:29], off
	v_pk_mul_f32 v[14:15], v[14:15], v[142:143]
	v_pk_mul_f32 v[16:17], v[16:17], v[144:145]
	v_pk_mul_f32 v[26:27], v[20:21], v[132:133]
	v_pk_mul_f32 v[20:21], v[18:19], v[130:131]
	s_waitcnt vmcnt(7)
	v_lshlrev_b32_e32 v18, 16, v98
	v_and_b32_e32 v19, 0xffff0000, v98
	v_pk_mul_f32 v[18:19], v[22:23], v[18:19]
	v_lshlrev_b32_e32 v22, 16, v99
	v_and_b32_e32 v23, 0xffff0000, v99
	v_pk_mul_f32 v[22:23], v[24:25], v[22:23]
	v_cvt_pk_bf16_f32 v18, v18, v19
	v_cvt_pk_bf16_f32 v19, v22, v23
	v_lshlrev_b32_e32 v22, 16, v100
	v_and_b32_e32 v23, 0xffff0000, v100
	v_pk_mul_f32 v[20:21], v[20:21], v[22:23]
	v_lshlrev_b32_e32 v22, 16, v101
	v_and_b32_e32 v23, 0xffff0000, v101
	v_pk_mul_f32 v[22:23], v[26:27], v[22:23]
	v_cvt_pk_bf16_f32 v20, v20, v21
	v_cvt_pk_bf16_f32 v21, v22, v23
	global_store_dwordx4 v[30:31], v[18:21], off offset:256
	v_pk_mul_f32 v[6:7], v[6:7], v[134:135]
	v_pk_mul_f32 v[8:9], v[8:9], v[136:137]
	v_pk_mul_f32 v[18:19], v[12:13], v[140:141]
	v_pk_mul_f32 v[12:13], v[10:11], v[138:139]
	s_waitcnt vmcnt(7)
	v_lshlrev_b32_e32 v10, 16, v70
	v_and_b32_e32 v11, 0xffff0000, v70
	v_pk_mul_f32 v[10:11], v[14:15], v[10:11]
	v_lshlrev_b32_e32 v14, 16, v71
	v_and_b32_e32 v15, 0xffff0000, v71
	v_pk_mul_f32 v[14:15], v[16:17], v[14:15]
	v_cvt_pk_bf16_f32 v10, v10, v11
	v_cvt_pk_bf16_f32 v11, v14, v15
	v_lshlrev_b32_e32 v14, 16, v72
	v_and_b32_e32 v15, 0xffff0000, v72
	v_pk_mul_f32 v[12:13], v[12:13], v[14:15]
	v_lshlrev_b32_e32 v14, 16, v73
	v_and_b32_e32 v15, 0xffff0000, v73
	v_pk_mul_f32 v[14:15], v[18:19], v[14:15]
	v_cvt_pk_bf16_f32 v12, v12, v13
	v_cvt_pk_bf16_f32 v13, v14, v15
	v_lshl_add_u64 v[14:15], s[12:13], 0, v[74:75]
	v_lshl_add_u64 v[14:15], v[14:15], 0, v[174:175]
	global_store_dwordx4 v[14:15], v[10:13], off
	s_nop 1
	v_pk_mul_f32 v[10:11], v[4:5], v[132:133]
	v_pk_mul_f32 v[4:5], v[2:3], v[130:131]
	s_waitcnt vmcnt(7)
	v_lshlrev_b32_e32 v2, 16, v66
	v_and_b32_e32 v3, 0xffff0000, v66
	v_pk_mul_f32 v[2:3], v[6:7], v[2:3]
	v_lshlrev_b32_e32 v6, 16, v67
	v_and_b32_e32 v7, 0xffff0000, v67
	v_pk_mul_f32 v[6:7], v[8:9], v[6:7]
	v_cvt_pk_bf16_f32 v2, v2, v3
	v_cvt_pk_bf16_f32 v3, v6, v7
	v_lshlrev_b32_e32 v6, 16, v68
	v_and_b32_e32 v7, 0xffff0000, v68
	v_pk_mul_f32 v[4:5], v[4:5], v[6:7]
	v_lshlrev_b32_e32 v6, 16, v69
	v_and_b32_e32 v7, 0xffff0000, v69
	v_pk_mul_f32 v[6:7], v[10:11], v[6:7]
	v_cvt_pk_bf16_f32 v4, v4, v5
	v_cvt_pk_bf16_f32 v5, v6, v7
	global_store_dwordx4 v[14:15], v[2:5], off offset:256
	s_cbranch_vccz .LBB0_615
	s_waitcnt vmcnt(0)
	s_cmpk_gt_u32 s4, 0xff
	s_cbranch_scc1 .LBB0_622
	s_barrier

; #define PG8_STAGE(bufoff, gbase, voff) do { _Pragma("unroll") for (int _i = 0; _i < 2; ++_i) \
;         __builtin_amdgcn_global_load_lds((const unsigned*)((const char*)(gbase) + (voff)[_i]), (PG8_LAS unsigned*)(lds + (bufoff) + ldsw + _i * 8192), 16, 0, 0); } while (0)
; #define PG8_LDA(dst, b, h) do { _Pragma("unroll") for (int m = 0; m < 4; ++m) _Pragma("unroll") for (int k = 0; k < 2; ++k) dst[m][k] = *(const PG8_LAS bf16x8*)(lds + PG8_SA(b, h) + aoff + m * 2048 + k * 1024); } while (0)
; #define PG8_LDB(dst, b, h) do { _Pragma("unroll") for (int n = 0; n < 2; ++n) _Pragma("unroll") for (int k = 0; k < 2; ++k) dst[n][k] = *(const PG8_LAS bf16x8*)(lds + PG8_SB(b, h) + boff + n * 2048 + k * 1024); } while (0)
; #define PG8_WAIT_V(n) asm volatile("s_waitcnt vmcnt(" #n ")" ::: "memory")
; #define PG8_WAIT_L(n) asm volatile("s_waitcnt lgkmcnt(" #n ")" ::: "memory")
; #define PG8_BAR __builtin_amdgcn_s_barrier()
; #define PG8_SCHED __builtin_amdgcn_sched_barrier(0)
; template <class Epi, class Sched, bool ALIGN_EPI = false, bool SP2 = false, bool F8 = false>
; __device__ __forceinline__ void gemm_phase(PG8_LAS unsigned char* lds, const Gemm g, const Sched& S, const Epi& E) {
;     ...
;         for (int t = 0; t < nt; t += 2) {
;             const bool last = (t == nt - 2);
;             const char* a1 = cA + (size_t)(t + 1) * kstep;
;             const char* a2 = last ? nA : cA + (size_t)(t + 2) * kstep; const char* b2 = last ? nB : cB + (size_t)(t + 2) * kstep;
;             const char* a3 = a2 + kstep; const char* b3 = b2 + kstep;
;             if (last && has_next) S.a_ready(nxt);
;             if constexpr (SP2) {
;             PG8_LDB(B0, 0, 0); PG8_LDB(B1, 0, 1); PG8_SCHED; PG8_LDA(At, 0, 0); PG8_STAGE(PG8_SA(1, 1), a1 + hA, voffA);
;             PG8_WAIT_V(8); PG8_WAIT_L(0); PG8_BAR; PG8_MMA(0, 0, At, B0); PG8_MMA(0, 1, At, B1); PG8_BAR; PG8_SCHED;
;             PG8_LDA(At, 0, 1); PG8_STAGE(PG8_SB(0, 0), b2, voffB); PG8_STAGE(PG8_SB(0, 1), b2 + hB, voffB); PG8_STAGE(PG8_SA(0, 0), a2, voffA);
;             PG8_WAIT_V(8); PG8_WAIT_L(0); PG8_BAR; PG8_MMA(1, 0, At, B0); PG8_MMA(1, 1, At, B1); PG8_BAR; PG8_SCHED;
.LBB0_630:
	ds_read_b128 v[26:29], v190
	ds_read_b128 v[30:33], v190 offset:1024
	ds_read_b128 v[18:21], v190 offset:2048
	ds_read_b128 v[22:25], v190 offset:3072
	ds_read_b128 v[10:13], v191
	ds_read_b128 v[14:17], v191 offset:1024
	ds_read_b128 v[2:5], v191 offset:2048
	ds_read_b128 v[6:9], v191 offset:3072
	s_add_u32 s30, s28, 0xfffc0080
	s_addc_u32 s31, s29, -1
	s_cmp_eq_u32 s51, 12
	s_cselect_b32 s35, s21, s31
	s_cselect_b32 s34, s47, s30
	s_cselect_b32 s31, s17, s50
	s_cselect_b32 s30, s48, s49
	v_lshl_add_u64 v[218:219], s[28:29], 0, v[172:173]
	s_add_i32 m0, s27, 0xc000
	ds_read_b128 v[178:181], v192
	ds_read_b128 v[182:185], v192 offset:1024
	ds_read_b128 v[194:197], v192 offset:2048
	ds_read_b128 v[198:201], v192 offset:3072
	ds_read_b128 v[202:205], v192 offset:4096
	ds_read_b128 v[206:209], v192 offset:5120
	ds_read_b128 v[210:213], v192 offset:6144
	ds_read_b128 v[214:217], v192 offset:7168
	global_load_lds_dwordx4 v[218:219], off
	v_lshl_add_u64 v[218:219], s[28:29], 0, v[170:171]
	s_add_i32 m0, s27, 0xe000
	s_nop 0
	global_load_lds_dwordx4 v[218:219], off
	s_waitcnt vmcnt(8)
	s_waitcnt lgkmcnt(0)
	s_setprio 1
	s_barrier
	v_mfma_scale_f32_16x16x128_f8f6f4 v[158:161], v[26:33], v[178:185], v[158:161], v186, v186 op_sel_hi:[0,0,0]
	v_mfma_scale_f32_16x16x128_f8f6f4 v[154:157], v[18:25], v[178:185], v[154:157], v186, v186 op_sel_hi:[0,0,0]
	v_mfma_scale_f32_16x16x128_f8f6f4 v[146:149], v[26:33], v[194:201], v[146:149], v186, v186 op_sel_hi:[0,0,0]
	v_mfma_scale_f32_16x16x128_f8f6f4 v[138:141], v[18:25], v[194:201], v[138:141], v186, v186 op_sel_hi:[0,0,0]
	v_mfma_scale_f32_16x16x128_f8f6f4 v[130:133], v[26:33], v[202:209], v[130:133], v186, v186 op_sel_hi:[0,0,0]
	v_mfma_scale_f32_16x16x128_f8f6f4 v[122:125], v[18:25], v[202:209], v[122:125], v186, v186 op_sel_hi:[0,0,0]
	v_mfma_scale_f32_16x16x128_f8f6f4 v[114:117], v[26:33], v[210:217], v[114:117], v186, v186 op_sel_hi:[0,0,0]
	v_mfma_scale_f32_16x16x128_f8f6f4 v[106:109], v[18:25], v[210:217], v[106:109], v186, v186 op_sel_hi:[0,0,0]
	v_mfma_scale_f32_16x16x128_f8f6f4 v[150:153], v[10:17], v[178:185], v[150:153], v186, v186 op_sel_hi:[0,0,0]
	v_mfma_scale_f32_16x16x128_f8f6f4 v[142:145], v[2:9], v[178:185], v[142:145], v186, v186 op_sel_hi:[0,0,0]
	v_mfma_scale_f32_16x16x128_f8f6f4 v[134:137], v[10:17], v[194:201], v[134:137], v186, v186 op_sel_hi:[0,0,0]
	v_mfma_scale_f32_16x16x128_f8f6f4 v[126:129], v[2:9], v[194:201], v[126:129], v186, v186 op_sel_hi:[0,0,0]
	v_mfma_scale_f32_16x16x128_f8f6f4 v[118:121], v[10:17], v[202:209], v[118:121], v186, v186 op_sel_hi:[0,0,0]
	v_mfma_scale_f32_16x16x128_f8f6f4 v[110:113], v[2:9], v[202:209], v[110:113], v186, v186 op_sel_hi:[0,0,0]
	v_mfma_scale_f32_16x16x128_f8f6f4 v[102:105], v[10:17], v[210:217], v[102:105], v186, v186 op_sel_hi:[0,0,0]
	v_mfma_scale_f32_16x16x128_f8f6f4 v[98:101], v[2:9], v[210:217], v[98:101], v186, v186 op_sel_hi:[0,0,0]
	s_barrier
	s_setprio 0
	s_add_i32 s52, s44, s19
	v_lshl_add_u64 v[178:179], s[30:31], 0, v[166:167]
	s_mov_b32 m0, s52
	ds_read_b128 v[194:197], v192 offset:16384
	ds_read_b128 v[198:201], v192 offset:17408
	ds_read_b128 v[202:205], v192 offset:18432
	ds_read_b128 v[206:209], v192 offset:19456
	ds_read_b128 v[210:213], v192 offset:20480
	ds_read_b128 v[214:217], v192 offset:21504
	ds_read_b128 v[218:221], v192 offset:22528
	ds_read_b128 v[222:225], v192 offset:23552
	global_load_lds_dwordx4 v[178:179], off
	s_add_i32 m0, s52, 0x2000
	s_add_u32 s52, s30, 0x40000
	v_lshl_add_u64 v[180:181], s[30:31], 0, v[162:163]
	s_addc_u32 s53, s31, 0
	s_add_i32 s54, s45, s19
	global_load_lds_dwordx4 v[180:181], off
	v_lshl_add_u64 v[182:183], s[52:53], 0, v[166:167]
	s_mov_b32 m0, s54
	v_lshl_add_u64 v[184:185], s[34:35], 0, v[164:165]
	global_load_lds_dwordx4 v[182:183], off
	v_lshl_add_u64 v[182:183], s[52:53], 0, v[162:163]
	s_add_i32 m0, s54, 0x2000
	s_nop 0
	global_load_lds_dwordx4 v[182:183], off
	v_lshl_add_u64 v[182:183], s[34:35], 0, v[168:169]
	s_mov_b32 m0, s27
	s_nop 0
	global_load_lds_dwordx4 v[182:183], off
	s_mov_b32 m0, s37
	s_nop 0
	global_load_lds_dwordx4 v[184:185], off
	s_waitcnt vmcnt(8)
	s_waitcnt lgkmcnt(0)
	s_setprio 1
	s_barrier
	v_mfma_scale_f32_16x16x128_f8f6f4 v[94:97], v[26:33], v[194:201], v[94:97], v186, v186 op_sel_hi:[0,0,0]
	v_mfma_scale_f32_16x16x128_f8f6f4 v[90:93], v[18:25], v[194:201], v[90:93], v186, v186 op_sel_hi:[0,0,0]
	v_mfma_scale_f32_16x16x128_f8f6f4 v[82:85], v[26:33], v[202:209], v[82:85], v186, v186 op_sel_hi:[0,0,0]
	v_mfma_scale_f32_16x16x128_f8f6f4 v[74:77], v[18:25], v[202:209], v[74:77], v186, v186 op_sel_hi:[0,0,0]
	v_mfma_scale_f32_16x16x128_f8f6f4 v[66:69], v[26:33], v[210:217], v[66:69], v186, v186 op_sel_hi:[0,0,0]
	v_mfma_scale_f32_16x16x128_f8f6f4 v[58:61], v[18:25], v[210:217], v[58:61], v186, v186 op_sel_hi:[0,0,0]
	v_mfma_scale_f32_16x16x128_f8f6f4 v[50:53], v[26:33], v[218:225], v[50:53], v186, v186 op_sel_hi:[0,0,0]
	v_mfma_scale_f32_16x16x128_f8f6f4 v[42:45], v[18:25], v[218:225], v[42:45], v186, v186 op_sel_hi:[0,0,0]
	v_mfma_scale_f32_16x16x128_f8f6f4 v[86:89], v[10:17], v[194:201], v[86:89], v186, v186 op_sel_hi:[0,0,0]
	v_mfma_scale_f32_16x16x128_f8f6f4 v[78:81], v[2:9], v[194:201], v[78:81], v186, v186 op_sel_hi:[0,0,0]
	v_mfma_scale_f32_16x16x128_f8f6f4 v[70:73], v[10:17], v[202:209], v[70:73], v186, v186 op_sel_hi:[0,0,0]
	v_mfma_scale_f32_16x16x128_f8f6f4 v[62:65], v[2:9], v[202:209], v[62:65], v186, v186 op_sel_hi:[0,0,0]
	v_mfma_scale_f32_16x16x128_f8f6f4 v[54:57], v[10:17], v[210:217], v[54:57], v186, v186 op_sel_hi:[0,0,0]
	v_mfma_scale_f32_16x16x128_f8f6f4 v[46:49], v[2:9], v[210:217], v[46:49], v186, v186 op_sel_hi:[0,0,0]
	v_mfma_scale_f32_16x16x128_f8f6f4 v[38:41], v[10:17], v[218:225], v[38:41], v186, v186 op_sel_hi:[0,0,0]
	v_mfma_scale_f32_16x16x128_f8f6f4 v[34:37], v[2:9], v[218:225], v[34:37], v186, v186 op_sel_hi:[0,0,0]
	s_barrier
; #define PG8_STAGE(bufoff, gbase, voff) do { _Pragma("unroll") for (int _i = 0; _i < 2; ++_i) \
;         __builtin_amdgcn_global_load_lds((const unsigned*)((const char*)(gbase) + (voff)[_i]), (PG8_LAS unsigned*)(lds + (bufoff) + ldsw + _i * 8192), 16, 0, 0); } while (0)
; #define PG8_LDA(dst, b, h) do { _Pragma("unroll") for (int m = 0; m < 4; ++m) _Pragma("unroll") for (int k = 0; k < 2; ++k) dst[m][k] = *(const PG8_LAS bf16x8*)(lds + PG8_SA(b, h) + aoff + m * 2048 + k * 1024); } while (0)
; #define PG8_LDB(dst, b, h) do { _Pragma("unroll") for (int n = 0; n < 2; ++n) _Pragma("unroll") for (int k = 0; k < 2; ++k) dst[n][k] = *(const PG8_LAS bf16x8*)(lds + PG8_SB(b, h) + boff + n * 2048 + k * 1024); } while (0)
; #define PG8_WAIT_V(n) asm volatile("s_waitcnt vmcnt(" #n ")" ::: "memory")
; #define PG8_WAIT_L(n) asm volatile("s_waitcnt lgkmcnt(" #n ")" ::: "memory")
; #define PG8_BAR __builtin_amdgcn_s_barrier()
; #define PG8_SCHED __builtin_amdgcn_sched_barrier(0)
; template <class Epi, class Sched, bool ALIGN_EPI = false, bool SP2 = false, bool F8 = false>
; __device__ __forceinline__ void gemm_phase(PG8_LAS unsigned char* lds, const Gemm g, const Sched& S, const Epi& E) {
;     ...
;             PG8_WAIT_V(8); PG8_WAIT_L(0); PG8_BAR; PG8_MMA(1, 0, At, B0); PG8_MMA(1, 1, At, B1); PG8_BAR; PG8_SCHED;
;             PG8_LDB(B0, 1, 0); PG8_LDB(B1, 1, 1); PG8_SCHED; PG8_LDA(At, 1, 0); PG8_STAGE(PG8_SA(0, 1), a2 + hA, voffA);
;             PG8_WAIT_V(8); PG8_WAIT_L(0); PG8_BAR; PG8_MMA(0, 0, At, B0); PG8_MMA(0, 1, At, B1); PG8_BAR; PG8_SCHED;
;             PG8_LDA(At, 1, 1); PG8_STAGE(PG8_SB(1, 0), b3, voffB); PG8_STAGE(PG8_SB(1, 1), b3 + hB, voffB); PG8_STAGE(PG8_SA(1, 0), a3, voffA);
;             PG8_WAIT_V(8); PG8_WAIT_L(0); PG8_BAR; PG8_MMA(1, 0, At, B0); PG8_MMA(1, 1, At, B1); PG8_BAR; PG8_SCHED;
	s_setprio 0
	s_add_i32 s52, 0, 0x18000
	s_add_i32 s53, 0, 0x1c000
	v_add_u32_e32 v14, s52, v188
	v_add_u32_e32 v30, s53, v188
	ds_read_b128 v[2:5], v14
	ds_read_b128 v[6:9], v14 offset:1024
	ds_read_b128 v[10:13], v14 offset:2048
	ds_read_b128 v[14:17], v14 offset:3072
	ds_read_b128 v[18:21], v30
	ds_read_b128 v[22:25], v30 offset:1024
	ds_read_b128 v[26:29], v30 offset:2048
	ds_read_b128 v[30:33], v30 offset:3072
	s_add_u32 s34, s34, 0x40000
	s_addc_u32 s35, s35, 0
	s_mov_b32 m0, s38
	v_lshl_add_u64 v[226:227], s[34:35], 0, v[168:169]
	ds_read_b128 v[194:197], v192 offset:32768
	ds_read_b128 v[198:201], v192 offset:33792
	ds_read_b128 v[202:205], v192 offset:34816
	ds_read_b128 v[206:209], v192 offset:35840
	ds_read_b128 v[210:213], v192 offset:36864
	ds_read_b128 v[214:217], v192 offset:37888
	ds_read_b128 v[218:221], v192 offset:38912
	ds_read_b128 v[222:225], v192 offset:39936
	global_load_lds_dwordx4 v[226:227], off
	v_lshl_add_u64 v[226:227], s[34:35], 0, v[164:165]
	s_mov_b32 m0, s39
	s_nop 0
	global_load_lds_dwordx4 v[226:227], off
	s_waitcnt vmcnt(8)
	s_waitcnt lgkmcnt(0)
	s_setprio 1
	s_barrier
	v_mfma_scale_f32_16x16x128_f8f6f4 v[158:161], v[2:9], v[194:201], v[158:161], v186, v186 op_sel_hi:[0,0,0]
	v_mfma_scale_f32_16x16x128_f8f6f4 v[154:157], v[10:17], v[194:201], v[154:157], v186, v186 op_sel_hi:[0,0,0]
	v_mfma_scale_f32_16x16x128_f8f6f4 v[146:149], v[2:9], v[202:209], v[146:149], v186, v186 op_sel_hi:[0,0,0]
	v_mfma_scale_f32_16x16x128_f8f6f4 v[138:141], v[10:17], v[202:209], v[138:141], v186, v186 op_sel_hi:[0,0,0]
	v_mfma_scale_f32_16x16x128_f8f6f4 v[130:133], v[2:9], v[210:217], v[130:133], v186, v186 op_sel_hi:[0,0,0]
	v_mfma_scale_f32_16x16x128_f8f6f4 v[122:125], v[10:17], v[210:217], v[122:125], v186, v186 op_sel_hi:[0,0,0]
	v_mfma_scale_f32_16x16x128_f8f6f4 v[114:117], v[2:9], v[218:225], v[114:117], v186, v186 op_sel_hi:[0,0,0]
	v_mfma_scale_f32_16x16x128_f8f6f4 v[106:109], v[10:17], v[218:225], v[106:109], v186, v186 op_sel_hi:[0,0,0]
	v_mfma_scale_f32_16x16x128_f8f6f4 v[150:153], v[18:25], v[194:201], v[150:153], v186, v186 op_sel_hi:[0,0,0]
	v_mfma_scale_f32_16x16x128_f8f6f4 v[142:145], v[26:33], v[194:201], v[142:145], v186, v186 op_sel_hi:[0,0,0]
	v_mfma_scale_f32_16x16x128_f8f6f4 v[134:137], v[18:25], v[202:209], v[134:137], v186, v186 op_sel_hi:[0,0,0]
	v_mfma_scale_f32_16x16x128_f8f6f4 v[126:129], v[26:33], v[202:209], v[126:129], v186, v186 op_sel_hi:[0,0,0]
	v_mfma_scale_f32_16x16x128_f8f6f4 v[118:121], v[18:25], v[210:217], v[118:121], v186, v186 op_sel_hi:[0,0,0]
	v_mfma_scale_f32_16x16x128_f8f6f4 v[110:113], v[26:33], v[210:217], v[110:113], v186, v186 op_sel_hi:[0,0,0]
	v_mfma_scale_f32_16x16x128_f8f6f4 v[102:105], v[18:25], v[218:225], v[102:105], v186, v186 op_sel_hi:[0,0,0]
	v_mfma_scale_f32_16x16x128_f8f6f4 v[98:101], v[26:33], v[218:225], v[98:101], v186, v186 op_sel_hi:[0,0,0]
	s_barrier
	s_setprio 0
	s_add_i32 s34, s52, s19
	v_lshl_add_u64 v[178:179], v[178:179], 0, s[14:15]
	s_mov_b32 m0, s34
	ds_read_b128 v[194:197], v192 offset:49152
	ds_read_b128 v[198:201], v192 offset:50176
	ds_read_b128 v[202:205], v192 offset:51200
	ds_read_b128 v[206:209], v192 offset:52224
	ds_read_b128 v[210:213], v192 offset:53248
	ds_read_b128 v[214:217], v192 offset:54272
	ds_read_b128 v[218:221], v192 offset:55296
	ds_read_b128 v[222:225], v192 offset:56320
	global_load_lds_dwordx4 v[178:179], off
	s_add_i32 m0, s34, 0x2000
	s_add_u32 s30, s30, 0x40080
	v_lshl_add_u64 v[178:179], v[180:181], 0, s[14:15]
	s_addc_u32 s31, s31, 0
	s_add_i32 s34, s53, s19
	global_load_lds_dwordx4 v[178:179], off
	v_lshl_add_u64 v[178:179], s[30:31], 0, v[166:167]
	s_mov_b32 m0, s34
	s_nop 0
	global_load_lds_dwordx4 v[178:179], off
	v_lshl_add_u64 v[178:179], s[30:31], 0, v[162:163]
	s_add_i32 m0, s34, 0x2000
	s_nop 0
	global_load_lds_dwordx4 v[178:179], off
	v_lshl_add_u64 v[178:179], v[182:183], 0, s[14:15]
	s_mov_b32 m0, s41
	s_nop 0
	global_load_lds_dwordx4 v[178:179], off
	v_lshl_add_u64 v[178:179], v[184:185], 0, s[14:15]
	s_mov_b32 m0, s42
	s_nop 0
	global_load_lds_dwordx4 v[178:179], off
	s_waitcnt vmcnt(8)
	s_waitcnt lgkmcnt(0)
	s_setprio 1
	s_barrier
	v_mfma_scale_f32_16x16x128_f8f6f4 v[94:97], v[2:9], v[194:201], v[94:97], v186, v186 op_sel_hi:[0,0,0]
	v_mfma_scale_f32_16x16x128_f8f6f4 v[90:93], v[10:17], v[194:201], v[90:93], v186, v186 op_sel_hi:[0,0,0]
	v_mfma_scale_f32_16x16x128_f8f6f4 v[82:85], v[2:9], v[202:209], v[82:85], v186, v186 op_sel_hi:[0,0,0]
	v_mfma_scale_f32_16x16x128_f8f6f4 v[74:77], v[10:17], v[202:209], v[74:77], v186, v186 op_sel_hi:[0,0,0]
	v_mfma_scale_f32_16x16x128_f8f6f4 v[66:69], v[2:9], v[210:217], v[66:69], v186, v186 op_sel_hi:[0,0,0]
	v_mfma_scale_f32_16x16x128_f8f6f4 v[58:61], v[10:17], v[210:217], v[58:61], v186, v186 op_sel_hi:[0,0,0]
	v_mfma_scale_f32_16x16x128_f8f6f4 v[50:53], v[2:9], v[218:225], v[50:53], v186, v186 op_sel_hi:[0,0,0]
	v_mfma_scale_f32_16x16x128_f8f6f4 v[42:45], v[10:17], v[218:225], v[42:45], v186, v186 op_sel_hi:[0,0,0]
	v_mfma_scale_f32_16x16x128_f8f6f4 v[86:89], v[18:25], v[194:201], v[86:89], v186, v186 op_sel_hi:[0,0,0]
	v_mfma_scale_f32_16x16x128_f8f6f4 v[78:81], v[26:33], v[194:201], v[78:81], v186, v186 op_sel_hi:[0,0,0]
	v_mfma_scale_f32_16x16x128_f8f6f4 v[70:73], v[18:25], v[202:209], v[70:73], v186, v186 op_sel_hi:[0,0,0]
	v_mfma_scale_f32_16x16x128_f8f6f4 v[62:65], v[26:33], v[202:209], v[62:65], v186, v186 op_sel_hi:[0,0,0]
	v_mfma_scale_f32_16x16x128_f8f6f4 v[54:57], v[18:25], v[210:217], v[54:57], v186, v186 op_sel_hi:[0,0,0]
	v_mfma_scale_f32_16x16x128_f8f6f4 v[46:49], v[26:33], v[210:217], v[46:49], v186, v186 op_sel_hi:[0,0,0]
	v_mfma_scale_f32_16x16x128_f8f6f4 v[38:41], v[18:25], v[218:225], v[38:41], v186, v186 op_sel_hi:[0,0,0]
	v_mfma_scale_f32_16x16x128_f8f6f4 v[34:37], v[26:33], v[218:225], v[34:37], v186, v186 op_sel_hi:[0,0,0]
	s_barrier
;     __device__ __forceinline__ void operator()(const f32x4 (&acc)[2][2][4][2], const Unit& un, int wr, int wc, int fr, int fq) const {
;         const int row0 = un.pm * BM + wr * 64 + fr, col0 = un.pn * BM + wc * 32 + 8 * fq;
; #pragma unroll
;         for (int ai = 0; ai < 2; ++ai) {
;             u32x4 gg[4][2], pp[4][2];
; #pragma unroll
;             for (int m = 0; m < 4; ++m)
; #pragma unroll
;                 for (int bj = 0; bj < 2; ++bj) { const size_t off = (size_t)(row0 + ai * HALF + m * 16) * 4096 + col0 + bj * HALF; gg[m][bj] = *(const PG8_GAS u32x4*)(sa + off); pp[m][bj] = *(const PG8_GAS u32x4*)(P + off); }
;             asm volatile("" ::: "memory");
; #pragma unroll
;             for (int m = 0; m < 4; ++m)
; #pragma unroll
;                 for (int bj = 0; bj < 2; ++bj) { const u32x4 g = gg[m][bj], p = pp[m][bj]; const f32x4 v0 = acc[ai][bj][m][0], v1 = acc[ai][bj][m][1];
;                     u32x4 w; w.x = cvt_pk_bf16(v0[0] * bf_lo(g.x) + bf_lo(p.x), v0[1] * bf_hi(g.x) + bf_hi(p.x)); w.y = cvt_pk_bf16(v0[2] * bf_lo(g.y) + bf_lo(p.y), v0[3] * bf_hi(g.y) + bf_hi(p.y));
;                     w.z = cvt_pk_bf16(v1[0] * bf_lo(g.z) + bf_lo(p.z), v1[1] * bf_hi(g.z) + bf_hi(p.z)); w.w = cvt_pk_bf16(v1[2] * bf_lo(g.w) + bf_lo(p.w), v1[3] * bf_hi(g.w) + bf_hi(p.w));
;                     *(PG8_GAS u32x4*)(sa + (size_t)(row0 + ai * HALF + m * 16) * 4096 + col0 + bj * HALF) = w; }
; template <class Epi, class Sched, bool ALIGN_EPI = false, bool SP2 = false, bool F8 = false>
; __device__ __forceinline__ void gemm_phase(PG8_LAS unsigned char* lds, const Gemm g, const Sched& S, const Epi& E) {
;     ...
;             PG8_WAIT_V(8); PG8_WAIT_L(0); PG8_BAR; PG8_MMA(0, 0, At, B0); PG8_MMA(0, 1, At, B1); PG8_BAR; PG8_SCHED;
;             PG8_LDA(At, 1, 1); PG8_STAGE(PG8_SB(1, 0), b3, voffB); PG8_STAGE(PG8_SB(1, 1), b3 + hB, voffB); PG8_STAGE(PG8_SA(1, 0), a3, voffA);
;             PG8_WAIT_V(8); PG8_WAIT_L(0); PG8_BAR; PG8_MMA(1, 0, At, B0); PG8_MMA(1, 1, At, B1); PG8_BAR; PG8_SCHED;
;             } else {
;             PG8_LDB(B0, 0, 0); PG8_SCHED; PG8_LDA(At, 0, 0); PG8_STAGE(PG8_SA(1, 1), a1 + hA, voffA);
;             PG8_WAIT_L(8); PG8_BAR; PG8_WAIT_L(0); PG8_MMA(0, 0, At, B0); PG8_BAR; PG8_SCHED;
;             PG8_LDB(B1, 0, 1); PG8_STAGE(PG8_SB(0, 0), b2, voffB);
;             PG8_BAR; PG8_WAIT_L(0); PG8_MMA(0, 1, At, B1); PG8_BAR;
	s_setprio 0
	s_add_i32 s51, s51, 2
	s_add_u32 s49, s49, 0x100
	s_addc_u32 s50, s50, 0
	s_add_u32 s28, s28, 0x100
	s_addc_u32 s29, s29, 0
	s_cmp_gt_u32 s51, 13
	s_cbranch_scc0 .LBB0_630
	v_lshl_add_u32 v182, s26, 8, v187
	v_lshl_or_b32 v180, s46, 8, v189
	v_ashrrev_i32_e32 v183, 31, v182
	v_ashrrev_i32_e32 v181, 31, v180
	v_lshlrev_b64 v[2:3], 12, v[182:183]
	v_lshl_add_u64 v[2:3], v[2:3], 0, v[180:181]
	v_lshlrev_b64 v[2:3], 1, v[2:3]
	s_nop 15
	s_nop 15
	s_nop 7
	v_lshl_add_u64 v[4:5], s[10:11], 0, v[2:3]
	global_load_dwordx4 v[30:33], v[4:5], off
	v_lshl_add_u64 v[4:5], s[12:13], 0, v[2:3]
	global_load_dwordx4 v[194:197], v[4:5], off
	v_or_b32_e32 v2, 0x100, v2
	v_lshl_add_u64 v[4:5], s[10:11], 0, v[2:3]
	v_lshl_add_u64 v[2:3], s[12:13], 0, v[2:3]
	global_load_dwordx4 v[198:201], v[4:5], off
	global_load_dwordx4 v[202:205], v[2:3], off
	v_or_b32_e32 v184, 16, v182
	v_ashrrev_i32_e32 v185, 31, v184
	v_lshlrev_b64 v[2:3], 13, v[182:183]
	v_lshlrev_b64 v[4:5], 12, v[184:185]
	v_lshlrev_b64 v[178:179], 1, v[180:181]
	v_lshl_add_u64 v[2:3], s[10:11], 0, v[2:3]
	v_lshl_add_u64 v[4:5], v[4:5], 0, v[180:181]
	v_lshl_add_u64 v[230:231], v[2:3], 0, v[178:179]
	v_lshlrev_b64 v[2:3], 1, v[4:5]
	v_lshl_add_u64 v[4:5], s[10:11], 0, v[2:3]
	global_load_dwordx4 v[206:209], v[4:5], off
	v_lshl_add_u64 v[4:5], s[12:13], 0, v[2:3]
	global_load_dwordx4 v[210:213], v[4:5], off
	v_or_b32_e32 v28, 32, v182
	v_or_b32_e32 v26, 48, v182
	v_ashrrev_i32_e32 v29, 31, v28
	v_ashrrev_i32_e32 v27, 31, v26
	v_lshlrev_b64 v[6:7], 12, v[28:29]
	v_lshlrev_b64 v[8:9], 12, v[26:27]
	v_lshl_add_u64 v[6:7], v[6:7], 0, v[180:181]
	v_lshl_add_u64 v[8:9], v[8:9], 0, v[180:181]
	v_lshlrev_b64 v[4:5], 1, v[6:7]
	v_lshlrev_b64 v[6:7], 1, v[8:9]
	v_or_b32_e32 v2, 0x100, v2
	v_lshl_add_u64 v[8:9], s[10:11], 0, v[4:5]
	v_lshl_add_u64 v[10:11], s[12:13], 0, v[4:5]
	v_or_b32_e32 v4, 0x100, v4
	v_lshl_add_u64 v[12:13], s[10:11], 0, v[6:7]
	v_lshl_add_u64 v[18:19], s[12:13], 0, v[6:7]
	v_or_b32_e32 v6, 0x100, v6
	v_lshl_add_u64 v[20:21], s[10:11], 0, v[2:3]
	v_lshl_add_u64 v[2:3], s[12:13], 0, v[2:3]
	global_load_dwordx4 v[214:217], v[8:9], off
	global_load_dwordx4 v[218:221], v[10:11], off
	v_lshl_add_u64 v[8:9], s[10:11], 0, v[4:5]
	v_lshl_add_u64 v[4:5], s[12:13], 0, v[4:5]
	global_load_dwordx4 v[14:17], v[12:13], off
	s_nop 0
	global_load_dwordx4 v[10:13], v[18:19], off
	v_lshl_add_u64 v[232:233], s[10:11], 0, v[6:7]
	v_lshl_add_u64 v[234:235], s[12:13], 0, v[6:7]
	global_load_dwordx4 v[222:225], v[20:21], off
	global_load_dwordx4 v[226:229], v[2:3], off
	global_load_dwordx4 v[22:25], v[8:9], off
	s_nop 0
	global_load_dwordx4 v[18:21], v[4:5], off
	global_load_dwordx4 v[6:9], v[232:233], off
	s_nop 0
	global_load_dwordx4 v[2:5], v[234:235], off
	s_and_b64 vcc, exec, s[8:9]
	s_mov_b32 s46, s16
	s_mov_b32 s26, s20
	s_mov_b64 s[28:29], s[24:25]
	s_mov_b64 s[30:31], s[22:23]
	s_waitcnt vmcnt(0)
	v_lshlrev_b32_e32 v232, 16, v30
	v_and_b32_e32 v233, 0xffff0000, v30
	v_lshlrev_b32_e32 v234, 16, v194
	v_and_b32_e32 v235, 0xffff0000, v194
	v_lshlrev_b32_e32 v30, 16, v31
	v_and_b32_e32 v31, 0xffff0000, v31
	v_lshlrev_b32_e32 v194, 16, v195
	v_and_b32_e32 v195, 0xffff0000, v195
	v_lshlrev_b32_e32 v236, 16, v32
	v_and_b32_e32 v237, 0xffff0000, v32
	v_lshlrev_b32_e32 v238, 16, v196
	v_and_b32_e32 v239, 0xffff0000, v196
	v_lshlrev_b32_e32 v32, 16, v33
	v_and_b32_e32 v33, 0xffff0000, v33
	v_lshlrev_b32_e32 v196, 16, v197
	v_and_b32_e32 v197, 0xffff0000, v197
	v_pk_fma_f32 v[158:159], v[158:159], v[232:233], v[234:235]
	v_pk_fma_f32 v[160:161], v[160:161], v[30:31], v[194:195]
	v_pk_fma_f32 v[154:155], v[154:155], v[236:237], v[238:239]
	v_pk_fma_f32 v[156:157], v[156:157], v[32:33], v[196:197]
	v_cvt_pk_bf16_f32 v30, v158, v159
	v_cvt_pk_bf16_f32 v31, v160, v161
	v_cvt_pk_bf16_f32 v32, v154, v155
	v_cvt_pk_bf16_f32 v33, v156, v157
	v_lshlrev_b32_e32 v194, 16, v198
	global_store_dwordx4 v[230:231], v[30:33], off
	v_and_b32_e32 v195, 0xffff0000, v198
	s_nop 0
	v_lshlrev_b32_e32 v30, 16, v202
	v_and_b32_e32 v31, 0xffff0000, v202
	v_pk_fma_f32 v[30:31], v[150:151], v[194:195], v[30:31]
	v_lshlrev_b32_e32 v32, 16, v199
	v_and_b32_e32 v33, 0xffff0000, v199
	v_lshlrev_b32_e32 v150, 16, v203
	v_and_b32_e32 v151, 0xffff0000, v203
	v_pk_fma_f32 v[32:33], v[152:153], v[32:33], v[150:151]
	v_cvt_pk_bf16_f32 v30, v30, v31
	v_cvt_pk_bf16_f32 v31, v32, v33
	v_lshlrev_b32_e32 v32, 16, v200
	v_and_b32_e32 v33, 0xffff0000, v200
	v_lshlrev_b32_e32 v150, 16, v204
	v_and_b32_e32 v151, 0xffff0000, v204
	v_pk_fma_f32 v[32:33], v[142:143], v[32:33], v[150:151]
	v_lshlrev_b32_e32 v142, 16, v201
	v_and_b32_e32 v143, 0xffff0000, v201
	v_lshlrev_b32_e32 v150, 16, v205
	v_and_b32_e32 v151, 0xffff0000, v205
	v_pk_fma_f32 v[142:143], v[144:145], v[142:143], v[150:151]
	v_cvt_pk_bf16_f32 v32, v32, v33
	v_cvt_pk_bf16_f32 v33, v142, v143
	global_store_dwordx4 v[230:231], v[30:33], off offset:256
	v_lshlrev_b32_e32 v144, 16, v211
	v_and_b32_e32 v145, 0xffff0000, v211
	v_lshlrev_b32_e32 v30, 16, v206
	v_and_b32_e32 v31, 0xffff0000, v206
	v_lshlrev_b32_e32 v32, 16, v210
	v_and_b32_e32 v33, 0xffff0000, v210
	v_pk_fma_f32 v[30:31], v[146:147], v[30:31], v[32:33]
	v_lshlrev_b32_e32 v32, 16, v207
	v_and_b32_e32 v33, 0xffff0000, v207
	v_pk_fma_f32 v[32:33], v[148:149], v[32:33], v[144:145]
	v_cvt_pk_bf16_f32 v30, v30, v31
	v_cvt_pk_bf16_f32 v31, v32, v33
	v_lshlrev_b32_e32 v32, 16, v208
	v_and_b32_e32 v33, 0xffff0000, v208
	v_lshlrev_b32_e32 v144, 16, v212
	v_and_b32_e32 v145, 0xffff0000, v212
	v_pk_fma_f32 v[32:33], v[138:139], v[32:33], v[144:145]
	v_lshlrev_b32_e32 v138, 16, v209
	v_and_b32_e32 v139, 0xffff0000, v209
; #define PG8_GAS __attribute__((address_space(1)))
; __device__ __forceinline__ unsigned cvt_pk_bf16(float lo, float hi) { const f32x2c v = {lo, hi}; return __builtin_bit_cast(unsigned, __builtin_convertvector(v, bf16x2c)); }
; __device__ __forceinline__ float bf_lo(unsigned w) { return __uint_as_float(w << 16); }
; __device__ __forceinline__ float bf_hi(unsigned w) { return __uint_as_float(w & 0xffff0000u); }
;     __device__ __forceinline__ void operator()(const f32x4 (&acc)[2][2][4][2], const Unit& un, int wr, int wc, int fr, int fq) const {
;     ...
;             for (int m = 0; m < 4; ++m)
; #pragma unroll
;                 for (int bj = 0; bj < 2; ++bj) { const u32x4 g = gg[m][bj], p = pp[m][bj]; const f32x4 v0 = acc[ai][bj][m][0], v1 = acc[ai][bj][m][1];
;                     u32x4 w; w.x = cvt_pk_bf16(v0[0] * bf_lo(g.x) + bf_lo(p.x), v0[1] * bf_hi(g.x) + bf_hi(p.x)); w.y = cvt_pk_bf16(v0[2] * bf_lo(g.y) + bf_lo(p.y), v0[3] * bf_hi(g.y) + bf_hi(p.y));
;                     w.z = cvt_pk_bf16(v1[0] * bf_lo(g.z) + bf_lo(p.z), v1[1] * bf_hi(g.z) + bf_hi(p.z)); w.w = cvt_pk_bf16(v1[2] * bf_lo(g.w) + bf_lo(p.w), v1[3] * bf_hi(g.w) + bf_hi(p.w));
;                     *(PG8_GAS u32x4*)(sa + (size_t)(row0 + ai * HALF + m * 16) * 4096 + col0 + bj * HALF) = w; }
	v_lshlrev_b32_e32 v144, 16, v213
	v_and_b32_e32 v145, 0xffff0000, v213
	v_lshlrev_b64 v[142:143], 13, v[184:185]
	v_pk_fma_f32 v[138:139], v[140:141], v[138:139], v[144:145]
	v_cvt_pk_bf16_f32 v32, v32, v33
	v_cvt_pk_bf16_f32 v33, v138, v139
	v_lshl_add_u64 v[138:139], s[10:11], 0, v[142:143]
	v_lshl_add_u64 v[138:139], v[138:139], 0, v[178:179]
	global_store_dwordx4 v[138:139], v[30:33], off
	s_nop 1
	v_lshlrev_b32_e32 v30, 16, v222
	v_and_b32_e32 v31, 0xffff0000, v222
	v_lshlrev_b32_e32 v32, 16, v226
	v_and_b32_e32 v33, 0xffff0000, v226
	v_pk_fma_f32 v[30:31], v[134:135], v[30:31], v[32:33]
	v_lshlrev_b32_e32 v32, 16, v223
	v_and_b32_e32 v33, 0xffff0000, v223
	v_lshlrev_b32_e32 v134, 16, v227
	v_and_b32_e32 v135, 0xffff0000, v227
	v_pk_fma_f32 v[32:33], v[136:137], v[32:33], v[134:135]
	v_cvt_pk_bf16_f32 v30, v30, v31
	v_cvt_pk_bf16_f32 v31, v32, v33
	v_lshlrev_b32_e32 v32, 16, v224
	v_and_b32_e32 v33, 0xffff0000, v224
	v_lshlrev_b32_e32 v134, 16, v228
	v_and_b32_e32 v135, 0xffff0000, v228
	v_pk_fma_f32 v[32:33], v[126:127], v[32:33], v[134:135]
	v_lshlrev_b32_e32 v126, 16, v225
	v_and_b32_e32 v127, 0xffff0000, v225
	v_lshlrev_b32_e32 v134, 16, v229
	v_and_b32_e32 v135, 0xffff0000, v229
	v_pk_fma_f32 v[126:127], v[128:129], v[126:127], v[134:135]
	v_cvt_pk_bf16_f32 v32, v32, v33
	v_cvt_pk_bf16_f32 v33, v126, v127
	global_store_dwordx4 v[138:139], v[30:33], off offset:256
	v_lshlrev_b32_e32 v126, 16, v219
	v_and_b32_e32 v127, 0xffff0000, v219
	v_lshlrev_b64 v[32:33], 13, v[28:29]
	v_lshlrev_b32_e32 v28, 16, v214
	v_and_b32_e32 v29, 0xffff0000, v214
	v_lshlrev_b32_e32 v30, 16, v218
	v_and_b32_e32 v31, 0xffff0000, v218
	v_pk_fma_f32 v[28:29], v[130:131], v[28:29], v[30:31]
	v_lshlrev_b32_e32 v30, 16, v215
	v_and_b32_e32 v31, 0xffff0000, v215
	v_pk_fma_f32 v[30:31], v[132:133], v[30:31], v[126:127]
	v_cvt_pk_bf16_f32 v28, v28, v29
	v_cvt_pk_bf16_f32 v29, v30, v31
	v_lshlrev_b32_e32 v30, 16, v216
	v_and_b32_e32 v31, 0xffff0000, v216
	v_lshlrev_b32_e32 v126, 16, v220
	v_and_b32_e32 v127, 0xffff0000, v220
	v_pk_fma_f32 v[30:31], v[122:123], v[30:31], v[126:127]
	v_lshlrev_b32_e32 v122, 16, v217
	v_and_b32_e32 v123, 0xffff0000, v217
	v_lshlrev_b32_e32 v126, 16, v221
	v_and_b32_e32 v127, 0xffff0000, v221
	v_pk_fma_f32 v[122:123], v[124:125], v[122:123], v[126:127]
	v_lshl_add_u64 v[32:33], s[10:11], 0, v[32:33]
	v_cvt_pk_bf16_f32 v30, v30, v31
	v_cvt_pk_bf16_f32 v31, v122, v123
	v_lshl_add_u64 v[32:33], v[32:33], 0, v[178:179]
	global_store_dwordx4 v[32:33], v[28:31], off
	v_add_u32_e32 v132, 0x80, v182
	v_ashrrev_i32_e32 v133, 31, v132
	v_lshlrev_b32_e32 v28, 16, v22
	v_and_b32_e32 v29, 0xffff0000, v22
	v_lshlrev_b32_e32 v30, 16, v18
	v_and_b32_e32 v31, 0xffff0000, v18
	v_pk_fma_f32 v[28:29], v[118:119], v[28:29], v[30:31]
	v_lshlrev_b32_e32 v22, 16, v23
	v_cvt_pk_bf16_f32 v18, v28, v29
	v_and_b32_e32 v23, 0xffff0000, v23
	v_lshlrev_b32_e32 v28, 16, v19
	v_and_b32_e32 v29, 0xffff0000, v19
	v_pk_fma_f32 v[22:23], v[120:121], v[22:23], v[28:29]
	v_lshlrev_b32_e32 v28, 16, v20
	v_cvt_pk_bf16_f32 v19, v22, v23
	v_lshlrev_b32_e32 v22, 16, v24
	v_and_b32_e32 v23, 0xffff0000, v24
	v_and_b32_e32 v29, 0xffff0000, v20
	v_pk_fma_f32 v[22:23], v[110:111], v[22:23], v[28:29]
	v_lshlrev_b32_e32 v24, 16, v21
	v_cvt_pk_bf16_f32 v20, v22, v23
	v_lshlrev_b32_e32 v22, 16, v25
	v_and_b32_e32 v23, 0xffff0000, v25
	v_and_b32_e32 v25, 0xffff0000, v21
	v_pk_fma_f32 v[22:23], v[112:113], v[22:23], v[24:25]
	v_add_u32_e32 v134, 0x90, v182
	v_cvt_pk_bf16_f32 v21, v22, v23
	global_store_dwordx4 v[32:33], v[18:21], off offset:256
	v_lshlrev_b32_e32 v22, 16, v10
	v_and_b32_e32 v23, 0xffff0000, v10
	v_lshlrev_b32_e32 v20, 16, v14
	v_and_b32_e32 v21, 0xffff0000, v14
	v_pk_fma_f32 v[20:21], v[114:115], v[20:21], v[22:23]
	v_lshlrev_b32_e32 v14, 16, v15
	v_cvt_pk_bf16_f32 v10, v20, v21
	v_and_b32_e32 v15, 0xffff0000, v15
	v_lshlrev_b32_e32 v20, 16, v11
	v_and_b32_e32 v21, 0xffff0000, v11
	v_pk_fma_f32 v[14:15], v[116:117], v[14:15], v[20:21]
	v_lshlrev_b32_e32 v20, 16, v12
	v_cvt_pk_bf16_f32 v11, v14, v15
	v_lshlrev_b32_e32 v14, 16, v16
	v_and_b32_e32 v15, 0xffff0000, v16
	v_and_b32_e32 v21, 0xffff0000, v12
	v_pk_fma_f32 v[14:15], v[106:107], v[14:15], v[20:21]
	v_lshlrev_b32_e32 v16, 16, v13
	v_cvt_pk_bf16_f32 v12, v14, v15
	v_lshlrev_b32_e32 v14, 16, v17
	v_and_b32_e32 v15, 0xffff0000, v17
	v_and_b32_e32 v17, 0xffff0000, v13
	v_lshlrev_b64 v[18:19], 13, v[26:27]
	v_pk_fma_f32 v[14:15], v[108:109], v[14:15], v[16:17]
	v_ashrrev_i32_e32 v135, 31, v134
	v_cvt_pk_bf16_f32 v13, v14, v15
	v_lshl_add_u64 v[14:15], s[10:11], 0, v[18:19]
	v_lshl_add_u64 v[14:15], v[14:15], 0, v[178:179]
	global_store_dwordx4 v[14:15], v[10:13], off
	v_add_u32_e32 v136, 0xa0, v182
	v_ashrrev_i32_e32 v137, 31, v136
	v_lshlrev_b32_e32 v10, 16, v6
	v_and_b32_e32 v11, 0xffff0000, v6
	v_lshlrev_b32_e32 v12, 16, v2
	v_and_b32_e32 v13, 0xffff0000, v2
	v_pk_fma_f32 v[10:11], v[102:103], v[10:11], v[12:13]
	v_lshlrev_b32_e32 v6, 16, v7
	v_cvt_pk_bf16_f32 v2, v10, v11
	v_and_b32_e32 v7, 0xffff0000, v7
	v_lshlrev_b32_e32 v10, 16, v3
	v_and_b32_e32 v11, 0xffff0000, v3
	v_pk_fma_f32 v[6:7], v[104:105], v[6:7], v[10:11]
	v_lshlrev_b32_e32 v10, 16, v4
	v_cvt_pk_bf16_f32 v3, v6, v7
	v_lshlrev_b32_e32 v6, 16, v8
	v_and_b32_e32 v7, 0xffff0000, v8
	v_and_b32_e32 v11, 0xffff0000, v4
	v_pk_fma_f32 v[6:7], v[98:99], v[6:7], v[10:11]
	v_lshlrev_b32_e32 v8, 16, v5
	v_cvt_pk_bf16_f32 v4, v6, v7
	v_lshlrev_b32_e32 v6, 16, v9
	v_and_b32_e32 v7, 0xffff0000, v9
	v_and_b32_e32 v9, 0xffff0000, v5
	v_pk_fma_f32 v[6:7], v[100:101], v[6:7], v[8:9]
	v_add_u32_e32 v98, 0xb0, v182
	v_cvt_pk_bf16_f32 v5, v6, v7
; #define PG8_GAS __attribute__((address_space(1)))
; __device__ __forceinline__ unsigned cvt_pk_bf16(float lo, float hi) { const f32x2c v = {lo, hi}; return __builtin_bit_cast(unsigned, __builtin_convertvector(v, bf16x2c)); }
; __device__ __forceinline__ float bf_lo(unsigned w) { return __uint_as_float(w << 16); }
; __device__ __forceinline__ float bf_hi(unsigned w) { return __uint_as_float(w & 0xffff0000u); }
;     __device__ __forceinline__ void operator()(const f32x4 (&acc)[2][2][4][2], const Unit& un, int wr, int wc, int fr, int fq) const {
;     ...
;         for (int ai = 0; ai < 2; ++ai) {
;             u32x4 gg[4][2], pp[4][2];
; #pragma unroll
;             for (int m = 0; m < 4; ++m)
; #pragma unroll
;                 for (int bj = 0; bj < 2; ++bj) { const size_t off = (size_t)(row0 + ai * HALF + m * 16) * 4096 + col0 + bj * HALF; gg[m][bj] = *(const PG8_GAS u32x4*)(sa + off); pp[m][bj] = *(const PG8_GAS u32x4*)(P + off); }
;             asm volatile("" ::: "memory");
; #pragma unroll
;             for (int m = 0; m < 4; ++m)
; #pragma unroll
;                 for (int bj = 0; bj < 2; ++bj) { const u32x4 g = gg[m][bj], p = pp[m][bj]; const f32x4 v0 = acc[ai][bj][m][0], v1 = acc[ai][bj][m][1];
;                     u32x4 w; w.x = cvt_pk_bf16(v0[0] * bf_lo(g.x) + bf_lo(p.x), v0[1] * bf_hi(g.x) + bf_hi(p.x)); w.y = cvt_pk_bf16(v0[2] * bf_lo(g.y) + bf_lo(p.y), v0[3] * bf_hi(g.y) + bf_hi(p.y));
;                     w.z = cvt_pk_bf16(v1[0] * bf_lo(g.z) + bf_lo(p.z), v1[1] * bf_hi(g.z) + bf_hi(p.z)); w.w = cvt_pk_bf16(v1[2] * bf_lo(g.w) + bf_lo(p.w), v1[3] * bf_hi(g.w) + bf_hi(p.w));
;                     *(PG8_GAS u32x4*)(sa + (size_t)(row0 + ai * HALF + m * 16) * 4096 + col0 + bj * HALF) = w; }
	global_store_dwordx4 v[14:15], v[2:5], off offset:256
	v_ashrrev_i32_e32 v99, 31, v98
	s_nop 0
	v_lshlrev_b64 v[2:3], 12, v[132:133]
	v_lshl_add_u64 v[2:3], v[2:3], 0, v[180:181]
	v_lshlrev_b64 v[2:3], 1, v[2:3]
	v_lshl_add_u64 v[4:5], s[10:11], 0, v[2:3]
	global_load_dwordx4 v[100:103], v[4:5], off
	v_lshl_add_u64 v[4:5], s[12:13], 0, v[2:3]
	global_load_dwordx4 v[104:107], v[4:5], off
	v_or_b32_e32 v2, 0x100, v2
	v_lshl_add_u64 v[4:5], s[10:11], 0, v[2:3]
	v_lshl_add_u64 v[2:3], s[12:13], 0, v[2:3]
	global_load_dwordx4 v[108:111], v[4:5], off
	global_load_dwordx4 v[112:115], v[2:3], off
	v_lshlrev_b64 v[2:3], 12, v[134:135]
	v_lshl_add_u64 v[2:3], v[2:3], 0, v[180:181]
	v_lshlrev_b64 v[2:3], 1, v[2:3]
	v_lshl_add_u64 v[4:5], s[10:11], 0, v[2:3]
	v_lshl_add_u64 v[6:7], s[12:13], 0, v[2:3]
	global_load_dwordx4 v[116:119], v[4:5], off
	global_load_dwordx4 v[120:123], v[6:7], off
	v_or_b32_e32 v2, 0x100, v2
	v_lshl_add_u64 v[4:5], s[10:11], 0, v[2:3]
	v_lshl_add_u64 v[2:3], s[12:13], 0, v[2:3]
	global_load_dwordx4 v[124:127], v[4:5], off
	global_load_dwordx4 v[128:131], v[2:3], off
	v_lshlrev_b64 v[2:3], 12, v[136:137]
	v_lshl_add_u64 v[2:3], v[2:3], 0, v[180:181]
	v_lshlrev_b64 v[2:3], 1, v[2:3]
	v_lshl_add_u64 v[4:5], s[10:11], 0, v[2:3]
	v_lshl_add_u64 v[6:7], s[12:13], 0, v[2:3]
	global_load_dwordx4 v[30:33], v[4:5], off
	global_load_dwordx4 v[26:29], v[6:7], off
	v_or_b32_e32 v2, 0x100, v2
	v_lshl_add_u64 v[4:5], s[10:11], 0, v[2:3]
	v_lshl_add_u64 v[2:3], s[12:13], 0, v[2:3]
	global_load_dwordx4 v[22:25], v[4:5], off
	global_load_dwordx4 v[18:21], v[2:3], off
	v_lshlrev_b64 v[2:3], 12, v[98:99]
	v_lshl_add_u64 v[2:3], v[2:3], 0, v[180:181]
	v_lshlrev_b64 v[2:3], 1, v[2:3]
	v_lshl_add_u64 v[4:5], s[10:11], 0, v[2:3]
	v_lshl_add_u64 v[6:7], s[12:13], 0, v[2:3]
	global_load_dwordx4 v[14:17], v[4:5], off
	global_load_dwordx4 v[10:13], v[6:7], off
	v_or_b32_e32 v2, 0x100, v2
	v_lshl_add_u64 v[4:5], s[10:11], 0, v[2:3]
	v_lshl_add_u64 v[2:3], s[12:13], 0, v[2:3]
	global_load_dwordx4 v[6:9], v[4:5], off
	s_nop 0
	global_load_dwordx4 v[2:5], v[2:3], off
	v_lshlrev_b64 v[132:133], 13, v[132:133]
	s_waitcnt vmcnt(15)
	v_lshlrev_b32_e32 v138, 16, v100
	v_and_b32_e32 v139, 0xffff0000, v100
	s_waitcnt vmcnt(14)
	v_lshlrev_b32_e32 v140, 16, v104
	v_and_b32_e32 v141, 0xffff0000, v104
	v_lshlrev_b32_e32 v100, 16, v101
	v_and_b32_e32 v101, 0xffff0000, v101
	v_lshlrev_b32_e32 v104, 16, v105
	v_and_b32_e32 v105, 0xffff0000, v105
	v_pk_fma_f32 v[94:95], v[94:95], v[138:139], v[140:141]
	v_pk_fma_f32 v[96:97], v[96:97], v[100:101], v[104:105]
	v_cvt_pk_bf16_f32 v94, v94, v95
	v_cvt_pk_bf16_f32 v95, v96, v97
	v_lshlrev_b32_e32 v96, 16, v102
	v_and_b32_e32 v97, 0xffff0000, v102
	v_lshlrev_b32_e32 v100, 16, v106
	v_and_b32_e32 v101, 0xffff0000, v106
	v_pk_fma_f32 v[90:91], v[90:91], v[96:97], v[100:101]
	v_lshlrev_b32_e32 v100, 16, v107
	v_cvt_pk_bf16_f32 v96, v90, v91
	v_lshlrev_b32_e32 v90, 16, v103
	v_and_b32_e32 v91, 0xffff0000, v103
	v_and_b32_e32 v101, 0xffff0000, v107
	v_pk_fma_f32 v[90:91], v[92:93], v[90:91], v[100:101]
	s_waitcnt vmcnt(13)
	v_lshlrev_b32_e32 v92, 16, v108
	v_cvt_pk_bf16_f32 v97, v90, v91
	v_lshl_add_u64 v[90:91], s[10:11], 0, v[132:133]
	v_lshl_add_u64 v[90:91], v[90:91], 0, v[178:179]
	global_store_dwordx4 v[90:91], v[94:97], off
	v_and_b32_e32 v93, 0xffff0000, v108
	s_waitcnt vmcnt(13)
	v_lshlrev_b32_e32 v94, 16, v112
	v_and_b32_e32 v95, 0xffff0000, v112
	v_pk_fma_f32 v[86:87], v[86:87], v[92:93], v[94:95]
	v_lshlrev_b32_e32 v92, 16, v109
	v_and_b32_e32 v93, 0xffff0000, v109
	v_lshlrev_b32_e32 v94, 16, v113
	v_and_b32_e32 v95, 0xffff0000, v113
	v_pk_fma_f32 v[88:89], v[88:89], v[92:93], v[94:95]
	v_cvt_pk_bf16_f32 v86, v86, v87
	v_cvt_pk_bf16_f32 v87, v88, v89
	v_lshlrev_b32_e32 v88, 16, v110
	v_and_b32_e32 v89, 0xffff0000, v110
	v_lshlrev_b32_e32 v92, 16, v114
	v_and_b32_e32 v93, 0xffff0000, v114
	v_pk_fma_f32 v[78:79], v[78:79], v[88:89], v[92:93]
	v_lshlrev_b32_e32 v92, 16, v115
	v_cvt_pk_bf16_f32 v88, v78, v79
	v_lshlrev_b32_e32 v78, 16, v111
	v_and_b32_e32 v79, 0xffff0000, v111
	v_and_b32_e32 v93, 0xffff0000, v115
	v_pk_fma_f32 v[78:79], v[80:81], v[78:79], v[92:93]
	s_waitcnt vmcnt(11)
	v_lshlrev_b32_e32 v80, 16, v120
	v_cvt_pk_bf16_f32 v89, v78, v79
	v_lshlrev_b32_e32 v78, 16, v116
	v_and_b32_e32 v79, 0xffff0000, v116
	v_and_b32_e32 v81, 0xffff0000, v120
	v_pk_fma_f32 v[78:79], v[82:83], v[78:79], v[80:81]
	v_lshlrev_b32_e32 v80, 16, v117
	v_and_b32_e32 v81, 0xffff0000, v117
	v_lshlrev_b32_e32 v82, 16, v121
	v_and_b32_e32 v83, 0xffff0000, v121
	v_pk_fma_f32 v[80:81], v[84:85], v[80:81], v[82:83]
	v_cvt_pk_bf16_f32 v78, v78, v79
	v_cvt_pk_bf16_f32 v79, v80, v81
	v_lshlrev_b32_e32 v80, 16, v118
	v_and_b32_e32 v81, 0xffff0000, v118
	v_lshlrev_b32_e32 v82, 16, v122
	v_and_b32_e32 v83, 0xffff0000, v122
	v_pk_fma_f32 v[74:75], v[74:75], v[80:81], v[82:83]
	v_lshlrev_b32_e32 v82, 16, v123
	v_cvt_pk_bf16_f32 v80, v74, v75
	v_lshlrev_b32_e32 v74, 16, v119
	v_and_b32_e32 v75, 0xffff0000, v119
	v_and_b32_e32 v83, 0xffff0000, v123
	global_store_dwordx4 v[90:91], v[86:89], off offset:256
	v_pk_fma_f32 v[74:75], v[76:77], v[74:75], v[82:83]
	s_waitcnt vmcnt(11)
	v_lshlrev_b32_e32 v76, 16, v124
	v_lshlrev_b64 v[86:87], 13, v[134:135]
	v_cvt_pk_bf16_f32 v81, v74, v75
	v_lshl_add_u64 v[74:75], s[10:11], 0, v[86:87]
	v_lshl_add_u64 v[74:75], v[74:75], 0, v[178:179]
	global_store_dwordx4 v[74:75], v[78:81], off
	v_and_b32_e32 v77, 0xffff0000, v124
	s_waitcnt vmcnt(11)
; #define PG8_GAS __attribute__((address_space(1)))
; __device__ __forceinline__ unsigned cvt_pk_bf16(float lo, float hi) { const f32x2c v = {lo, hi}; return __builtin_bit_cast(unsigned, __builtin_convertvector(v, bf16x2c)); }
; __device__ __forceinline__ float bf_lo(unsigned w) { return __uint_as_float(w << 16); }
; __device__ __forceinline__ float bf_hi(unsigned w) { return __uint_as_float(w & 0xffff0000u); }
;     __device__ __forceinline__ void operator()(const f32x4 (&acc)[2][2][4][2], const Unit& un, int wr, int wc, int fr, int fq) const {
;     ...
;             for (int m = 0; m < 4; ++m)
; #pragma unroll
;                 for (int bj = 0; bj < 2; ++bj) { const u32x4 g = gg[m][bj], p = pp[m][bj]; const f32x4 v0 = acc[ai][bj][m][0], v1 = acc[ai][bj][m][1];
;                     u32x4 w; w.x = cvt_pk_bf16(v0[0] * bf_lo(g.x) + bf_lo(p.x), v0[1] * bf_hi(g.x) + bf_hi(p.x)); w.y = cvt_pk_bf16(v0[2] * bf_lo(g.y) + bf_lo(p.y), v0[3] * bf_hi(g.y) + bf_hi(p.y));
;                     w.z = cvt_pk_bf16(v1[0] * bf_lo(g.z) + bf_lo(p.z), v1[1] * bf_hi(g.z) + bf_hi(p.z)); w.w = cvt_pk_bf16(v1[2] * bf_lo(g.w) + bf_lo(p.w), v1[3] * bf_hi(g.w) + bf_hi(p.w));
;                     *(PG8_GAS u32x4*)(sa + (size_t)(row0 + ai * HALF + m * 16) * 4096 + col0 + bj * HALF) = w; }
; template <class Epi, class Sched, bool ALIGN_EPI = false, bool SP2 = false, bool F8 = false>
; __device__ __forceinline__ void gemm_phase(PG8_LAS unsigned char* lds, const Gemm g, const Sched& S, const Epi& E) {
;     ...
;         if (!has_next) break;
	v_lshlrev_b32_e32 v78, 16, v128
	v_and_b32_e32 v79, 0xffff0000, v128
	v_pk_fma_f32 v[70:71], v[70:71], v[76:77], v[78:79]
	v_lshlrev_b32_e32 v76, 16, v125
	v_and_b32_e32 v77, 0xffff0000, v125
	v_lshlrev_b32_e32 v78, 16, v129
	v_and_b32_e32 v79, 0xffff0000, v129
	v_pk_fma_f32 v[72:73], v[72:73], v[76:77], v[78:79]
	v_cvt_pk_bf16_f32 v70, v70, v71
	v_cvt_pk_bf16_f32 v71, v72, v73
	v_lshlrev_b32_e32 v72, 16, v126
	v_and_b32_e32 v73, 0xffff0000, v126
	v_lshlrev_b32_e32 v76, 16, v130
	v_and_b32_e32 v77, 0xffff0000, v130
	v_pk_fma_f32 v[62:63], v[62:63], v[72:73], v[76:77]
	v_lshlrev_b32_e32 v76, 16, v131
	v_cvt_pk_bf16_f32 v72, v62, v63
	v_lshlrev_b32_e32 v62, 16, v127
	v_and_b32_e32 v63, 0xffff0000, v127
	v_and_b32_e32 v77, 0xffff0000, v131
	v_pk_fma_f32 v[62:63], v[64:65], v[62:63], v[76:77]
	s_waitcnt vmcnt(10)
	v_lshlrev_b32_e32 v64, 16, v30
	v_cvt_pk_bf16_f32 v73, v62, v63
	global_store_dwordx4 v[74:75], v[70:73], off offset:256
	v_and_b32_e32 v65, 0xffff0000, v30
	v_lshlrev_b32_e32 v30, 16, v31
	s_waitcnt vmcnt(10)
	v_lshlrev_b32_e32 v70, 16, v26
	v_and_b32_e32 v71, 0xffff0000, v26
	v_pk_fma_f32 v[64:65], v[66:67], v[64:65], v[70:71]
	v_and_b32_e32 v31, 0xffff0000, v31
	v_cvt_pk_bf16_f32 v26, v64, v65
	v_lshlrev_b32_e32 v64, 16, v27
	v_and_b32_e32 v65, 0xffff0000, v27
	v_pk_fma_f32 v[30:31], v[68:69], v[30:31], v[64:65]
	v_lshlrev_b32_e32 v64, 16, v28
	v_cvt_pk_bf16_f32 v27, v30, v31
	v_lshlrev_b32_e32 v30, 16, v32
	v_and_b32_e32 v31, 0xffff0000, v32
	v_and_b32_e32 v65, 0xffff0000, v28
	v_pk_fma_f32 v[30:31], v[58:59], v[30:31], v[64:65]
	v_lshlrev_b32_e32 v32, 16, v29
	v_cvt_pk_bf16_f32 v28, v30, v31
	v_lshlrev_b32_e32 v30, 16, v33
	v_and_b32_e32 v31, 0xffff0000, v33
	v_and_b32_e32 v33, 0xffff0000, v29
	v_lshlrev_b64 v[62:63], 13, v[136:137]
	v_pk_fma_f32 v[30:31], v[60:61], v[30:31], v[32:33]
	s_nop 0
	v_cvt_pk_bf16_f32 v29, v30, v31
	v_lshl_add_u64 v[30:31], s[10:11], 0, v[62:63]
	v_lshl_add_u64 v[30:31], v[30:31], 0, v[178:179]
	global_store_dwordx4 v[30:31], v[26:29], off
	s_waitcnt vmcnt(10)
	s_nop 0
	v_lshlrev_b32_e32 v26, 16, v22
	v_and_b32_e32 v27, 0xffff0000, v22
	s_waitcnt vmcnt(9)
	v_lshlrev_b32_e32 v28, 16, v18
	v_and_b32_e32 v29, 0xffff0000, v18
	v_pk_fma_f32 v[26:27], v[54:55], v[26:27], v[28:29]
	v_lshlrev_b32_e32 v22, 16, v23
	v_cvt_pk_bf16_f32 v18, v26, v27
	v_and_b32_e32 v23, 0xffff0000, v23
	v_lshlrev_b32_e32 v26, 16, v19
	v_and_b32_e32 v27, 0xffff0000, v19
	v_pk_fma_f32 v[22:23], v[56:57], v[22:23], v[26:27]
	v_lshlrev_b32_e32 v26, 16, v20
	v_cvt_pk_bf16_f32 v19, v22, v23
	v_lshlrev_b32_e32 v22, 16, v24
	v_and_b32_e32 v23, 0xffff0000, v24
	v_and_b32_e32 v27, 0xffff0000, v20
	v_pk_fma_f32 v[22:23], v[46:47], v[22:23], v[26:27]
	v_lshlrev_b32_e32 v24, 16, v21
	v_cvt_pk_bf16_f32 v20, v22, v23
	v_lshlrev_b32_e32 v22, 16, v25
	v_and_b32_e32 v23, 0xffff0000, v25
	v_and_b32_e32 v25, 0xffff0000, v21
	v_pk_fma_f32 v[22:23], v[48:49], v[22:23], v[24:25]
	s_nop 0
	v_cvt_pk_bf16_f32 v21, v22, v23
	global_store_dwordx4 v[30:31], v[18:21], off offset:256
	s_waitcnt vmcnt(8)
	v_lshlrev_b32_e32 v22, 16, v10
	v_and_b32_e32 v23, 0xffff0000, v10
	v_lshlrev_b32_e32 v20, 16, v14
	v_and_b32_e32 v21, 0xffff0000, v14
	v_pk_fma_f32 v[20:21], v[50:51], v[20:21], v[22:23]
	v_lshlrev_b32_e32 v14, 16, v15
	v_cvt_pk_bf16_f32 v10, v20, v21
	v_and_b32_e32 v15, 0xffff0000, v15
	v_lshlrev_b32_e32 v20, 16, v11
	v_and_b32_e32 v21, 0xffff0000, v11
	v_pk_fma_f32 v[14:15], v[52:53], v[14:15], v[20:21]
	v_lshlrev_b32_e32 v20, 16, v12
	v_cvt_pk_bf16_f32 v11, v14, v15
	v_lshlrev_b32_e32 v14, 16, v16
	v_and_b32_e32 v15, 0xffff0000, v16
	v_and_b32_e32 v21, 0xffff0000, v12
	v_pk_fma_f32 v[14:15], v[42:43], v[14:15], v[20:21]
	v_lshlrev_b32_e32 v16, 16, v13
	v_cvt_pk_bf16_f32 v12, v14, v15
	v_lshlrev_b32_e32 v14, 16, v17
	v_and_b32_e32 v15, 0xffff0000, v17
	v_and_b32_e32 v17, 0xffff0000, v13
	v_lshlrev_b64 v[18:19], 13, v[98:99]
	v_pk_fma_f32 v[14:15], v[44:45], v[14:15], v[16:17]
	s_nop 0
	v_cvt_pk_bf16_f32 v13, v14, v15
	v_lshl_add_u64 v[14:15], s[10:11], 0, v[18:19]
	v_lshl_add_u64 v[14:15], v[14:15], 0, v[178:179]
	global_store_dwordx4 v[14:15], v[10:13], off
	s_waitcnt vmcnt(8)
	s_nop 0
	v_lshlrev_b32_e32 v10, 16, v6
	v_and_b32_e32 v11, 0xffff0000, v6
	s_waitcnt vmcnt(7)
	v_lshlrev_b32_e32 v12, 16, v2
	v_and_b32_e32 v13, 0xffff0000, v2
	v_pk_fma_f32 v[10:11], v[38:39], v[10:11], v[12:13]
	v_lshlrev_b32_e32 v6, 16, v7
	v_cvt_pk_bf16_f32 v2, v10, v11
	v_and_b32_e32 v7, 0xffff0000, v7
	v_lshlrev_b32_e32 v10, 16, v3
	v_and_b32_e32 v11, 0xffff0000, v3
	v_pk_fma_f32 v[6:7], v[40:41], v[6:7], v[10:11]
	v_lshlrev_b32_e32 v10, 16, v4
	v_cvt_pk_bf16_f32 v3, v6, v7
	v_lshlrev_b32_e32 v6, 16, v8
	v_and_b32_e32 v7, 0xffff0000, v8
	v_and_b32_e32 v11, 0xffff0000, v4
	v_pk_fma_f32 v[6:7], v[34:35], v[6:7], v[10:11]
	v_lshlrev_b32_e32 v8, 16, v5
	v_cvt_pk_bf16_f32 v4, v6, v7
	v_lshlrev_b32_e32 v6, 16, v9
	v_and_b32_e32 v7, 0xffff0000, v9
	v_and_b32_e32 v9, 0xffff0000, v5
	v_pk_fma_f32 v[6:7], v[36:37], v[6:7], v[8:9]
	s_nop 0
	v_cvt_pk_bf16_f32 v5, v6, v7
	global_store_dwordx4 v[14:15], v[2:5], off offset:256
	s_cbranch_vccz .LBB0_627
	s_waitcnt vmcnt(0)
	s_cmpk_gt_u32 s4, 0xff
	s_cbranch_scc1 .LBB0_634
	s_barrier

; #define PG8_STAGE(bufoff, gbase, voff) do { _Pragma("unroll") for (int _i = 0; _i < 2; ++_i) \
;         __builtin_amdgcn_global_load_lds((const unsigned*)((const char*)(gbase) + (voff)[_i]), (PG8_LAS unsigned*)(lds + (bufoff) + ldsw + _i * 8192), 16, 0, 0); } while (0)
; #define PG8_LDA(dst, b, h) do { _Pragma("unroll") for (int m = 0; m < 4; ++m) _Pragma("unroll") for (int k = 0; k < 2; ++k) dst[m][k] = *(const PG8_LAS bf16x8*)(lds + PG8_SA(b, h) + aoff + m * 2048 + k * 1024); } while (0)
; #define PG8_LDB(dst, b, h) do { _Pragma("unroll") for (int n = 0; n < 2; ++n) _Pragma("unroll") for (int k = 0; k < 2; ++k) dst[n][k] = *(const PG8_LAS bf16x8*)(lds + PG8_SB(b, h) + boff + n * 2048 + k * 1024); } while (0)
; #define PG8_WAIT_V(n) asm volatile("s_waitcnt vmcnt(" #n ")" ::: "memory")
; #define PG8_WAIT_L(n) asm volatile("s_waitcnt lgkmcnt(" #n ")" ::: "memory")
; #define PG8_BAR __builtin_amdgcn_s_barrier()
; #define PG8_SCHED __builtin_amdgcn_sched_barrier(0)
; template <class Epi, class Sched, bool ALIGN_EPI = false, bool SP2 = false, bool F8 = false>
; __device__ __forceinline__ void gemm_phase(PG8_LAS unsigned char* lds, const Gemm g, const Sched& S, const Epi& E) {
;     ...
;         for (int t = 0; t < nt; t += 2) {
;             const bool last = (t == nt - 2);
;             const char* a1 = cA + (size_t)(t + 1) * kstep;
;             const char* a2 = last ? nA : cA + (size_t)(t + 2) * kstep; const char* b2 = last ? nB : cB + (size_t)(t + 2) * kstep;
;             const char* a3 = a2 + kstep; const char* b3 = b2 + kstep;
;             if (last && has_next) S.a_ready(nxt);
;             if constexpr (SP2) {
;             PG8_LDB(B0, 0, 0); PG8_LDB(B1, 0, 1); PG8_SCHED; PG8_LDA(At, 0, 0); PG8_STAGE(PG8_SA(1, 1), a1 + hA, voffA);
;             PG8_WAIT_V(8); PG8_WAIT_L(0); PG8_BAR; PG8_MMA(0, 0, At, B0); PG8_MMA(0, 1, At, B1); PG8_BAR; PG8_SCHED;
;             PG8_LDA(At, 0, 1); PG8_STAGE(PG8_SB(0, 0), b2, voffB); PG8_STAGE(PG8_SB(0, 1), b2 + hB, voffB); PG8_STAGE(PG8_SA(0, 0), a2, voffA);
.LBB0_689:
	ds_read_b128 v[130:133], v210
	ds_read_b128 v[134:137], v210 offset:1024
	ds_read_b128 v[138:141], v210 offset:2048
	ds_read_b128 v[142:145], v210 offset:3072
	ds_read_b128 v[146:149], v211
	ds_read_b128 v[150:153], v211 offset:1024
	ds_read_b128 v[154:157], v211 offset:2048
	ds_read_b128 v[158:161], v211 offset:3072
	s_add_u32 s38, s36, 0xfff00080
	s_addc_u32 s39, s37, -1
	s_cmp_eq_u32 s61, 60
	s_cselect_b32 s41, s17, s39
	s_cselect_b32 s40, s20, s38
	s_cselect_b32 s39, s25, s60
	s_cselect_b32 s38, s27, s35
	v_lshl_add_u64 v[218:219], s[36:37], 0, v[188:189]
	s_add_i32 m0, s33, 0xc000
	ds_read_b128 v[162:165], v212
	ds_read_b128 v[166:169], v212 offset:1024
	ds_read_b128 v[170:173], v212 offset:2048
	ds_read_b128 v[174:177], v212 offset:3072
	ds_read_b128 v[194:197], v212 offset:4096
	ds_read_b128 v[198:201], v212 offset:5120
	ds_read_b128 v[202:205], v212 offset:6144
	ds_read_b128 v[214:217], v212 offset:7168
	global_load_lds_dwordx4 v[218:219], off
	v_lshl_add_u64 v[218:219], s[36:37], 0, v[186:187]
	s_add_i32 m0, s33, 0xe000
	s_nop 0
	global_load_lds_dwordx4 v[218:219], off
	s_waitcnt vmcnt(8)
	s_waitcnt lgkmcnt(0)
	s_setprio 1
	s_barrier
	v_mfma_f32_16x16x32_bf16 v[126:129], v[130:133], v[162:165], v[126:129]
	v_mfma_f32_16x16x32_bf16 v[122:125], v[138:141], v[162:165], v[122:125]
	v_mfma_f32_16x16x32_bf16 v[110:113], v[130:133], v[170:173], v[110:113]
	v_mfma_f32_16x16x32_bf16 v[106:109], v[138:141], v[170:173], v[106:109]
	v_mfma_f32_16x16x32_bf16 v[94:97], v[130:133], v[194:197], v[94:97]
	v_mfma_f32_16x16x32_bf16 v[90:93], v[138:141], v[194:197], v[90:93]
	v_mfma_f32_16x16x32_bf16 v[78:81], v[130:133], v[202:205], v[78:81]
	v_mfma_f32_16x16x32_bf16 v[74:77], v[138:141], v[202:205], v[74:77]
	v_mfma_f32_16x16x32_bf16 v[126:129], v[134:137], v[166:169], v[126:129]
	v_mfma_f32_16x16x32_bf16 v[122:125], v[142:145], v[166:169], v[122:125]
	v_mfma_f32_16x16x32_bf16 v[110:113], v[134:137], v[174:177], v[110:113]
	v_mfma_f32_16x16x32_bf16 v[106:109], v[142:145], v[174:177], v[106:109]
	v_mfma_f32_16x16x32_bf16 v[94:97], v[134:137], v[198:201], v[94:97]
	v_mfma_f32_16x16x32_bf16 v[90:93], v[142:145], v[198:201], v[90:93]
	v_mfma_f32_16x16x32_bf16 v[78:81], v[134:137], v[214:217], v[78:81]
	v_mfma_f32_16x16x32_bf16 v[74:77], v[142:145], v[214:217], v[74:77]
	v_mfma_f32_16x16x32_bf16 v[118:121], v[146:149], v[162:165], v[118:121]
	v_mfma_f32_16x16x32_bf16 v[114:117], v[154:157], v[162:165], v[114:117]
	v_mfma_f32_16x16x32_bf16 v[102:105], v[146:149], v[170:173], v[102:105]
	v_mfma_f32_16x16x32_bf16 v[98:101], v[154:157], v[170:173], v[98:101]
	v_mfma_f32_16x16x32_bf16 v[86:89], v[146:149], v[194:197], v[86:89]
	v_mfma_f32_16x16x32_bf16 v[82:85], v[154:157], v[194:197], v[82:85]
	v_mfma_f32_16x16x32_bf16 v[70:73], v[146:149], v[202:205], v[70:73]
	v_mfma_f32_16x16x32_bf16 v[66:69], v[154:157], v[202:205], v[66:69]
	v_mfma_f32_16x16x32_bf16 v[118:121], v[150:153], v[166:169], v[118:121]
	v_mfma_f32_16x16x32_bf16 v[114:117], v[158:161], v[166:169], v[114:117]
	v_mfma_f32_16x16x32_bf16 v[102:105], v[150:153], v[174:177], v[102:105]
	v_mfma_f32_16x16x32_bf16 v[98:101], v[158:161], v[174:177], v[98:101]
	v_mfma_f32_16x16x32_bf16 v[86:89], v[150:153], v[198:201], v[86:89]
	v_mfma_f32_16x16x32_bf16 v[82:85], v[158:161], v[198:201], v[82:85]
	v_mfma_f32_16x16x32_bf16 v[70:73], v[150:153], v[214:217], v[70:73]
	v_mfma_f32_16x16x32_bf16 v[66:69], v[158:161], v[214:217], v[66:69]
	s_barrier
	s_setprio 0
	s_add_i32 s62, s56, s19
	v_lshl_add_u64 v[218:219], s[38:39], 0, v[180:181]
	s_mov_b32 m0, s62
	ds_read_b128 v[162:165], v212 offset:16384
	ds_read_b128 v[166:169], v212 offset:17408
	ds_read_b128 v[170:173], v212 offset:18432
	ds_read_b128 v[174:177], v212 offset:19456
	ds_read_b128 v[194:197], v212 offset:20480
	ds_read_b128 v[198:201], v212 offset:21504
	ds_read_b128 v[202:205], v212 offset:22528
	ds_read_b128 v[214:217], v212 offset:23552
	global_load_lds_dwordx4 v[218:219], off
	s_add_i32 m0, s62, 0x2000
	s_add_u32 s62, s38, 0x100000
	v_lshl_add_u64 v[220:221], s[38:39], 0, v[184:185]
	s_addc_u32 s63, s39, 0
	s_add_i32 s64, s57, s19
	global_load_lds_dwordx4 v[220:221], off
	v_lshl_add_u64 v[222:223], s[62:63], 0, v[180:181]
	s_mov_b32 m0, s64
	v_lshl_add_u64 v[224:225], s[40:41], 0, v[182:183]
	global_load_lds_dwordx4 v[222:223], off
	v_lshl_add_u64 v[222:223], s[62:63], 0, v[184:185]
	s_add_i32 m0, s64, 0x2000
	s_nop 0
	global_load_lds_dwordx4 v[222:223], off
	v_lshl_add_u64 v[222:223], s[40:41], 0, v[178:179]
	s_mov_b32 m0, s33
	s_nop 0
	global_load_lds_dwordx4 v[222:223], off
	s_mov_b32 m0, s42
	s_nop 0
	global_load_lds_dwordx4 v[224:225], off
	s_waitcnt vmcnt(8)
	s_waitcnt lgkmcnt(0)
	s_setprio 1
	s_barrier
; #define PG8_STAGE(bufoff, gbase, voff) do { _Pragma("unroll") for (int _i = 0; _i < 2; ++_i) \
;         __builtin_amdgcn_global_load_lds((const unsigned*)((const char*)(gbase) + (voff)[_i]), (PG8_LAS unsigned*)(lds + (bufoff) + ldsw + _i * 8192), 16, 0, 0); } while (0)
; #define PG8_LDA(dst, b, h) do { _Pragma("unroll") for (int m = 0; m < 4; ++m) _Pragma("unroll") for (int k = 0; k < 2; ++k) dst[m][k] = *(const PG8_LAS bf16x8*)(lds + PG8_SA(b, h) + aoff + m * 2048 + k * 1024); } while (0)
; #define PG8_LDB(dst, b, h) do { _Pragma("unroll") for (int n = 0; n < 2; ++n) _Pragma("unroll") for (int k = 0; k < 2; ++k) dst[n][k] = *(const PG8_LAS bf16x8*)(lds + PG8_SB(b, h) + boff + n * 2048 + k * 1024); } while (0)
; #define PG8_WAIT_V(n) asm volatile("s_waitcnt vmcnt(" #n ")" ::: "memory")
; #define PG8_WAIT_L(n) asm volatile("s_waitcnt lgkmcnt(" #n ")" ::: "memory")
; #define PG8_BAR __builtin_amdgcn_s_barrier()
; #define PG8_SCHED __builtin_amdgcn_sched_barrier(0)
; template <class Epi, class Sched, bool ALIGN_EPI = false, bool SP2 = false, bool F8 = false>
; __device__ __forceinline__ void gemm_phase(PG8_LAS unsigned char* lds, const Gemm g, const Sched& S, const Epi& E) {
;     ...
;             PG8_LDA(At, 0, 1); PG8_STAGE(PG8_SB(0, 0), b2, voffB); PG8_STAGE(PG8_SB(0, 1), b2 + hB, voffB); PG8_STAGE(PG8_SA(0, 0), a2, voffA);
;             PG8_WAIT_V(8); PG8_WAIT_L(0); PG8_BAR; PG8_MMA(1, 0, At, B0); PG8_MMA(1, 1, At, B1); PG8_BAR; PG8_SCHED;
;             PG8_LDB(B0, 1, 0); PG8_LDB(B1, 1, 1); PG8_SCHED; PG8_LDA(At, 1, 0); PG8_STAGE(PG8_SA(0, 1), a2 + hA, voffA);
;             PG8_WAIT_V(8); PG8_WAIT_L(0); PG8_BAR; PG8_MMA(0, 0, At, B0); PG8_MMA(0, 1, At, B1); PG8_BAR; PG8_SCHED;
;             PG8_LDA(At, 1, 1); PG8_STAGE(PG8_SB(1, 0), b3, voffB); PG8_STAGE(PG8_SB(1, 1), b3 + hB, voffB); PG8_STAGE(PG8_SA(1, 0), a3, voffA);
	v_mfma_f32_16x16x32_bf16 v[62:65], v[130:133], v[162:165], v[62:65]
	v_mfma_f32_16x16x32_bf16 v[58:61], v[138:141], v[162:165], v[58:61]
	v_mfma_f32_16x16x32_bf16 v[46:49], v[130:133], v[170:173], v[46:49]
	v_mfma_f32_16x16x32_bf16 v[42:45], v[138:141], v[170:173], v[42:45]
	v_mfma_f32_16x16x32_bf16 v[30:33], v[130:133], v[194:197], v[30:33]
	v_mfma_f32_16x16x32_bf16 v[26:29], v[138:141], v[194:197], v[26:29]
	v_mfma_f32_16x16x32_bf16 v[14:17], v[130:133], v[202:205], v[14:17]
	v_mfma_f32_16x16x32_bf16 v[10:13], v[138:141], v[202:205], v[10:13]
	v_mfma_f32_16x16x32_bf16 v[62:65], v[134:137], v[166:169], v[62:65]
	v_mfma_f32_16x16x32_bf16 v[58:61], v[142:145], v[166:169], v[58:61]
	v_mfma_f32_16x16x32_bf16 v[46:49], v[134:137], v[174:177], v[46:49]
	v_mfma_f32_16x16x32_bf16 v[42:45], v[142:145], v[174:177], v[42:45]
	v_mfma_f32_16x16x32_bf16 v[30:33], v[134:137], v[198:201], v[30:33]
	v_mfma_f32_16x16x32_bf16 v[26:29], v[142:145], v[198:201], v[26:29]
	v_mfma_f32_16x16x32_bf16 v[14:17], v[134:137], v[214:217], v[14:17]
	v_mfma_f32_16x16x32_bf16 v[10:13], v[142:145], v[214:217], v[10:13]
	v_mfma_f32_16x16x32_bf16 v[54:57], v[146:149], v[162:165], v[54:57]
	v_mfma_f32_16x16x32_bf16 v[50:53], v[154:157], v[162:165], v[50:53]
	v_mfma_f32_16x16x32_bf16 v[38:41], v[146:149], v[170:173], v[38:41]
	v_mfma_f32_16x16x32_bf16 v[34:37], v[154:157], v[170:173], v[34:37]
	v_mfma_f32_16x16x32_bf16 v[22:25], v[146:149], v[194:197], v[22:25]
	v_mfma_f32_16x16x32_bf16 v[18:21], v[154:157], v[194:197], v[18:21]
	v_mfma_f32_16x16x32_bf16 v[6:9], v[146:149], v[202:205], v[6:9]
	v_mfma_f32_16x16x32_bf16 v[2:5], v[154:157], v[202:205], v[2:5]
	v_mfma_f32_16x16x32_bf16 v[54:57], v[150:153], v[166:169], v[54:57]
	v_mfma_f32_16x16x32_bf16 v[50:53], v[158:161], v[166:169], v[50:53]
	v_mfma_f32_16x16x32_bf16 v[38:41], v[150:153], v[174:177], v[38:41]
	v_mfma_f32_16x16x32_bf16 v[34:37], v[158:161], v[174:177], v[34:37]
	v_mfma_f32_16x16x32_bf16 v[22:25], v[150:153], v[198:201], v[22:25]
	v_mfma_f32_16x16x32_bf16 v[18:21], v[158:161], v[198:201], v[18:21]
	v_mfma_f32_16x16x32_bf16 v[6:9], v[150:153], v[214:217], v[6:9]
	v_mfma_f32_16x16x32_bf16 v[2:5], v[158:161], v[214:217], v[2:5]
	s_barrier
	s_setprio 0
	s_add_i32 s62, 0, 0x18000
	s_add_i32 s63, 0, 0x1c000
	v_add_u32_e32 v142, s62, v207
	v_add_u32_e32 v158, s63, v207
	ds_read_b128 v[130:133], v142
	ds_read_b128 v[134:137], v142 offset:1024
	ds_read_b128 v[138:141], v142 offset:2048
	ds_read_b128 v[142:145], v142 offset:3072
	ds_read_b128 v[146:149], v158
	ds_read_b128 v[150:153], v158 offset:1024
	ds_read_b128 v[154:157], v158 offset:2048
	ds_read_b128 v[158:161], v158 offset:3072
	s_add_u32 s40, s40, 0x100000
	s_addc_u32 s41, s41, 0
	s_mov_b32 m0, s43
	v_lshl_add_u64 v[226:227], s[40:41], 0, v[178:179]
	ds_read_b128 v[162:165], v212 offset:32768
	ds_read_b128 v[166:169], v212 offset:33792
	ds_read_b128 v[170:173], v212 offset:34816
	ds_read_b128 v[174:177], v212 offset:35840
	ds_read_b128 v[194:197], v212 offset:36864
	ds_read_b128 v[198:201], v212 offset:37888
	ds_read_b128 v[202:205], v212 offset:38912
	ds_read_b128 v[214:217], v212 offset:39936
	global_load_lds_dwordx4 v[226:227], off
	v_lshl_add_u64 v[226:227], s[40:41], 0, v[182:183]
	s_mov_b32 m0, s44
	s_nop 0
	global_load_lds_dwordx4 v[226:227], off
	s_waitcnt vmcnt(8)
	s_waitcnt lgkmcnt(0)
	s_setprio 1
	s_barrier
	v_mfma_f32_16x16x32_bf16 v[126:129], v[130:133], v[162:165], v[126:129]
	v_mfma_f32_16x16x32_bf16 v[122:125], v[138:141], v[162:165], v[122:125]
	v_mfma_f32_16x16x32_bf16 v[110:113], v[130:133], v[170:173], v[110:113]
	v_mfma_f32_16x16x32_bf16 v[106:109], v[138:141], v[170:173], v[106:109]
	v_mfma_f32_16x16x32_bf16 v[94:97], v[130:133], v[194:197], v[94:97]
	v_mfma_f32_16x16x32_bf16 v[90:93], v[138:141], v[194:197], v[90:93]
	v_mfma_f32_16x16x32_bf16 v[78:81], v[130:133], v[202:205], v[78:81]
	v_mfma_f32_16x16x32_bf16 v[74:77], v[138:141], v[202:205], v[74:77]
	v_mfma_f32_16x16x32_bf16 v[126:129], v[134:137], v[166:169], v[126:129]
	v_mfma_f32_16x16x32_bf16 v[122:125], v[142:145], v[166:169], v[122:125]
	v_mfma_f32_16x16x32_bf16 v[110:113], v[134:137], v[174:177], v[110:113]
	v_mfma_f32_16x16x32_bf16 v[106:109], v[142:145], v[174:177], v[106:109]
	v_mfma_f32_16x16x32_bf16 v[94:97], v[134:137], v[198:201], v[94:97]
	v_mfma_f32_16x16x32_bf16 v[90:93], v[142:145], v[198:201], v[90:93]
	v_mfma_f32_16x16x32_bf16 v[78:81], v[134:137], v[214:217], v[78:81]
	v_mfma_f32_16x16x32_bf16 v[74:77], v[142:145], v[214:217], v[74:77]
	v_mfma_f32_16x16x32_bf16 v[118:121], v[146:149], v[162:165], v[118:121]
	v_mfma_f32_16x16x32_bf16 v[114:117], v[154:157], v[162:165], v[114:117]
	v_mfma_f32_16x16x32_bf16 v[102:105], v[146:149], v[170:173], v[102:105]
	v_mfma_f32_16x16x32_bf16 v[98:101], v[154:157], v[170:173], v[98:101]
	v_mfma_f32_16x16x32_bf16 v[86:89], v[146:149], v[194:197], v[86:89]
	v_mfma_f32_16x16x32_bf16 v[82:85], v[154:157], v[194:197], v[82:85]
	v_mfma_f32_16x16x32_bf16 v[70:73], v[146:149], v[202:205], v[70:73]
	v_mfma_f32_16x16x32_bf16 v[66:69], v[154:157], v[202:205], v[66:69]
	v_mfma_f32_16x16x32_bf16 v[118:121], v[150:153], v[166:169], v[118:121]
	v_mfma_f32_16x16x32_bf16 v[114:117], v[158:161], v[166:169], v[114:117]
	v_mfma_f32_16x16x32_bf16 v[102:105], v[150:153], v[174:177], v[102:105]
	v_mfma_f32_16x16x32_bf16 v[98:101], v[158:161], v[174:177], v[98:101]
	v_mfma_f32_16x16x32_bf16 v[86:89], v[150:153], v[198:201], v[86:89]
	v_mfma_f32_16x16x32_bf16 v[82:85], v[158:161], v[198:201], v[82:85]
	v_mfma_f32_16x16x32_bf16 v[70:73], v[150:153], v[214:217], v[70:73]
	v_mfma_f32_16x16x32_bf16 v[66:69], v[158:161], v[214:217], v[66:69]
	s_barrier
; #define PG8_STAGE(bufoff, gbase, voff) do { _Pragma("unroll") for (int _i = 0; _i < 2; ++_i) \
;         __builtin_amdgcn_global_load_lds((const unsigned*)((const char*)(gbase) + (voff)[_i]), (PG8_LAS unsigned*)(lds + (bufoff) + ldsw + _i * 8192), 16, 0, 0); } while (0)
; #define PG8_LDA(dst, b, h) do { _Pragma("unroll") for (int m = 0; m < 4; ++m) _Pragma("unroll") for (int k = 0; k < 2; ++k) dst[m][k] = *(const PG8_LAS bf16x8*)(lds + PG8_SA(b, h) + aoff + m * 2048 + k * 1024); } while (0)
; #define PG8_LDB(dst, b, h) do { _Pragma("unroll") for (int n = 0; n < 2; ++n) _Pragma("unroll") for (int k = 0; k < 2; ++k) dst[n][k] = *(const PG8_LAS bf16x8*)(lds + PG8_SB(b, h) + boff + n * 2048 + k * 1024); } while (0)
; #define PG8_WAIT_V(n) asm volatile("s_waitcnt vmcnt(" #n ")" ::: "memory")
; #define PG8_WAIT_L(n) asm volatile("s_waitcnt lgkmcnt(" #n ")" ::: "memory")
; #define PG8_BAR __builtin_amdgcn_s_barrier()
; #define PG8_SCHED __builtin_amdgcn_sched_barrier(0)
;     __device__ __forceinline__ void run(const f32x4 (&acc)[2][2][4][2], const Unit& un, int wr, int wc, int fr, int fq, PG8_LAS unsigned char* xl) const {
;     ...
;         const float* bs = un.pm < split_pm ? base + (size_t)un.pm * BM * 4096 : base2 + (size_t)(un.pm - split_pm) * BM * 4096;
; template <class Epi, class Sched, bool ALIGN_EPI = false, bool SP2 = false, bool F8 = false>
; __device__ __forceinline__ void gemm_phase(PG8_LAS unsigned char* lds, const Gemm g, const Sched& S, const Epi& E) {
;     ...
;             PG8_LDB(B0, 1, 0); PG8_LDB(B1, 1, 1); PG8_SCHED; PG8_LDA(At, 1, 0); PG8_STAGE(PG8_SA(0, 1), a2 + hA, voffA);
;             PG8_WAIT_V(8); PG8_WAIT_L(0); PG8_BAR; PG8_MMA(0, 0, At, B0); PG8_MMA(0, 1, At, B1); PG8_BAR; PG8_SCHED;
;             PG8_LDA(At, 1, 1); PG8_STAGE(PG8_SB(1, 0), b3, voffB); PG8_STAGE(PG8_SB(1, 1), b3 + hB, voffB); PG8_STAGE(PG8_SA(1, 0), a3, voffA);
;             PG8_WAIT_V(8); PG8_WAIT_L(0); PG8_BAR; PG8_MMA(1, 0, At, B0); PG8_MMA(1, 1, At, B1); PG8_BAR; PG8_SCHED;
	s_setprio 0
	s_add_i32 s40, s62, s19
	v_lshl_add_u64 v[218:219], v[218:219], 0, s[22:23]
	s_mov_b32 m0, s40
	ds_read_b128 v[162:165], v212 offset:49152
	ds_read_b128 v[166:169], v212 offset:50176
	ds_read_b128 v[170:173], v212 offset:51200
	ds_read_b128 v[174:177], v212 offset:52224
	ds_read_b128 v[194:197], v212 offset:53248
	ds_read_b128 v[198:201], v212 offset:54272
	ds_read_b128 v[202:205], v212 offset:55296
	ds_read_b128 v[214:217], v212 offset:56320
	global_load_lds_dwordx4 v[218:219], off
	s_add_i32 m0, s40, 0x2000
	s_add_u32 s38, s38, 0x100080
	v_lshl_add_u64 v[218:219], v[220:221], 0, s[22:23]
	s_addc_u32 s39, s39, 0
	s_add_i32 s40, s63, s19
	global_load_lds_dwordx4 v[218:219], off
	v_lshl_add_u64 v[218:219], s[38:39], 0, v[180:181]
	s_mov_b32 m0, s40
	s_nop 0
	global_load_lds_dwordx4 v[218:219], off
	v_lshl_add_u64 v[218:219], s[38:39], 0, v[184:185]
	s_add_i32 m0, s40, 0x2000
	s_nop 0
	global_load_lds_dwordx4 v[218:219], off
	v_lshl_add_u64 v[218:219], v[222:223], 0, s[22:23]
	s_mov_b32 m0, s50
	s_nop 0
	global_load_lds_dwordx4 v[218:219], off
	v_lshl_add_u64 v[218:219], v[224:225], 0, s[22:23]
	s_mov_b32 m0, s51
	s_nop 0
	global_load_lds_dwordx4 v[218:219], off
	s_waitcnt vmcnt(8)
	s_waitcnt lgkmcnt(0)
	s_setprio 1
	s_barrier
	v_mfma_f32_16x16x32_bf16 v[62:65], v[130:133], v[162:165], v[62:65]
	v_mfma_f32_16x16x32_bf16 v[58:61], v[138:141], v[162:165], v[58:61]
	v_mfma_f32_16x16x32_bf16 v[46:49], v[130:133], v[170:173], v[46:49]
	v_mfma_f32_16x16x32_bf16 v[42:45], v[138:141], v[170:173], v[42:45]
	v_mfma_f32_16x16x32_bf16 v[30:33], v[130:133], v[194:197], v[30:33]
	v_mfma_f32_16x16x32_bf16 v[26:29], v[138:141], v[194:197], v[26:29]
	v_mfma_f32_16x16x32_bf16 v[14:17], v[130:133], v[202:205], v[14:17]
	v_mfma_f32_16x16x32_bf16 v[10:13], v[138:141], v[202:205], v[10:13]
	v_mfma_f32_16x16x32_bf16 v[62:65], v[134:137], v[166:169], v[62:65]
	v_mfma_f32_16x16x32_bf16 v[58:61], v[142:145], v[166:169], v[58:61]
	v_mfma_f32_16x16x32_bf16 v[46:49], v[134:137], v[174:177], v[46:49]
	v_mfma_f32_16x16x32_bf16 v[42:45], v[142:145], v[174:177], v[42:45]
	v_mfma_f32_16x16x32_bf16 v[30:33], v[134:137], v[198:201], v[30:33]
	v_mfma_f32_16x16x32_bf16 v[26:29], v[142:145], v[198:201], v[26:29]
	v_mfma_f32_16x16x32_bf16 v[14:17], v[134:137], v[214:217], v[14:17]
	v_mfma_f32_16x16x32_bf16 v[10:13], v[142:145], v[214:217], v[10:13]
	v_mfma_f32_16x16x32_bf16 v[54:57], v[146:149], v[162:165], v[54:57]
	v_mfma_f32_16x16x32_bf16 v[50:53], v[154:157], v[162:165], v[50:53]
	v_mfma_f32_16x16x32_bf16 v[38:41], v[146:149], v[170:173], v[38:41]
	v_mfma_f32_16x16x32_bf16 v[34:37], v[154:157], v[170:173], v[34:37]
	v_mfma_f32_16x16x32_bf16 v[22:25], v[146:149], v[194:197], v[22:25]
	v_mfma_f32_16x16x32_bf16 v[18:21], v[154:157], v[194:197], v[18:21]
	v_mfma_f32_16x16x32_bf16 v[6:9], v[146:149], v[202:205], v[6:9]
	v_mfma_f32_16x16x32_bf16 v[2:5], v[154:157], v[202:205], v[2:5]
	v_mfma_f32_16x16x32_bf16 v[54:57], v[150:153], v[166:169], v[54:57]
	v_mfma_f32_16x16x32_bf16 v[50:53], v[158:161], v[166:169], v[50:53]
	v_mfma_f32_16x16x32_bf16 v[38:41], v[150:153], v[174:177], v[38:41]
	v_mfma_f32_16x16x32_bf16 v[34:37], v[158:161], v[174:177], v[34:37]
	v_mfma_f32_16x16x32_bf16 v[22:25], v[150:153], v[198:201], v[22:25]
	v_mfma_f32_16x16x32_bf16 v[18:21], v[158:161], v[198:201], v[18:21]
	v_mfma_f32_16x16x32_bf16 v[6:9], v[150:153], v[214:217], v[6:9]
	v_mfma_f32_16x16x32_bf16 v[2:5], v[158:161], v[214:217], v[2:5]
	s_barrier
	s_setprio 0
	s_add_i32 s61, s61, 2
	s_add_u32 s35, s35, 0x100
	s_addc_u32 s60, s60, 0
	s_add_u32 s36, s36, 0x100
	s_addc_u32 s37, s37, 0
	s_cmp_gt_u32 s61, 61
	s_cbranch_scc0 .LBB0_689
	v_mov_b32_e32 v214, v206
	s_cmp_gt_i32 s16, 63
	s_mov_b64 s[38:39], -1
	s_cbranch_scc0 .LBB0_692
	s_sub_i32 s20, s16, 64
	s_lshl_b64 s[36:37], s[20:21], 22
	s_add_u32 s36, s14, s36
	s_addc_u32 s37, s15, s37
	s_mov_b32 s17, s21
	s_mov_b64 s[38:39], 0

; #define PG8_STAGE(bufoff, gbase, voff) do { _Pragma("unroll") for (int _i = 0; _i < 2; ++_i) \
;         __builtin_amdgcn_global_load_lds((const unsigned*)((const char*)(gbase) + (voff)[_i]), (PG8_LAS unsigned*)(lds + (bufoff) + ldsw + _i * 8192), 16, 0, 0); } while (0)
; #define PG8_LDA(dst, b, h) do { _Pragma("unroll") for (int m = 0; m < 4; ++m) _Pragma("unroll") for (int k = 0; k < 2; ++k) dst[m][k] = *(const PG8_LAS bf16x8*)(lds + PG8_SA(b, h) + aoff + m * 2048 + k * 1024); } while (0)
; #define PG8_LDB(dst, b, h) do { _Pragma("unroll") for (int n = 0; n < 2; ++n) _Pragma("unroll") for (int k = 0; k < 2; ++k) dst[n][k] = *(const PG8_LAS bf16x8*)(lds + PG8_SB(b, h) + boff + n * 2048 + k * 1024); } while (0)
; #define PG8_WAIT_V(n) asm volatile("s_waitcnt vmcnt(" #n ")" ::: "memory")
; #define PG8_WAIT_L(n) asm volatile("s_waitcnt lgkmcnt(" #n ")" ::: "memory")
; #define PG8_BAR __builtin_amdgcn_s_barrier()
; #define PG8_SCHED __builtin_amdgcn_sched_barrier(0)
; template <class Epi, class Sched, bool ALIGN_EPI = false, bool SP2 = false, bool F8 = false>
; __device__ __forceinline__ void gemm_phase(PG8_LAS unsigned char* lds, const Gemm g, const Sched& S, const Epi& E) {
;     ...
;         for (int t = 0; t < nt; t += 2) {
;             const bool last = (t == nt - 2);
;             const char* a1 = cA + (size_t)(t + 1) * kstep;
;             const char* a2 = last ? nA : cA + (size_t)(t + 2) * kstep; const char* b2 = last ? nB : cB + (size_t)(t + 2) * kstep;
;             const char* a3 = a2 + kstep; const char* b3 = b2 + kstep;
;             if (last && has_next) S.a_ready(nxt);
;             if constexpr (SP2) {
;             PG8_LDB(B0, 0, 0); PG8_LDB(B1, 0, 1); PG8_SCHED; PG8_LDA(At, 0, 0); PG8_STAGE(PG8_SA(1, 1), a1 + hA, voffA);
;             PG8_WAIT_V(8); PG8_WAIT_L(0); PG8_BAR; PG8_MMA(0, 0, At, B0); PG8_MMA(0, 1, At, B1); PG8_BAR; PG8_SCHED;
;             PG8_LDA(At, 0, 1); PG8_STAGE(PG8_SB(0, 0), b2, voffB); PG8_STAGE(PG8_SB(0, 1), b2 + hB, voffB); PG8_STAGE(PG8_SA(0, 0), a2, voffA);
.LBB0_770:
	ds_read_b128 v[130:133], v241
	ds_read_b128 v[134:137], v241 offset:1024
	ds_read_b128 v[138:141], v241 offset:2048
	ds_read_b128 v[142:145], v241 offset:3072
	ds_read_b128 v[146:149], v242
	ds_read_b128 v[150:153], v242 offset:1024
	ds_read_b128 v[154:157], v242 offset:2048
	ds_read_b128 v[158:161], v242 offset:3072
	s_add_u32 s14, s12, 0xfff00080
	s_addc_u32 s15, s13, -1
	s_cmp_eq_u32 s80, 60
	s_cselect_b32 s17, s11, s15
	s_cselect_b32 s16, s63, s14
	s_cselect_b32 s15, s61, s79
	s_cselect_b32 s14, s77, s78
	v_lshl_add_u64 v[208:209], s[12:13], 0, v[188:189]
	s_add_i32 m0, s7, 0xc000
	ds_read_b128 v[162:165], v243
	ds_read_b128 v[166:169], v243 offset:1024
	ds_read_b128 v[170:173], v243 offset:2048
	ds_read_b128 v[174:177], v243 offset:3072
	ds_read_b128 v[192:195], v243 offset:4096
	ds_read_b128 v[196:199], v243 offset:5120
	ds_read_b128 v[200:203], v243 offset:6144
	ds_read_b128 v[204:207], v243 offset:7168
	global_load_lds_dwordx4 v[208:209], off
	v_lshl_add_u64 v[208:209], s[12:13], 0, v[186:187]
	s_add_i32 m0, s7, 0xe000
	s_nop 0
	global_load_lds_dwordx4 v[208:209], off
	s_waitcnt vmcnt(8)
	s_waitcnt lgkmcnt(0)
	s_setprio 1
	s_barrier
	v_mfma_f32_16x16x32_bf16 v[126:129], v[130:133], v[162:165], v[126:129]
	v_mfma_f32_16x16x32_bf16 v[90:93], v[138:141], v[162:165], v[90:93]
	v_mfma_f32_16x16x32_bf16 v[110:113], v[130:133], v[170:173], v[110:113]
	v_mfma_f32_16x16x32_bf16 v[86:89], v[138:141], v[170:173], v[86:89]
	v_mfma_f32_16x16x32_bf16 v[106:109], v[130:133], v[192:195], v[106:109]
	v_mfma_f32_16x16x32_bf16 v[82:85], v[138:141], v[192:195], v[82:85]
	v_mfma_f32_16x16x32_bf16 v[118:121], v[130:133], v[200:203], v[118:121]
	v_mfma_f32_16x16x32_bf16 v[122:125], v[138:141], v[200:203], v[122:125]
	v_mfma_f32_16x16x32_bf16 v[126:129], v[134:137], v[166:169], v[126:129]
	v_mfma_f32_16x16x32_bf16 v[90:93], v[142:145], v[166:169], v[90:93]
	v_mfma_f32_16x16x32_bf16 v[110:113], v[134:137], v[174:177], v[110:113]
	v_mfma_f32_16x16x32_bf16 v[86:89], v[142:145], v[174:177], v[86:89]
	v_mfma_f32_16x16x32_bf16 v[106:109], v[134:137], v[196:199], v[106:109]
	v_mfma_f32_16x16x32_bf16 v[82:85], v[142:145], v[196:199], v[82:85]
	v_mfma_f32_16x16x32_bf16 v[118:121], v[134:137], v[204:207], v[118:121]
	v_mfma_f32_16x16x32_bf16 v[122:125], v[142:145], v[204:207], v[122:125]
	v_mfma_f32_16x16x32_bf16 v[94:97], v[146:149], v[162:165], v[94:97]
	v_mfma_f32_16x16x32_bf16 v[66:69], v[154:157], v[162:165], v[66:69]
	v_mfma_f32_16x16x32_bf16 v[102:105], v[146:149], v[170:173], v[102:105]
	v_mfma_f32_16x16x32_bf16 v[78:81], v[154:157], v[170:173], v[78:81]
	v_mfma_f32_16x16x32_bf16 v[98:101], v[146:149], v[192:195], v[98:101]
	v_mfma_f32_16x16x32_bf16 v[74:77], v[154:157], v[192:195], v[74:77]
	v_mfma_f32_16x16x32_bf16 v[70:73], v[146:149], v[200:203], v[70:73]
	v_mfma_f32_16x16x32_bf16 v[58:61], v[154:157], v[200:203], v[58:61]
	v_mfma_f32_16x16x32_bf16 v[94:97], v[150:153], v[166:169], v[94:97]
	v_mfma_f32_16x16x32_bf16 v[66:69], v[158:161], v[166:169], v[66:69]
	v_mfma_f32_16x16x32_bf16 v[102:105], v[150:153], v[174:177], v[102:105]
	v_mfma_f32_16x16x32_bf16 v[78:81], v[158:161], v[174:177], v[78:81]
	v_mfma_f32_16x16x32_bf16 v[98:101], v[150:153], v[196:199], v[98:101]
	v_mfma_f32_16x16x32_bf16 v[74:77], v[158:161], v[196:199], v[74:77]
	v_mfma_f32_16x16x32_bf16 v[70:73], v[150:153], v[204:207], v[70:73]
	v_mfma_f32_16x16x32_bf16 v[58:61], v[158:161], v[204:207], v[58:61]
	s_barrier
	s_setprio 0
	s_add_i32 s81, s97, s6
	v_lshl_add_u64 v[208:209], s[14:15], 0, v[180:181]
	s_mov_b32 m0, s81
	ds_read_b128 v[162:165], v243 offset:16384
	ds_read_b128 v[166:169], v243 offset:17408
	ds_read_b128 v[170:173], v243 offset:18432
	ds_read_b128 v[174:177], v243 offset:19456
	ds_read_b128 v[192:195], v243 offset:20480
	ds_read_b128 v[196:199], v243 offset:21504
	ds_read_b128 v[200:203], v243 offset:22528
	ds_read_b128 v[204:207], v243 offset:23552
	global_load_lds_dwordx4 v[208:209], off
	s_add_i32 m0, s81, 0x2000
	s_add_u32 vcc_lo, s14, 0x100000
	v_lshl_add_u64 v[210:211], s[14:15], 0, v[184:185]
	s_addc_u32 vcc_hi, s15, 0
	s_add_i32 s81, s86, s6
	global_load_lds_dwordx4 v[210:211], off
	v_lshl_add_u64 v[212:213], vcc, 0, v[180:181]
	s_mov_b32 m0, s81
	v_lshl_add_u64 v[214:215], s[16:17], 0, v[182:183]
	global_load_lds_dwordx4 v[212:213], off
	v_lshl_add_u64 v[212:213], vcc, 0, v[184:185]
	s_add_i32 m0, s81, 0x2000
	s_nop 0
	global_load_lds_dwordx4 v[212:213], off
	v_lshl_add_u64 v[212:213], s[16:17], 0, v[178:179]
	s_mov_b32 m0, s7
	s_nop 0
	global_load_lds_dwordx4 v[212:213], off
	s_mov_b32 m0, s18
	s_nop 0
	global_load_lds_dwordx4 v[214:215], off
	s_waitcnt vmcnt(8)
	s_waitcnt lgkmcnt(0)
	s_setprio 1
	s_barrier
; #define PG8_STAGE(bufoff, gbase, voff) do { _Pragma("unroll") for (int _i = 0; _i < 2; ++_i) \
;         __builtin_amdgcn_global_load_lds((const unsigned*)((const char*)(gbase) + (voff)[_i]), (PG8_LAS unsigned*)(lds + (bufoff) + ldsw + _i * 8192), 16, 0, 0); } while (0)
; #define PG8_LDA(dst, b, h) do { _Pragma("unroll") for (int m = 0; m < 4; ++m) _Pragma("unroll") for (int k = 0; k < 2; ++k) dst[m][k] = *(const PG8_LAS bf16x8*)(lds + PG8_SA(b, h) + aoff + m * 2048 + k * 1024); } while (0)
; #define PG8_LDB(dst, b, h) do { _Pragma("unroll") for (int n = 0; n < 2; ++n) _Pragma("unroll") for (int k = 0; k < 2; ++k) dst[n][k] = *(const PG8_LAS bf16x8*)(lds + PG8_SB(b, h) + boff + n * 2048 + k * 1024); } while (0)
; #define PG8_WAIT_V(n) asm volatile("s_waitcnt vmcnt(" #n ")" ::: "memory")
; #define PG8_WAIT_L(n) asm volatile("s_waitcnt lgkmcnt(" #n ")" ::: "memory")
; #define PG8_BAR __builtin_amdgcn_s_barrier()
; #define PG8_SCHED __builtin_amdgcn_sched_barrier(0)
; template <class Epi, class Sched, bool ALIGN_EPI = false, bool SP2 = false, bool F8 = false>
; __device__ __forceinline__ void gemm_phase(PG8_LAS unsigned char* lds, const Gemm g, const Sched& S, const Epi& E) {
;     ...
;             PG8_LDA(At, 0, 1); PG8_STAGE(PG8_SB(0, 0), b2, voffB); PG8_STAGE(PG8_SB(0, 1), b2 + hB, voffB); PG8_STAGE(PG8_SA(0, 0), a2, voffA);
;             PG8_WAIT_V(8); PG8_WAIT_L(0); PG8_BAR; PG8_MMA(1, 0, At, B0); PG8_MMA(1, 1, At, B1); PG8_BAR; PG8_SCHED;
;             PG8_LDB(B0, 1, 0); PG8_LDB(B1, 1, 1); PG8_SCHED; PG8_LDA(At, 1, 0); PG8_STAGE(PG8_SA(0, 1), a2 + hA, voffA);
;             PG8_WAIT_V(8); PG8_WAIT_L(0); PG8_BAR; PG8_MMA(0, 0, At, B0); PG8_MMA(0, 1, At, B1); PG8_BAR; PG8_SCHED;
;             PG8_LDA(At, 1, 1); PG8_STAGE(PG8_SB(1, 0), b3, voffB); PG8_STAGE(PG8_SB(1, 1), b3 + hB, voffB); PG8_STAGE(PG8_SA(1, 0), a3, voffA);
	v_mfma_f32_16x16x32_bf16 v[62:65], v[130:133], v[162:165], v[62:65]
	v_mfma_f32_16x16x32_bf16 v[38:41], v[138:141], v[162:165], v[38:41]
	v_mfma_f32_16x16x32_bf16 v[42:45], v[130:133], v[170:173], v[42:45]
	v_mfma_f32_16x16x32_bf16 v[14:17], v[138:141], v[170:173], v[14:17]
	v_mfma_f32_16x16x32_bf16 v[34:37], v[130:133], v[192:195], v[34:37]
	v_mfma_f32_16x16x32_bf16 v[10:13], v[138:141], v[192:195], v[10:13]
	v_mfma_f32_16x16x32_bf16 v[50:53], v[130:133], v[200:203], v[50:53]
	v_mfma_f32_16x16x32_bf16 v[114:117], v[138:141], v[200:203], v[114:117]
	v_mfma_f32_16x16x32_bf16 v[62:65], v[134:137], v[166:169], v[62:65]
	v_mfma_f32_16x16x32_bf16 v[38:41], v[142:145], v[166:169], v[38:41]
	v_mfma_f32_16x16x32_bf16 v[42:45], v[134:137], v[174:177], v[42:45]
	v_mfma_f32_16x16x32_bf16 v[14:17], v[142:145], v[174:177], v[14:17]
	v_mfma_f32_16x16x32_bf16 v[34:37], v[134:137], v[196:199], v[34:37]
	v_mfma_f32_16x16x32_bf16 v[10:13], v[142:145], v[196:199], v[10:13]
	v_mfma_f32_16x16x32_bf16 v[50:53], v[134:137], v[204:207], v[50:53]
	v_mfma_f32_16x16x32_bf16 v[114:117], v[142:145], v[204:207], v[114:117]
	v_mfma_f32_16x16x32_bf16 v[46:49], v[146:149], v[162:165], v[46:49]
	v_mfma_f32_16x16x32_bf16 v[22:25], v[154:157], v[162:165], v[22:25]
	v_mfma_f32_16x16x32_bf16 v[30:33], v[146:149], v[170:173], v[30:33]
	v_mfma_f32_16x16x32_bf16 v[6:9], v[154:157], v[170:173], v[6:9]
	v_mfma_f32_16x16x32_bf16 v[26:29], v[146:149], v[192:195], v[26:29]
	v_mfma_f32_16x16x32_bf16 v[2:5], v[154:157], v[192:195], v[2:5]
	v_mfma_f32_16x16x32_bf16 v[54:57], v[146:149], v[200:203], v[54:57]
	v_mfma_f32_16x16x32_bf16 v[18:21], v[154:157], v[200:203], v[18:21]
	v_mfma_f32_16x16x32_bf16 v[46:49], v[150:153], v[166:169], v[46:49]
	v_mfma_f32_16x16x32_bf16 v[22:25], v[158:161], v[166:169], v[22:25]
	v_mfma_f32_16x16x32_bf16 v[30:33], v[150:153], v[174:177], v[30:33]
	v_mfma_f32_16x16x32_bf16 v[6:9], v[158:161], v[174:177], v[6:9]
	v_mfma_f32_16x16x32_bf16 v[26:29], v[150:153], v[196:199], v[26:29]
	v_mfma_f32_16x16x32_bf16 v[2:5], v[158:161], v[196:199], v[2:5]
	v_mfma_f32_16x16x32_bf16 v[54:57], v[150:153], v[204:207], v[54:57]
	v_mfma_f32_16x16x32_bf16 v[18:21], v[158:161], v[204:207], v[18:21]
	s_barrier
	s_setprio 0
	s_add_i32 s81, 0, 0x18000
	s_add_i32 vcc_lo, 0, 0x1c000
	v_add_u32_e32 v142, s81, v240
	v_add_u32_e32 v158, vcc_lo, v240
	ds_read_b128 v[130:133], v142
	ds_read_b128 v[134:137], v142 offset:1024
	ds_read_b128 v[138:141], v142 offset:2048
	ds_read_b128 v[142:145], v142 offset:3072
	ds_read_b128 v[146:149], v158
	ds_read_b128 v[150:153], v158 offset:1024
	ds_read_b128 v[154:157], v158 offset:2048
	ds_read_b128 v[158:161], v158 offset:3072
	s_add_u32 s16, s16, 0x100000
	s_addc_u32 s17, s17, 0
	s_mov_b32 m0, s19
	v_lshl_add_u64 v[216:217], s[16:17], 0, v[178:179]
	ds_read_b128 v[162:165], v243 offset:32768
	ds_read_b128 v[166:169], v243 offset:33792
	ds_read_b128 v[170:173], v243 offset:34816
	ds_read_b128 v[174:177], v243 offset:35840
	ds_read_b128 v[192:195], v243 offset:36864
	ds_read_b128 v[196:199], v243 offset:37888
	ds_read_b128 v[200:203], v243 offset:38912
	ds_read_b128 v[204:207], v243 offset:39936
	global_load_lds_dwordx4 v[216:217], off
	v_lshl_add_u64 v[216:217], s[16:17], 0, v[182:183]
	s_mov_b32 m0, s33
	s_nop 0
	global_load_lds_dwordx4 v[216:217], off
	s_waitcnt vmcnt(8)
	s_waitcnt lgkmcnt(0)
	s_setprio 1
	s_barrier
	v_mfma_f32_16x16x32_bf16 v[126:129], v[130:133], v[162:165], v[126:129]
	v_mfma_f32_16x16x32_bf16 v[90:93], v[138:141], v[162:165], v[90:93]
	v_mfma_f32_16x16x32_bf16 v[110:113], v[130:133], v[170:173], v[110:113]
	v_mfma_f32_16x16x32_bf16 v[86:89], v[138:141], v[170:173], v[86:89]
	v_mfma_f32_16x16x32_bf16 v[106:109], v[130:133], v[192:195], v[106:109]
	v_mfma_f32_16x16x32_bf16 v[82:85], v[138:141], v[192:195], v[82:85]
	v_mfma_f32_16x16x32_bf16 v[118:121], v[130:133], v[200:203], v[118:121]
	v_mfma_f32_16x16x32_bf16 v[122:125], v[138:141], v[200:203], v[122:125]
	v_mfma_f32_16x16x32_bf16 v[126:129], v[134:137], v[166:169], v[126:129]
	v_mfma_f32_16x16x32_bf16 v[90:93], v[142:145], v[166:169], v[90:93]
	v_mfma_f32_16x16x32_bf16 v[110:113], v[134:137], v[174:177], v[110:113]
	v_mfma_f32_16x16x32_bf16 v[86:89], v[142:145], v[174:177], v[86:89]
	v_mfma_f32_16x16x32_bf16 v[106:109], v[134:137], v[196:199], v[106:109]
	v_mfma_f32_16x16x32_bf16 v[82:85], v[142:145], v[196:199], v[82:85]
	v_mfma_f32_16x16x32_bf16 v[118:121], v[134:137], v[204:207], v[118:121]
	v_mfma_f32_16x16x32_bf16 v[122:125], v[142:145], v[204:207], v[122:125]
	v_mfma_f32_16x16x32_bf16 v[94:97], v[146:149], v[162:165], v[94:97]
	v_mfma_f32_16x16x32_bf16 v[66:69], v[154:157], v[162:165], v[66:69]
	v_mfma_f32_16x16x32_bf16 v[102:105], v[146:149], v[170:173], v[102:105]
	v_mfma_f32_16x16x32_bf16 v[78:81], v[154:157], v[170:173], v[78:81]
	v_mfma_f32_16x16x32_bf16 v[98:101], v[146:149], v[192:195], v[98:101]
	v_mfma_f32_16x16x32_bf16 v[74:77], v[154:157], v[192:195], v[74:77]
	v_mfma_f32_16x16x32_bf16 v[70:73], v[146:149], v[200:203], v[70:73]
	v_mfma_f32_16x16x32_bf16 v[58:61], v[154:157], v[200:203], v[58:61]
	v_mfma_f32_16x16x32_bf16 v[94:97], v[150:153], v[166:169], v[94:97]
	v_mfma_f32_16x16x32_bf16 v[66:69], v[158:161], v[166:169], v[66:69]
	v_mfma_f32_16x16x32_bf16 v[102:105], v[150:153], v[174:177], v[102:105]
	v_mfma_f32_16x16x32_bf16 v[78:81], v[158:161], v[174:177], v[78:81]
	v_mfma_f32_16x16x32_bf16 v[98:101], v[150:153], v[196:199], v[98:101]
	v_mfma_f32_16x16x32_bf16 v[74:77], v[158:161], v[196:199], v[74:77]
	v_mfma_f32_16x16x32_bf16 v[70:73], v[150:153], v[204:207], v[70:73]
	v_mfma_f32_16x16x32_bf16 v[58:61], v[158:161], v[204:207], v[58:61]
	s_barrier
; #define PG8_STAGE(bufoff, gbase, voff) do { _Pragma("unroll") for (int _i = 0; _i < 2; ++_i) \
;         __builtin_amdgcn_global_load_lds((const unsigned*)((const char*)(gbase) + (voff)[_i]), (PG8_LAS unsigned*)(lds + (bufoff) + ldsw + _i * 8192), 16, 0, 0); } while (0)
; #define PG8_LDA(dst, b, h) do { _Pragma("unroll") for (int m = 0; m < 4; ++m) _Pragma("unroll") for (int k = 0; k < 2; ++k) dst[m][k] = *(const PG8_LAS bf16x8*)(lds + PG8_SA(b, h) + aoff + m * 2048 + k * 1024); } while (0)
; #define PG8_WAIT_V(n) asm volatile("s_waitcnt vmcnt(" #n ")" ::: "memory")
; #define PG8_WAIT_L(n) asm volatile("s_waitcnt lgkmcnt(" #n ")" ::: "memory")
; #define PG8_BAR __builtin_amdgcn_s_barrier()
; #define PG8_SCHED __builtin_amdgcn_sched_barrier(0)
; template <class Epi, class Sched, bool ALIGN_EPI = false, bool SP2 = false, bool F8 = false>
; __device__ __forceinline__ void gemm_phase(PG8_LAS unsigned char* lds, const Gemm g, const Sched& S, const Epi& E) {
;     ...
;             PG8_LDA(At, 1, 1); PG8_STAGE(PG8_SB(1, 0), b3, voffB); PG8_STAGE(PG8_SB(1, 1), b3 + hB, voffB); PG8_STAGE(PG8_SA(1, 0), a3, voffA);
;             PG8_WAIT_V(8); PG8_WAIT_L(0); PG8_BAR; PG8_MMA(1, 0, At, B0); PG8_MMA(1, 1, At, B1); PG8_BAR; PG8_SCHED;
;     ...
;         if constexpr (ALIGN_EPI) { if (wr == 0) PG8_BAR; }
	s_setprio 0
	s_add_i32 s16, s81, s6
	v_lshl_add_u64 v[208:209], v[208:209], 0, s[36:37]
	s_mov_b32 m0, s16
	ds_read_b128 v[162:165], v243 offset:49152
	ds_read_b128 v[166:169], v243 offset:50176
	ds_read_b128 v[170:173], v243 offset:51200
	ds_read_b128 v[174:177], v243 offset:52224
	ds_read_b128 v[192:195], v243 offset:53248
	ds_read_b128 v[196:199], v243 offset:54272
	ds_read_b128 v[200:203], v243 offset:55296
	ds_read_b128 v[204:207], v243 offset:56320
	global_load_lds_dwordx4 v[208:209], off
	s_add_i32 m0, s16, 0x2000
	s_add_u32 s14, s14, 0x100080
	v_lshl_add_u64 v[208:209], v[210:211], 0, s[36:37]
	s_addc_u32 s15, s15, 0
	s_add_i32 s16, vcc_lo, s6
	global_load_lds_dwordx4 v[208:209], off
	v_lshl_add_u64 v[208:209], s[14:15], 0, v[180:181]
	s_mov_b32 m0, s16
	s_nop 0
	global_load_lds_dwordx4 v[208:209], off
	v_lshl_add_u64 v[208:209], s[14:15], 0, v[184:185]
	s_add_i32 m0, s16, 0x2000
	s_nop 0
	global_load_lds_dwordx4 v[208:209], off
	v_lshl_add_u64 v[208:209], v[212:213], 0, s[36:37]
	s_mov_b32 m0, s71
	s_nop 0
	global_load_lds_dwordx4 v[208:209], off
	v_lshl_add_u64 v[208:209], v[214:215], 0, s[36:37]
	s_mov_b32 m0, s74
	s_nop 0
	global_load_lds_dwordx4 v[208:209], off
	s_waitcnt vmcnt(8)
	s_waitcnt lgkmcnt(0)
	s_setprio 1
	s_barrier
	v_mfma_f32_16x16x32_bf16 v[62:65], v[130:133], v[162:165], v[62:65]
	v_mfma_f32_16x16x32_bf16 v[38:41], v[138:141], v[162:165], v[38:41]
	v_mfma_f32_16x16x32_bf16 v[42:45], v[130:133], v[170:173], v[42:45]
	v_mfma_f32_16x16x32_bf16 v[14:17], v[138:141], v[170:173], v[14:17]
	v_mfma_f32_16x16x32_bf16 v[34:37], v[130:133], v[192:195], v[34:37]
	v_mfma_f32_16x16x32_bf16 v[10:13], v[138:141], v[192:195], v[10:13]
	v_mfma_f32_16x16x32_bf16 v[50:53], v[130:133], v[200:203], v[50:53]
	v_mfma_f32_16x16x32_bf16 v[114:117], v[138:141], v[200:203], v[114:117]
	v_mfma_f32_16x16x32_bf16 v[62:65], v[134:137], v[166:169], v[62:65]
	v_mfma_f32_16x16x32_bf16 v[38:41], v[142:145], v[166:169], v[38:41]
	v_mfma_f32_16x16x32_bf16 v[42:45], v[134:137], v[174:177], v[42:45]
	v_mfma_f32_16x16x32_bf16 v[14:17], v[142:145], v[174:177], v[14:17]
	v_mfma_f32_16x16x32_bf16 v[34:37], v[134:137], v[196:199], v[34:37]
	v_mfma_f32_16x16x32_bf16 v[10:13], v[142:145], v[196:199], v[10:13]
	v_mfma_f32_16x16x32_bf16 v[50:53], v[134:137], v[204:207], v[50:53]
	v_mfma_f32_16x16x32_bf16 v[114:117], v[142:145], v[204:207], v[114:117]
	v_mfma_f32_16x16x32_bf16 v[46:49], v[146:149], v[162:165], v[46:49]
	v_mfma_f32_16x16x32_bf16 v[22:25], v[154:157], v[162:165], v[22:25]
	v_mfma_f32_16x16x32_bf16 v[30:33], v[146:149], v[170:173], v[30:33]
	v_mfma_f32_16x16x32_bf16 v[6:9], v[154:157], v[170:173], v[6:9]
	v_mfma_f32_16x16x32_bf16 v[26:29], v[146:149], v[192:195], v[26:29]
	v_mfma_f32_16x16x32_bf16 v[2:5], v[154:157], v[192:195], v[2:5]
	v_mfma_f32_16x16x32_bf16 v[54:57], v[146:149], v[200:203], v[54:57]
	v_mfma_f32_16x16x32_bf16 v[18:21], v[154:157], v[200:203], v[18:21]
	v_mfma_f32_16x16x32_bf16 v[46:49], v[150:153], v[166:169], v[46:49]
	v_mfma_f32_16x16x32_bf16 v[22:25], v[158:161], v[166:169], v[22:25]
	v_mfma_f32_16x16x32_bf16 v[30:33], v[150:153], v[174:177], v[30:33]
	v_mfma_f32_16x16x32_bf16 v[6:9], v[158:161], v[174:177], v[6:9]
	v_mfma_f32_16x16x32_bf16 v[26:29], v[150:153], v[196:199], v[26:29]
	v_mfma_f32_16x16x32_bf16 v[2:5], v[158:161], v[196:199], v[2:5]
	v_mfma_f32_16x16x32_bf16 v[54:57], v[150:153], v[204:207], v[54:57]
	v_mfma_f32_16x16x32_bf16 v[18:21], v[158:161], v[204:207], v[18:21]
	s_barrier
	s_setprio 0
	s_add_i32 s80, s80, 2
	s_add_u32 s78, s78, 0x100
	s_addc_u32 s79, s79, 0
	s_add_u32 s12, s12, 0x100
	s_addc_u32 s13, s13, 0
	s_cmp_gt_u32 s80, 61
	s_cbranch_scc0 .LBB0_770
	s_and_b64 vcc, exec, s[38:39]
	s_cbranch_vccz .LBB0_773
	s_barrier

; #define PG8_STAGE(bufoff, gbase, voff) do { _Pragma("unroll") for (int _i = 0; _i < 2; ++_i) \
;         __builtin_amdgcn_global_load_lds((const unsigned*)((const char*)(gbase) + (voff)[_i]), (PG8_LAS unsigned*)(lds + (bufoff) + ldsw + _i * 8192), 16, 0, 0); } while (0)
; #define PG8_LDA(dst, b, h) do { _Pragma("unroll") for (int m = 0; m < 4; ++m) _Pragma("unroll") for (int k = 0; k < 2; ++k) dst[m][k] = *(const PG8_LAS bf16x8*)(lds + PG8_SA(b, h) + aoff + m * 2048 + k * 1024); } while (0)
; #define PG8_LDB(dst, b, h) do { _Pragma("unroll") for (int n = 0; n < 2; ++n) _Pragma("unroll") for (int k = 0; k < 2; ++k) dst[n][k] = *(const PG8_LAS bf16x8*)(lds + PG8_SB(b, h) + boff + n * 2048 + k * 1024); } while (0)
; #define PG8_WAIT_V(n) asm volatile("s_waitcnt vmcnt(" #n ")" ::: "memory")
; #define PG8_WAIT_L(n) asm volatile("s_waitcnt lgkmcnt(" #n ")" ::: "memory")
; #define PG8_BAR __builtin_amdgcn_s_barrier()
; #define PG8_SCHED __builtin_amdgcn_sched_barrier(0)
; template <class Epi, class Sched, bool ALIGN_EPI = false, bool SP2 = false, bool F8 = false>
; __device__ __forceinline__ void gemm_phase(PG8_LAS unsigned char* lds, const Gemm g, const Sched& S, const Epi& E) {
;     ...
;             PG8_LDB(B0, 0, 0); PG8_LDB(B1, 0, 1); PG8_SCHED; PG8_LDA(At, 0, 0); PG8_STAGE(PG8_SA(1, 1), a1 + hA, voffA);
;             PG8_WAIT_V(8); PG8_WAIT_L(0); PG8_BAR; PG8_MMA(0, 0, At, B0); PG8_MMA(0, 1, At, B1); PG8_BAR; PG8_SCHED;
;             PG8_LDA(At, 0, 1); PG8_STAGE(PG8_SB(0, 0), b2, voffB); PG8_STAGE(PG8_SB(0, 1), b2 + hB, voffB); PG8_STAGE(PG8_SA(0, 0), a2, voffA);
;             PG8_WAIT_V(8); PG8_WAIT_L(0); PG8_BAR; PG8_MMA(1, 0, At, B0); PG8_MMA(1, 1, At, B1); PG8_BAR; PG8_SCHED;
.LBB0_825:
	ds_read_b128 v[130:133], v241
	ds_read_b128 v[134:137], v241 offset:1024
	ds_read_b128 v[138:141], v241 offset:2048
	ds_read_b128 v[142:145], v241 offset:3072
	ds_read_b128 v[146:149], v242
	ds_read_b128 v[150:153], v242 offset:1024
	ds_read_b128 v[154:157], v242 offset:2048
	ds_read_b128 v[158:161], v242 offset:3072
	s_add_u32 s14, s12, 0xfff00080
	s_addc_u32 s15, s13, -1
	s_cmp_eq_u32 s82, 60
	s_cselect_b32 s17, s11, s15
	s_cselect_b32 s16, s63, s14
	s_cselect_b32 s15, s65, s81
	s_cselect_b32 s14, s79, s80
	v_lshl_add_u64 v[208:209], s[12:13], 0, v[188:189]
	s_add_i32 m0, s7, 0xc000
	ds_read_b128 v[162:165], v243
	ds_read_b128 v[166:169], v243 offset:1024
	ds_read_b128 v[170:173], v243 offset:2048
	ds_read_b128 v[174:177], v243 offset:3072
	ds_read_b128 v[192:195], v243 offset:4096
	ds_read_b128 v[196:199], v243 offset:5120
	ds_read_b128 v[200:203], v243 offset:6144
	ds_read_b128 v[204:207], v243 offset:7168
	global_load_lds_dwordx4 v[208:209], off
	v_lshl_add_u64 v[208:209], s[12:13], 0, v[186:187]
	s_add_i32 m0, s7, 0xe000
	s_nop 0
	global_load_lds_dwordx4 v[208:209], off
	s_waitcnt vmcnt(8)
	s_waitcnt lgkmcnt(0)
	s_setprio 1
	s_barrier
	v_mfma_f32_16x16x32_bf16 v[126:129], v[130:133], v[162:165], v[126:129]
	v_mfma_f32_16x16x32_bf16 v[90:93], v[138:141], v[162:165], v[90:93]
	v_mfma_f32_16x16x32_bf16 v[110:113], v[130:133], v[170:173], v[110:113]
	v_mfma_f32_16x16x32_bf16 v[86:89], v[138:141], v[170:173], v[86:89]
	v_mfma_f32_16x16x32_bf16 v[106:109], v[130:133], v[192:195], v[106:109]
	v_mfma_f32_16x16x32_bf16 v[82:85], v[138:141], v[192:195], v[82:85]
	v_mfma_f32_16x16x32_bf16 v[118:121], v[130:133], v[200:203], v[118:121]
	v_mfma_f32_16x16x32_bf16 v[122:125], v[138:141], v[200:203], v[122:125]
	v_mfma_f32_16x16x32_bf16 v[126:129], v[134:137], v[166:169], v[126:129]
	v_mfma_f32_16x16x32_bf16 v[90:93], v[142:145], v[166:169], v[90:93]
	v_mfma_f32_16x16x32_bf16 v[110:113], v[134:137], v[174:177], v[110:113]
	v_mfma_f32_16x16x32_bf16 v[86:89], v[142:145], v[174:177], v[86:89]
	v_mfma_f32_16x16x32_bf16 v[106:109], v[134:137], v[196:199], v[106:109]
	v_mfma_f32_16x16x32_bf16 v[82:85], v[142:145], v[196:199], v[82:85]
	v_mfma_f32_16x16x32_bf16 v[118:121], v[134:137], v[204:207], v[118:121]
	v_mfma_f32_16x16x32_bf16 v[122:125], v[142:145], v[204:207], v[122:125]
	v_mfma_f32_16x16x32_bf16 v[94:97], v[146:149], v[162:165], v[94:97]
	v_mfma_f32_16x16x32_bf16 v[66:69], v[154:157], v[162:165], v[66:69]
	v_mfma_f32_16x16x32_bf16 v[102:105], v[146:149], v[170:173], v[102:105]
	v_mfma_f32_16x16x32_bf16 v[78:81], v[154:157], v[170:173], v[78:81]
	v_mfma_f32_16x16x32_bf16 v[98:101], v[146:149], v[192:195], v[98:101]
	v_mfma_f32_16x16x32_bf16 v[74:77], v[154:157], v[192:195], v[74:77]
	v_mfma_f32_16x16x32_bf16 v[70:73], v[146:149], v[200:203], v[70:73]
	v_mfma_f32_16x16x32_bf16 v[58:61], v[154:157], v[200:203], v[58:61]
	v_mfma_f32_16x16x32_bf16 v[94:97], v[150:153], v[166:169], v[94:97]
	v_mfma_f32_16x16x32_bf16 v[66:69], v[158:161], v[166:169], v[66:69]
	v_mfma_f32_16x16x32_bf16 v[102:105], v[150:153], v[174:177], v[102:105]
	v_mfma_f32_16x16x32_bf16 v[78:81], v[158:161], v[174:177], v[78:81]
	v_mfma_f32_16x16x32_bf16 v[98:101], v[150:153], v[196:199], v[98:101]
	v_mfma_f32_16x16x32_bf16 v[74:77], v[158:161], v[196:199], v[74:77]
	v_mfma_f32_16x16x32_bf16 v[70:73], v[150:153], v[204:207], v[70:73]
	v_mfma_f32_16x16x32_bf16 v[58:61], v[158:161], v[204:207], v[58:61]
	s_barrier
	s_setprio 0
	s_add_i32 s83, s30, s5
	v_lshl_add_u64 v[208:209], s[14:15], 0, v[180:181]
	s_mov_b32 m0, s83
	ds_read_b128 v[162:165], v243 offset:16384
	ds_read_b128 v[166:169], v243 offset:17408
	ds_read_b128 v[170:173], v243 offset:18432
	ds_read_b128 v[174:177], v243 offset:19456
	ds_read_b128 v[192:195], v243 offset:20480
	ds_read_b128 v[196:199], v243 offset:21504
	ds_read_b128 v[200:203], v243 offset:22528
	ds_read_b128 v[204:207], v243 offset:23552
	global_load_lds_dwordx4 v[208:209], off
	s_add_i32 m0, s83, 0x2000
	s_add_u32 vcc_lo, s14, 0x100000
	v_lshl_add_u64 v[210:211], s[14:15], 0, v[184:185]
	s_addc_u32 vcc_hi, s15, 0
	s_add_i32 s83, s86, s5
	global_load_lds_dwordx4 v[210:211], off
	v_lshl_add_u64 v[212:213], vcc, 0, v[180:181]
	s_mov_b32 m0, s83
	v_lshl_add_u64 v[214:215], s[16:17], 0, v[182:183]
	global_load_lds_dwordx4 v[212:213], off
	v_lshl_add_u64 v[212:213], vcc, 0, v[184:185]
	s_add_i32 m0, s83, 0x2000
	s_nop 0
	global_load_lds_dwordx4 v[212:213], off
	v_lshl_add_u64 v[212:213], s[16:17], 0, v[178:179]
	s_mov_b32 m0, s7
	s_nop 0
	global_load_lds_dwordx4 v[212:213], off
	s_mov_b32 m0, s18
	s_nop 0
	global_load_lds_dwordx4 v[214:215], off
	s_waitcnt vmcnt(8)
	s_waitcnt lgkmcnt(0)
	s_setprio 1
	s_barrier
; #define PG8_STAGE(bufoff, gbase, voff) do { _Pragma("unroll") for (int _i = 0; _i < 2; ++_i) \
;         __builtin_amdgcn_global_load_lds((const unsigned*)((const char*)(gbase) + (voff)[_i]), (PG8_LAS unsigned*)(lds + (bufoff) + ldsw + _i * 8192), 16, 0, 0); } while (0)
; #define PG8_LDA(dst, b, h) do { _Pragma("unroll") for (int m = 0; m < 4; ++m) _Pragma("unroll") for (int k = 0; k < 2; ++k) dst[m][k] = *(const PG8_LAS bf16x8*)(lds + PG8_SA(b, h) + aoff + m * 2048 + k * 1024); } while (0)
; #define PG8_LDB(dst, b, h) do { _Pragma("unroll") for (int n = 0; n < 2; ++n) _Pragma("unroll") for (int k = 0; k < 2; ++k) dst[n][k] = *(const PG8_LAS bf16x8*)(lds + PG8_SB(b, h) + boff + n * 2048 + k * 1024); } while (0)
; #define PG8_WAIT_V(n) asm volatile("s_waitcnt vmcnt(" #n ")" ::: "memory")
; #define PG8_WAIT_L(n) asm volatile("s_waitcnt lgkmcnt(" #n ")" ::: "memory")
; #define PG8_BAR __builtin_amdgcn_s_barrier()
; #define PG8_SCHED __builtin_amdgcn_sched_barrier(0)
; template <class Epi, class Sched, bool ALIGN_EPI = false, bool SP2 = false, bool F8 = false>
; __device__ __forceinline__ void gemm_phase(PG8_LAS unsigned char* lds, const Gemm g, const Sched& S, const Epi& E) {
;     ...
;             PG8_WAIT_V(8); PG8_WAIT_L(0); PG8_BAR; PG8_MMA(1, 0, At, B0); PG8_MMA(1, 1, At, B1); PG8_BAR; PG8_SCHED;
;             PG8_LDB(B0, 1, 0); PG8_LDB(B1, 1, 1); PG8_SCHED; PG8_LDA(At, 1, 0); PG8_STAGE(PG8_SA(0, 1), a2 + hA, voffA);
;             PG8_WAIT_V(8); PG8_WAIT_L(0); PG8_BAR; PG8_MMA(0, 0, At, B0); PG8_MMA(0, 1, At, B1); PG8_BAR; PG8_SCHED;
	v_mfma_f32_16x16x32_bf16 v[62:65], v[130:133], v[162:165], v[62:65]
	v_mfma_f32_16x16x32_bf16 v[38:41], v[138:141], v[162:165], v[38:41]
	v_mfma_f32_16x16x32_bf16 v[42:45], v[130:133], v[170:173], v[42:45]
	v_mfma_f32_16x16x32_bf16 v[14:17], v[138:141], v[170:173], v[14:17]
	v_mfma_f32_16x16x32_bf16 v[34:37], v[130:133], v[192:195], v[34:37]
	v_mfma_f32_16x16x32_bf16 v[10:13], v[138:141], v[192:195], v[10:13]
	v_mfma_f32_16x16x32_bf16 v[50:53], v[130:133], v[200:203], v[50:53]
	v_mfma_f32_16x16x32_bf16 v[114:117], v[138:141], v[200:203], v[114:117]
	v_mfma_f32_16x16x32_bf16 v[62:65], v[134:137], v[166:169], v[62:65]
	v_mfma_f32_16x16x32_bf16 v[38:41], v[142:145], v[166:169], v[38:41]
	v_mfma_f32_16x16x32_bf16 v[42:45], v[134:137], v[174:177], v[42:45]
	v_mfma_f32_16x16x32_bf16 v[14:17], v[142:145], v[174:177], v[14:17]
	v_mfma_f32_16x16x32_bf16 v[34:37], v[134:137], v[196:199], v[34:37]
	v_mfma_f32_16x16x32_bf16 v[10:13], v[142:145], v[196:199], v[10:13]
	v_mfma_f32_16x16x32_bf16 v[50:53], v[134:137], v[204:207], v[50:53]
	v_mfma_f32_16x16x32_bf16 v[114:117], v[142:145], v[204:207], v[114:117]
	v_mfma_f32_16x16x32_bf16 v[46:49], v[146:149], v[162:165], v[46:49]
	v_mfma_f32_16x16x32_bf16 v[22:25], v[154:157], v[162:165], v[22:25]
	v_mfma_f32_16x16x32_bf16 v[30:33], v[146:149], v[170:173], v[30:33]
	v_mfma_f32_16x16x32_bf16 v[6:9], v[154:157], v[170:173], v[6:9]
	v_mfma_f32_16x16x32_bf16 v[26:29], v[146:149], v[192:195], v[26:29]
	v_mfma_f32_16x16x32_bf16 v[2:5], v[154:157], v[192:195], v[2:5]
	v_mfma_f32_16x16x32_bf16 v[54:57], v[146:149], v[200:203], v[54:57]
	v_mfma_f32_16x16x32_bf16 v[18:21], v[154:157], v[200:203], v[18:21]
	v_mfma_f32_16x16x32_bf16 v[46:49], v[150:153], v[166:169], v[46:49]
	v_mfma_f32_16x16x32_bf16 v[22:25], v[158:161], v[166:169], v[22:25]
	v_mfma_f32_16x16x32_bf16 v[30:33], v[150:153], v[174:177], v[30:33]
	v_mfma_f32_16x16x32_bf16 v[6:9], v[158:161], v[174:177], v[6:9]
	v_mfma_f32_16x16x32_bf16 v[26:29], v[150:153], v[196:199], v[26:29]
	v_mfma_f32_16x16x32_bf16 v[2:5], v[158:161], v[196:199], v[2:5]
	v_mfma_f32_16x16x32_bf16 v[54:57], v[150:153], v[204:207], v[54:57]
	v_mfma_f32_16x16x32_bf16 v[18:21], v[158:161], v[204:207], v[18:21]
	s_barrier
	s_setprio 0
	s_add_i32 s83, 0, 0x18000
	s_add_i32 vcc_lo, 0, 0x1c000
	v_add_u32_e32 v142, s83, v240
	v_add_u32_e32 v158, vcc_lo, v240
	ds_read_b128 v[130:133], v142
	ds_read_b128 v[134:137], v142 offset:1024
	ds_read_b128 v[138:141], v142 offset:2048
	ds_read_b128 v[142:145], v142 offset:3072
	ds_read_b128 v[146:149], v158
	ds_read_b128 v[150:153], v158 offset:1024
	ds_read_b128 v[154:157], v158 offset:2048
	ds_read_b128 v[158:161], v158 offset:3072
	s_add_u32 s16, s16, 0x100000
	s_addc_u32 s17, s17, 0
	s_mov_b32 m0, s19
	v_lshl_add_u64 v[216:217], s[16:17], 0, v[178:179]
	ds_read_b128 v[162:165], v243 offset:32768
	ds_read_b128 v[166:169], v243 offset:33792
	ds_read_b128 v[170:173], v243 offset:34816
	ds_read_b128 v[174:177], v243 offset:35840
	ds_read_b128 v[192:195], v243 offset:36864
	ds_read_b128 v[196:199], v243 offset:37888
	ds_read_b128 v[200:203], v243 offset:38912
	ds_read_b128 v[204:207], v243 offset:39936
	global_load_lds_dwordx4 v[216:217], off
	v_lshl_add_u64 v[216:217], s[16:17], 0, v[182:183]
	s_mov_b32 m0, s29
	s_nop 0
	global_load_lds_dwordx4 v[216:217], off
	s_waitcnt vmcnt(8)
	s_waitcnt lgkmcnt(0)
	s_setprio 1
	s_barrier
	v_mfma_f32_16x16x32_bf16 v[126:129], v[130:133], v[162:165], v[126:129]
	v_mfma_f32_16x16x32_bf16 v[90:93], v[138:141], v[162:165], v[90:93]
	v_mfma_f32_16x16x32_bf16 v[110:113], v[130:133], v[170:173], v[110:113]
	v_mfma_f32_16x16x32_bf16 v[86:89], v[138:141], v[170:173], v[86:89]
	v_mfma_f32_16x16x32_bf16 v[106:109], v[130:133], v[192:195], v[106:109]
	v_mfma_f32_16x16x32_bf16 v[82:85], v[138:141], v[192:195], v[82:85]
	v_mfma_f32_16x16x32_bf16 v[118:121], v[130:133], v[200:203], v[118:121]
	v_mfma_f32_16x16x32_bf16 v[122:125], v[138:141], v[200:203], v[122:125]
	v_mfma_f32_16x16x32_bf16 v[126:129], v[134:137], v[166:169], v[126:129]
	v_mfma_f32_16x16x32_bf16 v[90:93], v[142:145], v[166:169], v[90:93]
	v_mfma_f32_16x16x32_bf16 v[110:113], v[134:137], v[174:177], v[110:113]
	v_mfma_f32_16x16x32_bf16 v[86:89], v[142:145], v[174:177], v[86:89]
	v_mfma_f32_16x16x32_bf16 v[106:109], v[134:137], v[196:199], v[106:109]
	v_mfma_f32_16x16x32_bf16 v[82:85], v[142:145], v[196:199], v[82:85]
	v_mfma_f32_16x16x32_bf16 v[118:121], v[134:137], v[204:207], v[118:121]
	v_mfma_f32_16x16x32_bf16 v[122:125], v[142:145], v[204:207], v[122:125]
	v_mfma_f32_16x16x32_bf16 v[94:97], v[146:149], v[162:165], v[94:97]
	v_mfma_f32_16x16x32_bf16 v[66:69], v[154:157], v[162:165], v[66:69]
	v_mfma_f32_16x16x32_bf16 v[102:105], v[146:149], v[170:173], v[102:105]
	v_mfma_f32_16x16x32_bf16 v[78:81], v[154:157], v[170:173], v[78:81]
	v_mfma_f32_16x16x32_bf16 v[98:101], v[146:149], v[192:195], v[98:101]
	v_mfma_f32_16x16x32_bf16 v[74:77], v[154:157], v[192:195], v[74:77]
	v_mfma_f32_16x16x32_bf16 v[70:73], v[146:149], v[200:203], v[70:73]
	v_mfma_f32_16x16x32_bf16 v[58:61], v[154:157], v[200:203], v[58:61]
	v_mfma_f32_16x16x32_bf16 v[94:97], v[150:153], v[166:169], v[94:97]
	v_mfma_f32_16x16x32_bf16 v[66:69], v[158:161], v[166:169], v[66:69]
	v_mfma_f32_16x16x32_bf16 v[102:105], v[150:153], v[174:177], v[102:105]
	v_mfma_f32_16x16x32_bf16 v[78:81], v[158:161], v[174:177], v[78:81]
	v_mfma_f32_16x16x32_bf16 v[98:101], v[150:153], v[196:199], v[98:101]
	v_mfma_f32_16x16x32_bf16 v[74:77], v[158:161], v[196:199], v[74:77]
	v_mfma_f32_16x16x32_bf16 v[70:73], v[150:153], v[204:207], v[70:73]
	v_mfma_f32_16x16x32_bf16 v[58:61], v[158:161], v[204:207], v[58:61]
	s_barrier
; #define PG8_STAGE(bufoff, gbase, voff) do { _Pragma("unroll") for (int _i = 0; _i < 2; ++_i) \
;         __builtin_amdgcn_global_load_lds((const unsigned*)((const char*)(gbase) + (voff)[_i]), (PG8_LAS unsigned*)(lds + (bufoff) + ldsw + _i * 8192), 16, 0, 0); } while (0)
; #define PG8_LDA(dst, b, h) do { _Pragma("unroll") for (int m = 0; m < 4; ++m) _Pragma("unroll") for (int k = 0; k < 2; ++k) dst[m][k] = *(const PG8_LAS bf16x8*)(lds + PG8_SA(b, h) + aoff + m * 2048 + k * 1024); } while (0)
; #define PG8_WAIT_V(n) asm volatile("s_waitcnt vmcnt(" #n ")" ::: "memory")
; #define PG8_WAIT_L(n) asm volatile("s_waitcnt lgkmcnt(" #n ")" ::: "memory")
; #define PG8_BAR __builtin_amdgcn_s_barrier()
; #define PG8_SCHED __builtin_amdgcn_sched_barrier(0)
; template <class Epi, class Sched, bool ALIGN_EPI = false, bool SP2 = false, bool F8 = false>
; __device__ __forceinline__ void gemm_phase(PG8_LAS unsigned char* lds, const Gemm g, const Sched& S, const Epi& E) {
;     ...
;             PG8_LDA(At, 1, 1); PG8_STAGE(PG8_SB(1, 0), b3, voffB); PG8_STAGE(PG8_SB(1, 1), b3 + hB, voffB); PG8_STAGE(PG8_SA(1, 0), a3, voffA);
;             PG8_WAIT_V(8); PG8_WAIT_L(0); PG8_BAR; PG8_MMA(1, 0, At, B0); PG8_MMA(1, 1, At, B1); PG8_BAR; PG8_SCHED;
;     ...
;         if constexpr (ALIGN_EPI) { if (wr == 0) PG8_BAR; }
	s_setprio 0
	s_add_i32 s16, s83, s5
	v_lshl_add_u64 v[208:209], v[208:209], 0, s[38:39]
	s_mov_b32 m0, s16
	ds_read_b128 v[162:165], v243 offset:49152
	ds_read_b128 v[166:169], v243 offset:50176
	ds_read_b128 v[170:173], v243 offset:51200
	ds_read_b128 v[174:177], v243 offset:52224
	ds_read_b128 v[192:195], v243 offset:53248
	ds_read_b128 v[196:199], v243 offset:54272
	ds_read_b128 v[200:203], v243 offset:55296
	ds_read_b128 v[204:207], v243 offset:56320
	global_load_lds_dwordx4 v[208:209], off
	s_add_i32 m0, s16, 0x2000
	s_add_u32 s14, s14, 0x100080
	v_lshl_add_u64 v[208:209], v[210:211], 0, s[38:39]
	s_addc_u32 s15, s15, 0
	s_add_i32 s16, vcc_lo, s5
	global_load_lds_dwordx4 v[208:209], off
	v_lshl_add_u64 v[208:209], s[14:15], 0, v[180:181]
	s_mov_b32 m0, s16
	s_nop 0
	global_load_lds_dwordx4 v[208:209], off
	v_lshl_add_u64 v[208:209], s[14:15], 0, v[184:185]
	s_add_i32 m0, s16, 0x2000
	s_nop 0
	global_load_lds_dwordx4 v[208:209], off
	v_lshl_add_u64 v[208:209], v[212:213], 0, s[38:39]
	s_mov_b32 m0, s70
	s_nop 0
	global_load_lds_dwordx4 v[208:209], off
	v_lshl_add_u64 v[208:209], v[214:215], 0, s[38:39]
	s_mov_b32 m0, s71
	s_nop 0
	global_load_lds_dwordx4 v[208:209], off
	s_waitcnt vmcnt(8)
	s_waitcnt lgkmcnt(0)
	s_setprio 1
	s_barrier
	v_mfma_f32_16x16x32_bf16 v[62:65], v[130:133], v[162:165], v[62:65]
	v_mfma_f32_16x16x32_bf16 v[38:41], v[138:141], v[162:165], v[38:41]
	v_mfma_f32_16x16x32_bf16 v[42:45], v[130:133], v[170:173], v[42:45]
	v_mfma_f32_16x16x32_bf16 v[14:17], v[138:141], v[170:173], v[14:17]
	v_mfma_f32_16x16x32_bf16 v[34:37], v[130:133], v[192:195], v[34:37]
	v_mfma_f32_16x16x32_bf16 v[10:13], v[138:141], v[192:195], v[10:13]
	v_mfma_f32_16x16x32_bf16 v[50:53], v[130:133], v[200:203], v[50:53]
	v_mfma_f32_16x16x32_bf16 v[114:117], v[138:141], v[200:203], v[114:117]
	v_mfma_f32_16x16x32_bf16 v[62:65], v[134:137], v[166:169], v[62:65]
	v_mfma_f32_16x16x32_bf16 v[38:41], v[142:145], v[166:169], v[38:41]
	v_mfma_f32_16x16x32_bf16 v[42:45], v[134:137], v[174:177], v[42:45]
	v_mfma_f32_16x16x32_bf16 v[14:17], v[142:145], v[174:177], v[14:17]
	v_mfma_f32_16x16x32_bf16 v[34:37], v[134:137], v[196:199], v[34:37]
	v_mfma_f32_16x16x32_bf16 v[10:13], v[142:145], v[196:199], v[10:13]
	v_mfma_f32_16x16x32_bf16 v[50:53], v[134:137], v[204:207], v[50:53]
	v_mfma_f32_16x16x32_bf16 v[114:117], v[142:145], v[204:207], v[114:117]
	v_mfma_f32_16x16x32_bf16 v[46:49], v[146:149], v[162:165], v[46:49]
	v_mfma_f32_16x16x32_bf16 v[22:25], v[154:157], v[162:165], v[22:25]
	v_mfma_f32_16x16x32_bf16 v[30:33], v[146:149], v[170:173], v[30:33]
	v_mfma_f32_16x16x32_bf16 v[6:9], v[154:157], v[170:173], v[6:9]
	v_mfma_f32_16x16x32_bf16 v[26:29], v[146:149], v[192:195], v[26:29]
	v_mfma_f32_16x16x32_bf16 v[2:5], v[154:157], v[192:195], v[2:5]
	v_mfma_f32_16x16x32_bf16 v[54:57], v[146:149], v[200:203], v[54:57]
	v_mfma_f32_16x16x32_bf16 v[18:21], v[154:157], v[200:203], v[18:21]
	v_mfma_f32_16x16x32_bf16 v[46:49], v[150:153], v[166:169], v[46:49]
	v_mfma_f32_16x16x32_bf16 v[22:25], v[158:161], v[166:169], v[22:25]
	v_mfma_f32_16x16x32_bf16 v[30:33], v[150:153], v[174:177], v[30:33]
	v_mfma_f32_16x16x32_bf16 v[6:9], v[158:161], v[174:177], v[6:9]
	v_mfma_f32_16x16x32_bf16 v[26:29], v[150:153], v[196:199], v[26:29]
	v_mfma_f32_16x16x32_bf16 v[2:5], v[158:161], v[196:199], v[2:5]
	v_mfma_f32_16x16x32_bf16 v[54:57], v[150:153], v[204:207], v[54:57]
	v_mfma_f32_16x16x32_bf16 v[18:21], v[158:161], v[204:207], v[18:21]
	s_barrier
	s_setprio 0
	s_add_i32 s82, s82, 2
	s_add_u32 s80, s80, 0x100
	s_addc_u32 s81, s81, 0
	s_add_u32 s12, s12, 0x100
	s_addc_u32 s13, s13, 0
	s_cmp_gt_u32 s82, 61
	s_cbranch_scc0 .LBB0_825
	s_and_b64 vcc, exec, s[40:41]
	s_cbranch_vccz .LBB0_828
	s_barrier

; #define PG8_STAGE(bufoff, gbase, voff) do { _Pragma("unroll") for (int _i = 0; _i < 2; ++_i) \
;         __builtin_amdgcn_global_load_lds((const unsigned*)((const char*)(gbase) + (voff)[_i]), (PG8_LAS unsigned*)(lds + (bufoff) + ldsw + _i * 8192), 16, 0, 0); } while (0)
; #define PG8_LDA(dst, b, h) do { _Pragma("unroll") for (int m = 0; m < 4; ++m) _Pragma("unroll") for (int k = 0; k < 2; ++k) dst[m][k] = *(const PG8_LAS bf16x8*)(lds + PG8_SA(b, h) + aoff + m * 2048 + k * 1024); } while (0)
; #define PG8_LDB(dst, b, h) do { _Pragma("unroll") for (int n = 0; n < 2; ++n) _Pragma("unroll") for (int k = 0; k < 2; ++k) dst[n][k] = *(const PG8_LAS bf16x8*)(lds + PG8_SB(b, h) + boff + n * 2048 + k * 1024); } while (0)
; #define PG8_WAIT_V(n) asm volatile("s_waitcnt vmcnt(" #n ")" ::: "memory")
; #define PG8_WAIT_L(n) asm volatile("s_waitcnt lgkmcnt(" #n ")" ::: "memory")
; #define PG8_BAR __builtin_amdgcn_s_barrier()
; #define PG8_SCHED __builtin_amdgcn_sched_barrier(0)
; template <class Epi, class Sched, bool ALIGN_EPI = false, bool SP2 = false, bool F8 = false>
; __device__ __forceinline__ void gemm_phase(PG8_LAS unsigned char* lds, const Gemm g, const Sched& S, const Epi& E) {
;     ...
;             PG8_LDB(B0, 0, 0); PG8_LDB(B1, 0, 1); PG8_SCHED; PG8_LDA(At, 0, 0); PG8_STAGE(PG8_SA(1, 1), a1 + hA, voffA);
;             PG8_WAIT_V(8); PG8_WAIT_L(0); PG8_BAR; PG8_MMA(0, 0, At, B0); PG8_MMA(0, 1, At, B1); PG8_BAR; PG8_SCHED;
;             PG8_LDA(At, 0, 1); PG8_STAGE(PG8_SB(0, 0), b2, voffB); PG8_STAGE(PG8_SB(0, 1), b2 + hB, voffB); PG8_STAGE(PG8_SA(0, 0), a2, voffA);
;             PG8_WAIT_V(8); PG8_WAIT_L(0); PG8_BAR; PG8_MMA(1, 0, At, B0); PG8_MMA(1, 1, At, B1); PG8_BAR; PG8_SCHED;
.LBB0_883:
	ds_read_b128 v[130:133], v247
	ds_read_b128 v[134:137], v247 offset:1024
	ds_read_b128 v[138:141], v247 offset:2048
	ds_read_b128 v[142:145], v247 offset:3072
	ds_read_b128 v[146:149], v248
	ds_read_b128 v[150:153], v248 offset:1024
	ds_read_b128 v[154:157], v248 offset:2048
	ds_read_b128 v[158:161], v248 offset:3072
	s_add_u32 s14, s10, 0xfff00080
	s_addc_u32 s15, s11, -1
	s_cmp_eq_u32 s88, 12
	s_cselect_b32 s17, s13, s15
	s_cselect_b32 s16, s77, s14
	s_cselect_b32 s15, s79, s87
	s_cselect_b32 s14, s85, s86
	v_lshl_add_u64 v[212:213], s[10:11], 0, v[194:195]
	s_add_i32 m0, s6, 0xc000
	ds_read_b128 v[162:165], v249
	ds_read_b128 v[166:169], v249 offset:1024
	ds_read_b128 v[170:173], v249 offset:2048
	ds_read_b128 v[174:177], v249 offset:3072
	ds_read_b128 v[178:181], v249 offset:4096
	ds_read_b128 v[200:203], v249 offset:5120
	ds_read_b128 v[204:207], v249 offset:6144
	ds_read_b128 v[208:211], v249 offset:7168
	global_load_lds_dwordx4 v[212:213], off
	v_lshl_add_u64 v[212:213], s[10:11], 0, v[192:193]
	s_add_i32 m0, s6, 0xe000
	s_nop 0
	global_load_lds_dwordx4 v[212:213], off
	s_waitcnt vmcnt(8)
	s_waitcnt lgkmcnt(0)
	s_setprio 1
	s_barrier
	v_mfma_f32_16x16x32_bf16 v[126:129], v[130:133], v[162:165], v[126:129]
	v_mfma_f32_16x16x32_bf16 v[122:125], v[138:141], v[162:165], v[122:125]
	v_mfma_f32_16x16x32_bf16 v[118:121], v[130:133], v[170:173], v[118:121]
	v_mfma_f32_16x16x32_bf16 v[114:117], v[138:141], v[170:173], v[114:117]
	v_mfma_f32_16x16x32_bf16 v[110:113], v[130:133], v[178:181], v[110:113]
	v_mfma_f32_16x16x32_bf16 v[106:109], v[138:141], v[178:181], v[106:109]
	v_mfma_f32_16x16x32_bf16 v[102:105], v[130:133], v[204:207], v[102:105]
	v_mfma_f32_16x16x32_bf16 v[98:101], v[138:141], v[204:207], v[98:101]
	v_mfma_f32_16x16x32_bf16 v[126:129], v[134:137], v[166:169], v[126:129]
	v_mfma_f32_16x16x32_bf16 v[122:125], v[142:145], v[166:169], v[122:125]
	v_mfma_f32_16x16x32_bf16 v[118:121], v[134:137], v[174:177], v[118:121]
	v_mfma_f32_16x16x32_bf16 v[114:117], v[142:145], v[174:177], v[114:117]
	v_mfma_f32_16x16x32_bf16 v[110:113], v[134:137], v[200:203], v[110:113]
	v_mfma_f32_16x16x32_bf16 v[106:109], v[142:145], v[200:203], v[106:109]
	v_mfma_f32_16x16x32_bf16 v[102:105], v[134:137], v[208:211], v[102:105]
	v_mfma_f32_16x16x32_bf16 v[98:101], v[142:145], v[208:211], v[98:101]
	v_mfma_f32_16x16x32_bf16 v[82:85], v[146:149], v[162:165], v[82:85]
	v_mfma_f32_16x16x32_bf16 v[74:77], v[154:157], v[162:165], v[74:77]
	v_mfma_f32_16x16x32_bf16 v[94:97], v[146:149], v[170:173], v[94:97]
	v_mfma_f32_16x16x32_bf16 v[90:93], v[154:157], v[170:173], v[90:93]
	v_mfma_f32_16x16x32_bf16 v[86:89], v[146:149], v[178:181], v[86:89]
	v_mfma_f32_16x16x32_bf16 v[78:81], v[154:157], v[178:181], v[78:81]
	v_mfma_f32_16x16x32_bf16 v[70:73], v[146:149], v[204:207], v[70:73]
	v_mfma_f32_16x16x32_bf16 v[62:65], v[154:157], v[204:207], v[62:65]
	v_mfma_f32_16x16x32_bf16 v[82:85], v[150:153], v[166:169], v[82:85]
	v_mfma_f32_16x16x32_bf16 v[74:77], v[158:161], v[166:169], v[74:77]
	v_mfma_f32_16x16x32_bf16 v[94:97], v[150:153], v[174:177], v[94:97]
	v_mfma_f32_16x16x32_bf16 v[90:93], v[158:161], v[174:177], v[90:93]
	v_mfma_f32_16x16x32_bf16 v[86:89], v[150:153], v[200:203], v[86:89]
	v_mfma_f32_16x16x32_bf16 v[78:81], v[158:161], v[200:203], v[78:81]
	v_mfma_f32_16x16x32_bf16 v[70:73], v[150:153], v[208:211], v[70:73]
	v_mfma_f32_16x16x32_bf16 v[62:65], v[158:161], v[208:211], v[62:65]
	s_barrier
	s_setprio 0
	s_add_i32 s89, s54, s96
	v_lshl_add_u64 v[212:213], s[14:15], 0, v[184:185]
	s_mov_b32 m0, s89
	ds_read_b128 v[162:165], v249 offset:16384
	ds_read_b128 v[166:169], v249 offset:17408
	ds_read_b128 v[170:173], v249 offset:18432
	ds_read_b128 v[174:177], v249 offset:19456
	ds_read_b128 v[178:181], v249 offset:20480
	ds_read_b128 v[200:203], v249 offset:21504
	ds_read_b128 v[204:207], v249 offset:22528
	ds_read_b128 v[208:211], v249 offset:23552
	global_load_lds_dwordx4 v[212:213], off
	s_add_i32 m0, s89, 0x2000
	s_add_u32 s90, s14, 0x100000
	v_lshl_add_u64 v[214:215], s[14:15], 0, v[188:189]
	s_addc_u32 s91, s15, 0
	s_add_i32 s89, s55, s96
	global_load_lds_dwordx4 v[214:215], off
	v_lshl_add_u64 v[216:217], s[90:91], 0, v[184:185]
	s_mov_b32 m0, s89
	v_lshl_add_u64 v[218:219], s[16:17], 0, v[186:187]
	global_load_lds_dwordx4 v[216:217], off
	v_lshl_add_u64 v[216:217], s[90:91], 0, v[188:189]
	s_add_i32 m0, s89, 0x2000
	s_nop 0
	global_load_lds_dwordx4 v[216:217], off
	v_lshl_add_u64 v[216:217], s[16:17], 0, v[182:183]
	s_mov_b32 m0, s6
	s_nop 0
	global_load_lds_dwordx4 v[216:217], off
	s_mov_b32 m0, s7
	s_nop 0
	global_load_lds_dwordx4 v[218:219], off
	s_waitcnt vmcnt(8)
	s_waitcnt lgkmcnt(0)
	s_setprio 1
	s_barrier
; #define PG8_STAGE(bufoff, gbase, voff) do { _Pragma("unroll") for (int _i = 0; _i < 2; ++_i) \
;         __builtin_amdgcn_global_load_lds((const unsigned*)((const char*)(gbase) + (voff)[_i]), (PG8_LAS unsigned*)(lds + (bufoff) + ldsw + _i * 8192), 16, 0, 0); } while (0)
; #define PG8_LDA(dst, b, h) do { _Pragma("unroll") for (int m = 0; m < 4; ++m) _Pragma("unroll") for (int k = 0; k < 2; ++k) dst[m][k] = *(const PG8_LAS bf16x8*)(lds + PG8_SA(b, h) + aoff + m * 2048 + k * 1024); } while (0)
; #define PG8_LDB(dst, b, h) do { _Pragma("unroll") for (int n = 0; n < 2; ++n) _Pragma("unroll") for (int k = 0; k < 2; ++k) dst[n][k] = *(const PG8_LAS bf16x8*)(lds + PG8_SB(b, h) + boff + n * 2048 + k * 1024); } while (0)
; #define PG8_WAIT_V(n) asm volatile("s_waitcnt vmcnt(" #n ")" ::: "memory")
; #define PG8_WAIT_L(n) asm volatile("s_waitcnt lgkmcnt(" #n ")" ::: "memory")
; #define PG8_BAR __builtin_amdgcn_s_barrier()
; #define PG8_SCHED __builtin_amdgcn_sched_barrier(0)
; template <class Epi, class Sched, bool ALIGN_EPI = false, bool SP2 = false, bool F8 = false>
; __device__ __forceinline__ void gemm_phase(PG8_LAS unsigned char* lds, const Gemm g, const Sched& S, const Epi& E) {
;     ...
;             PG8_WAIT_V(8); PG8_WAIT_L(0); PG8_BAR; PG8_MMA(1, 0, At, B0); PG8_MMA(1, 1, At, B1); PG8_BAR; PG8_SCHED;
;             PG8_LDB(B0, 1, 0); PG8_LDB(B1, 1, 1); PG8_SCHED; PG8_LDA(At, 1, 0); PG8_STAGE(PG8_SA(0, 1), a2 + hA, voffA);
;             PG8_WAIT_V(8); PG8_WAIT_L(0); PG8_BAR; PG8_MMA(0, 0, At, B0); PG8_MMA(0, 1, At, B1); PG8_BAR; PG8_SCHED;
	v_mfma_f32_16x16x32_bf16 v[66:69], v[130:133], v[162:165], v[66:69]
	v_mfma_f32_16x16x32_bf16 v[58:61], v[138:141], v[162:165], v[58:61]
	v_mfma_f32_16x16x32_bf16 v[54:57], v[130:133], v[170:173], v[54:57]
	v_mfma_f32_16x16x32_bf16 v[50:53], v[138:141], v[170:173], v[50:53]
	v_mfma_f32_16x16x32_bf16 v[46:49], v[130:133], v[178:181], v[46:49]
	v_mfma_f32_16x16x32_bf16 v[42:45], v[138:141], v[178:181], v[42:45]
	v_mfma_f32_16x16x32_bf16 v[38:41], v[130:133], v[204:207], v[38:41]
	v_mfma_f32_16x16x32_bf16 v[34:37], v[138:141], v[204:207], v[34:37]
	v_mfma_f32_16x16x32_bf16 v[66:69], v[134:137], v[166:169], v[66:69]
	v_mfma_f32_16x16x32_bf16 v[58:61], v[142:145], v[166:169], v[58:61]
	v_mfma_f32_16x16x32_bf16 v[54:57], v[134:137], v[174:177], v[54:57]
	v_mfma_f32_16x16x32_bf16 v[50:53], v[142:145], v[174:177], v[50:53]
	v_mfma_f32_16x16x32_bf16 v[46:49], v[134:137], v[200:203], v[46:49]
	v_mfma_f32_16x16x32_bf16 v[42:45], v[142:145], v[200:203], v[42:45]
	v_mfma_f32_16x16x32_bf16 v[38:41], v[134:137], v[208:211], v[38:41]
	v_mfma_f32_16x16x32_bf16 v[34:37], v[142:145], v[208:211], v[34:37]
	v_mfma_f32_16x16x32_bf16 v[30:33], v[146:149], v[162:165], v[30:33]
	v_mfma_f32_16x16x32_bf16 v[18:21], v[154:157], v[162:165], v[18:21]
	v_mfma_f32_16x16x32_bf16 v[26:29], v[146:149], v[170:173], v[26:29]
	v_mfma_f32_16x16x32_bf16 v[22:25], v[154:157], v[170:173], v[22:25]
	v_mfma_f32_16x16x32_bf16 v[14:17], v[146:149], v[178:181], v[14:17]
	v_mfma_f32_16x16x32_bf16 v[10:13], v[154:157], v[178:181], v[10:13]
	v_mfma_f32_16x16x32_bf16 v[6:9], v[146:149], v[204:207], v[6:9]
	v_mfma_f32_16x16x32_bf16 v[2:5], v[154:157], v[204:207], v[2:5]
	v_mfma_f32_16x16x32_bf16 v[30:33], v[150:153], v[166:169], v[30:33]
	v_mfma_f32_16x16x32_bf16 v[18:21], v[158:161], v[166:169], v[18:21]
	v_mfma_f32_16x16x32_bf16 v[26:29], v[150:153], v[174:177], v[26:29]
	v_mfma_f32_16x16x32_bf16 v[22:25], v[158:161], v[174:177], v[22:25]
	v_mfma_f32_16x16x32_bf16 v[14:17], v[150:153], v[200:203], v[14:17]
	v_mfma_f32_16x16x32_bf16 v[10:13], v[158:161], v[200:203], v[10:13]
	v_mfma_f32_16x16x32_bf16 v[6:9], v[150:153], v[208:211], v[6:9]
	v_mfma_f32_16x16x32_bf16 v[2:5], v[158:161], v[208:211], v[2:5]
	s_barrier
	s_setprio 0
	s_add_i32 s89, 0, 0x18000
	s_add_i32 s90, 0, 0x1c000
	v_add_u32_e32 v142, s89, v245
	v_add_u32_e32 v158, s90, v245
	ds_read_b128 v[130:133], v142
	ds_read_b128 v[134:137], v142 offset:1024
	ds_read_b128 v[138:141], v142 offset:2048
	ds_read_b128 v[142:145], v142 offset:3072
	ds_read_b128 v[146:149], v158
	ds_read_b128 v[150:153], v158 offset:1024
	ds_read_b128 v[154:157], v158 offset:2048
	ds_read_b128 v[158:161], v158 offset:3072
	s_add_u32 s16, s16, 0x100000
	s_addc_u32 s17, s17, 0
	s_mov_b32 m0, s5
	v_lshl_add_u64 v[220:221], s[16:17], 0, v[182:183]
	ds_read_b128 v[162:165], v249 offset:32768
	ds_read_b128 v[166:169], v249 offset:33792
	ds_read_b128 v[170:173], v249 offset:34816
	ds_read_b128 v[174:177], v249 offset:35840
	ds_read_b128 v[178:181], v249 offset:36864
	ds_read_b128 v[200:203], v249 offset:37888
	ds_read_b128 v[204:207], v249 offset:38912
	ds_read_b128 v[208:211], v249 offset:39936
	global_load_lds_dwordx4 v[220:221], off
	v_lshl_add_u64 v[220:221], s[16:17], 0, v[186:187]
	s_mov_b32 m0, s18
	s_nop 0
	global_load_lds_dwordx4 v[220:221], off
	s_waitcnt vmcnt(8)
	s_waitcnt lgkmcnt(0)
	s_setprio 1
	s_barrier
	v_mfma_f32_16x16x32_bf16 v[126:129], v[130:133], v[162:165], v[126:129]
	v_mfma_f32_16x16x32_bf16 v[122:125], v[138:141], v[162:165], v[122:125]
	v_mfma_f32_16x16x32_bf16 v[118:121], v[130:133], v[170:173], v[118:121]
	v_mfma_f32_16x16x32_bf16 v[114:117], v[138:141], v[170:173], v[114:117]
	v_mfma_f32_16x16x32_bf16 v[110:113], v[130:133], v[178:181], v[110:113]
	v_mfma_f32_16x16x32_bf16 v[106:109], v[138:141], v[178:181], v[106:109]
	v_mfma_f32_16x16x32_bf16 v[102:105], v[130:133], v[204:207], v[102:105]
	v_mfma_f32_16x16x32_bf16 v[98:101], v[138:141], v[204:207], v[98:101]
	v_mfma_f32_16x16x32_bf16 v[126:129], v[134:137], v[166:169], v[126:129]
	v_mfma_f32_16x16x32_bf16 v[122:125], v[142:145], v[166:169], v[122:125]
	v_mfma_f32_16x16x32_bf16 v[118:121], v[134:137], v[174:177], v[118:121]
	v_mfma_f32_16x16x32_bf16 v[114:117], v[142:145], v[174:177], v[114:117]
	v_mfma_f32_16x16x32_bf16 v[110:113], v[134:137], v[200:203], v[110:113]
	v_mfma_f32_16x16x32_bf16 v[106:109], v[142:145], v[200:203], v[106:109]
	v_mfma_f32_16x16x32_bf16 v[102:105], v[134:137], v[208:211], v[102:105]
	v_mfma_f32_16x16x32_bf16 v[98:101], v[142:145], v[208:211], v[98:101]
	v_mfma_f32_16x16x32_bf16 v[82:85], v[146:149], v[162:165], v[82:85]
	v_mfma_f32_16x16x32_bf16 v[74:77], v[154:157], v[162:165], v[74:77]
	v_mfma_f32_16x16x32_bf16 v[94:97], v[146:149], v[170:173], v[94:97]
	v_mfma_f32_16x16x32_bf16 v[90:93], v[154:157], v[170:173], v[90:93]
	v_mfma_f32_16x16x32_bf16 v[86:89], v[146:149], v[178:181], v[86:89]
	v_mfma_f32_16x16x32_bf16 v[78:81], v[154:157], v[178:181], v[78:81]
	v_mfma_f32_16x16x32_bf16 v[70:73], v[146:149], v[204:207], v[70:73]
	v_mfma_f32_16x16x32_bf16 v[62:65], v[154:157], v[204:207], v[62:65]
	v_mfma_f32_16x16x32_bf16 v[82:85], v[150:153], v[166:169], v[82:85]
	v_mfma_f32_16x16x32_bf16 v[74:77], v[158:161], v[166:169], v[74:77]
	v_mfma_f32_16x16x32_bf16 v[94:97], v[150:153], v[174:177], v[94:97]
	v_mfma_f32_16x16x32_bf16 v[90:93], v[158:161], v[174:177], v[90:93]
	v_mfma_f32_16x16x32_bf16 v[86:89], v[150:153], v[200:203], v[86:89]
	v_mfma_f32_16x16x32_bf16 v[78:81], v[158:161], v[200:203], v[78:81]
	v_mfma_f32_16x16x32_bf16 v[70:73], v[150:153], v[208:211], v[70:73]
	v_mfma_f32_16x16x32_bf16 v[62:65], v[158:161], v[208:211], v[62:65]
	s_barrier
; #define PG8_STAGE(bufoff, gbase, voff) do { _Pragma("unroll") for (int _i = 0; _i < 2; ++_i) \
;         __builtin_amdgcn_global_load_lds((const unsigned*)((const char*)(gbase) + (voff)[_i]), (PG8_LAS unsigned*)(lds + (bufoff) + ldsw + _i * 8192), 16, 0, 0); } while (0)
; #define PG8_LDA(dst, b, h) do { _Pragma("unroll") for (int m = 0; m < 4; ++m) _Pragma("unroll") for (int k = 0; k < 2; ++k) dst[m][k] = *(const PG8_LAS bf16x8*)(lds + PG8_SA(b, h) + aoff + m * 2048 + k * 1024); } while (0)
; #define PG8_WAIT_V(n) asm volatile("s_waitcnt vmcnt(" #n ")" ::: "memory")
; #define PG8_WAIT_L(n) asm volatile("s_waitcnt lgkmcnt(" #n ")" ::: "memory")
; #define PG8_BAR __builtin_amdgcn_s_barrier()
; #define PG8_SCHED __builtin_amdgcn_sched_barrier(0)
; template <class Epi, class Sched, bool ALIGN_EPI = false, bool SP2 = false, bool F8 = false>
; __device__ __forceinline__ void gemm_phase(PG8_LAS unsigned char* lds, const Gemm g, const Sched& S, const Epi& E) {
;     ...
;             PG8_LDA(At, 1, 1); PG8_STAGE(PG8_SB(1, 0), b3, voffB); PG8_STAGE(PG8_SB(1, 1), b3 + hB, voffB); PG8_STAGE(PG8_SA(1, 0), a3, voffA);
;             PG8_WAIT_V(8); PG8_WAIT_L(0); PG8_BAR; PG8_MMA(1, 0, At, B0); PG8_MMA(1, 1, At, B1); PG8_BAR; PG8_SCHED;
;     ...
;         if constexpr (ALIGN_EPI) { if (wr == 0) PG8_BAR; }
	s_setprio 0
	s_add_i32 s16, s89, s96
	v_lshl_add_u64 v[212:213], v[212:213], 0, s[34:35]
	s_mov_b32 m0, s16
	ds_read_b128 v[162:165], v249 offset:49152
	ds_read_b128 v[166:169], v249 offset:50176
	ds_read_b128 v[170:173], v249 offset:51200
	ds_read_b128 v[174:177], v249 offset:52224
	ds_read_b128 v[178:181], v249 offset:53248
	ds_read_b128 v[200:203], v249 offset:54272
	ds_read_b128 v[204:207], v249 offset:55296
	ds_read_b128 v[208:211], v249 offset:56320
	global_load_lds_dwordx4 v[212:213], off
	s_add_i32 m0, s16, 0x2000
	s_add_u32 s14, s14, 0x100080
	v_lshl_add_u64 v[212:213], v[214:215], 0, s[34:35]
	s_addc_u32 s15, s15, 0
	s_add_i32 s16, s90, s96
	global_load_lds_dwordx4 v[212:213], off
	v_lshl_add_u64 v[212:213], s[14:15], 0, v[184:185]
	s_mov_b32 m0, s16
	s_nop 0
	global_load_lds_dwordx4 v[212:213], off
	v_lshl_add_u64 v[212:213], s[14:15], 0, v[188:189]
	s_add_i32 m0, s16, 0x2000
	s_nop 0
	global_load_lds_dwordx4 v[212:213], off
	v_lshl_add_u64 v[212:213], v[216:217], 0, s[34:35]
	s_mov_b32 m0, s31
	s_nop 0
	global_load_lds_dwordx4 v[212:213], off
	v_lshl_add_u64 v[212:213], v[218:219], 0, s[34:35]
	s_mov_b32 m0, s50
	s_nop 0
	global_load_lds_dwordx4 v[212:213], off
	s_waitcnt vmcnt(8)
	s_waitcnt lgkmcnt(0)
	s_setprio 1
	s_barrier
	v_mfma_f32_16x16x32_bf16 v[66:69], v[130:133], v[162:165], v[66:69]
	v_mfma_f32_16x16x32_bf16 v[58:61], v[138:141], v[162:165], v[58:61]
	v_mfma_f32_16x16x32_bf16 v[54:57], v[130:133], v[170:173], v[54:57]
	v_mfma_f32_16x16x32_bf16 v[50:53], v[138:141], v[170:173], v[50:53]
	v_mfma_f32_16x16x32_bf16 v[46:49], v[130:133], v[178:181], v[46:49]
	v_mfma_f32_16x16x32_bf16 v[42:45], v[138:141], v[178:181], v[42:45]
	v_mfma_f32_16x16x32_bf16 v[38:41], v[130:133], v[204:207], v[38:41]
	v_mfma_f32_16x16x32_bf16 v[34:37], v[138:141], v[204:207], v[34:37]
	v_mfma_f32_16x16x32_bf16 v[66:69], v[134:137], v[166:169], v[66:69]
	v_mfma_f32_16x16x32_bf16 v[58:61], v[142:145], v[166:169], v[58:61]
	v_mfma_f32_16x16x32_bf16 v[54:57], v[134:137], v[174:177], v[54:57]
	v_mfma_f32_16x16x32_bf16 v[50:53], v[142:145], v[174:177], v[50:53]
	v_mfma_f32_16x16x32_bf16 v[46:49], v[134:137], v[200:203], v[46:49]
	v_mfma_f32_16x16x32_bf16 v[42:45], v[142:145], v[200:203], v[42:45]
	v_mfma_f32_16x16x32_bf16 v[38:41], v[134:137], v[208:211], v[38:41]
	v_mfma_f32_16x16x32_bf16 v[34:37], v[142:145], v[208:211], v[34:37]
	v_mfma_f32_16x16x32_bf16 v[30:33], v[146:149], v[162:165], v[30:33]
	v_mfma_f32_16x16x32_bf16 v[18:21], v[154:157], v[162:165], v[18:21]
	v_mfma_f32_16x16x32_bf16 v[26:29], v[146:149], v[170:173], v[26:29]
	v_mfma_f32_16x16x32_bf16 v[22:25], v[154:157], v[170:173], v[22:25]
	v_mfma_f32_16x16x32_bf16 v[14:17], v[146:149], v[178:181], v[14:17]
	v_mfma_f32_16x16x32_bf16 v[10:13], v[154:157], v[178:181], v[10:13]
	v_mfma_f32_16x16x32_bf16 v[6:9], v[146:149], v[204:207], v[6:9]
	v_mfma_f32_16x16x32_bf16 v[2:5], v[154:157], v[204:207], v[2:5]
	v_mfma_f32_16x16x32_bf16 v[30:33], v[150:153], v[166:169], v[30:33]
	v_mfma_f32_16x16x32_bf16 v[18:21], v[158:161], v[166:169], v[18:21]
	v_mfma_f32_16x16x32_bf16 v[26:29], v[150:153], v[174:177], v[26:29]
	v_mfma_f32_16x16x32_bf16 v[22:25], v[158:161], v[174:177], v[22:25]
	v_mfma_f32_16x16x32_bf16 v[14:17], v[150:153], v[200:203], v[14:17]
	v_mfma_f32_16x16x32_bf16 v[10:13], v[158:161], v[200:203], v[10:13]
	v_mfma_f32_16x16x32_bf16 v[6:9], v[150:153], v[208:211], v[6:9]
	v_mfma_f32_16x16x32_bf16 v[2:5], v[158:161], v[208:211], v[2:5]
	s_barrier
	s_setprio 0
	s_add_i32 s88, s88, 2
	s_add_u32 s86, s86, 0x100
	s_addc_u32 s87, s87, 0
	s_add_u32 s10, s10, 0x100
	s_addc_u32 s11, s11, 0
	s_cmp_gt_u32 s88, 13
	s_cbranch_scc0 .LBB0_883
	s_and_b64 vcc, exec, s[36:37]
	s_cbranch_vccz .LBB0_886
	s_barrier

; #define PG8_STAGE(bufoff, gbase, voff) do { _Pragma("unroll") for (int _i = 0; _i < 2; ++_i) \
;         __builtin_amdgcn_global_load_lds((const unsigned*)((const char*)(gbase) + (voff)[_i]), (PG8_LAS unsigned*)(lds + (bufoff) + ldsw + _i * 8192), 16, 0, 0); } while (0)
; #define PG8_LDA(dst, b, h) do { _Pragma("unroll") for (int m = 0; m < 4; ++m) _Pragma("unroll") for (int k = 0; k < 2; ++k) dst[m][k] = *(const PG8_LAS bf16x8*)(lds + PG8_SA(b, h) + aoff + m * 2048 + k * 1024); } while (0)
; #define PG8_LDB(dst, b, h) do { _Pragma("unroll") for (int n = 0; n < 2; ++n) _Pragma("unroll") for (int k = 0; k < 2; ++k) dst[n][k] = *(const PG8_LAS bf16x8*)(lds + PG8_SB(b, h) + boff + n * 2048 + k * 1024); } while (0)
; #define PG8_WAIT_V(n) asm volatile("s_waitcnt vmcnt(" #n ")" ::: "memory")
; #define PG8_WAIT_L(n) asm volatile("s_waitcnt lgkmcnt(" #n ")" ::: "memory")
; #define PG8_BAR __builtin_amdgcn_s_barrier()
; #define PG8_SCHED __builtin_amdgcn_sched_barrier(0)
; template <class Epi, class Sched, bool ALIGN_EPI = false, bool SP2 = false, bool F8 = false>
; __device__ __forceinline__ void gemm_phase(PG8_LAS unsigned char* lds, const Gemm g, const Sched& S, const Epi& E) {
;     ...
;             PG8_LDB(B0, 0, 0); PG8_LDB(B1, 0, 1); PG8_SCHED; PG8_LDA(At, 0, 0); PG8_STAGE(PG8_SA(1, 1), a1 + hA, voffA);
;             PG8_WAIT_V(8); PG8_WAIT_L(0); PG8_BAR; PG8_MMA(0, 0, At, B0); PG8_MMA(0, 1, At, B1); PG8_BAR; PG8_SCHED;
;             PG8_LDA(At, 0, 1); PG8_STAGE(PG8_SB(0, 0), b2, voffB); PG8_STAGE(PG8_SB(0, 1), b2 + hB, voffB); PG8_STAGE(PG8_SA(0, 0), a2, voffA);
;             PG8_WAIT_V(8); PG8_WAIT_L(0); PG8_BAR; PG8_MMA(1, 0, At, B0); PG8_MMA(1, 1, At, B1); PG8_BAR; PG8_SCHED;
.LBB0_1078:
	ds_read_b128 v[130:133], v197
	ds_read_b128 v[134:137], v197 offset:1024
	ds_read_b128 v[138:141], v197 offset:2048
	ds_read_b128 v[142:145], v197 offset:3072
	ds_read_b128 v[146:149], v198
	ds_read_b128 v[150:153], v198 offset:1024
	ds_read_b128 v[154:157], v198 offset:2048
	ds_read_b128 v[158:161], v198 offset:3072
	s_add_u32 s28, s26, 0x100
	s_addc_u32 s29, s27, 0
	s_cmpk_eq_i32 s55, 0xa8
	s_cselect_b32 s35, s7, s29
	s_cselect_b32 s34, s6, s28
	s_cselect_b32 s31, s9, s54
	s_cselect_b32 s30, s8, s53
	v_lshl_add_u64 v[216:217], s[26:27], 0, v[176:177]
	s_add_i32 m0, s39, 0xc000
	ds_read_b128 v[162:165], v199
	ds_read_b128 v[182:185], v199 offset:1024
	ds_read_b128 v[186:189], v199 offset:2048
	ds_read_b128 v[190:193], v199 offset:3072
	ds_read_b128 v[200:203], v199 offset:4096
	ds_read_b128 v[204:207], v199 offset:5120
	ds_read_b128 v[208:211], v199 offset:6144
	ds_read_b128 v[212:215], v199 offset:7168
	global_load_lds_dwordx4 v[216:217], off
	v_lshl_add_u64 v[216:217], s[26:27], 0, v[174:175]
	s_add_i32 m0, s39, 0xe000
	s_nop 0
	global_load_lds_dwordx4 v[216:217], off
	s_waitcnt vmcnt(8)
	s_waitcnt lgkmcnt(0)
	s_setprio 1
	s_barrier
	v_mfma_f32_16x16x32_bf16 v[126:129], v[130:133], v[162:165], v[126:129]
	v_mfma_f32_16x16x32_bf16 v[122:125], v[138:141], v[162:165], v[122:125]
	v_mfma_f32_16x16x32_bf16 v[118:121], v[130:133], v[186:189], v[118:121]
	v_mfma_f32_16x16x32_bf16 v[106:109], v[138:141], v[186:189], v[106:109]
	v_mfma_f32_16x16x32_bf16 v[98:101], v[130:133], v[200:203], v[98:101]
	v_mfma_f32_16x16x32_bf16 v[90:93], v[138:141], v[200:203], v[90:93]
	v_mfma_f32_16x16x32_bf16 v[82:85], v[130:133], v[208:211], v[82:85]
	v_mfma_f32_16x16x32_bf16 v[74:77], v[138:141], v[208:211], v[74:77]
	v_mfma_f32_16x16x32_bf16 v[126:129], v[134:137], v[182:185], v[126:129]
	v_mfma_f32_16x16x32_bf16 v[122:125], v[142:145], v[182:185], v[122:125]
	v_mfma_f32_16x16x32_bf16 v[118:121], v[134:137], v[190:193], v[118:121]
	v_mfma_f32_16x16x32_bf16 v[106:109], v[142:145], v[190:193], v[106:109]
	v_mfma_f32_16x16x32_bf16 v[98:101], v[134:137], v[204:207], v[98:101]
	v_mfma_f32_16x16x32_bf16 v[90:93], v[142:145], v[204:207], v[90:93]
	v_mfma_f32_16x16x32_bf16 v[82:85], v[134:137], v[212:215], v[82:85]
	v_mfma_f32_16x16x32_bf16 v[74:77], v[142:145], v[212:215], v[74:77]
	v_mfma_f32_16x16x32_bf16 v[114:117], v[146:149], v[162:165], v[114:117]
	v_mfma_f32_16x16x32_bf16 v[110:113], v[154:157], v[162:165], v[110:113]
	v_mfma_f32_16x16x32_bf16 v[102:105], v[146:149], v[186:189], v[102:105]
	v_mfma_f32_16x16x32_bf16 v[94:97], v[154:157], v[186:189], v[94:97]
	v_mfma_f32_16x16x32_bf16 v[86:89], v[146:149], v[200:203], v[86:89]
	v_mfma_f32_16x16x32_bf16 v[78:81], v[154:157], v[200:203], v[78:81]
	v_mfma_f32_16x16x32_bf16 v[70:73], v[146:149], v[208:211], v[70:73]
	v_mfma_f32_16x16x32_bf16 v[66:69], v[154:157], v[208:211], v[66:69]
	v_mfma_f32_16x16x32_bf16 v[114:117], v[150:153], v[182:185], v[114:117]
	v_mfma_f32_16x16x32_bf16 v[110:113], v[158:161], v[182:185], v[110:113]
	v_mfma_f32_16x16x32_bf16 v[102:105], v[150:153], v[190:193], v[102:105]
	v_mfma_f32_16x16x32_bf16 v[94:97], v[158:161], v[190:193], v[94:97]
	v_mfma_f32_16x16x32_bf16 v[86:89], v[150:153], v[204:207], v[86:89]
	v_mfma_f32_16x16x32_bf16 v[78:81], v[158:161], v[204:207], v[78:81]
	v_mfma_f32_16x16x32_bf16 v[70:73], v[150:153], v[212:215], v[70:73]
	v_mfma_f32_16x16x32_bf16 v[66:69], v[158:161], v[212:215], v[66:69]
	s_barrier
	s_setprio 0
	s_add_i32 s26, s47, s36
	v_lshl_add_u64 v[216:217], s[30:31], 0, v[170:171]
	s_mov_b32 m0, s26
	ds_read_b128 v[162:165], v199 offset:16384
	ds_read_b128 v[182:185], v199 offset:17408
	ds_read_b128 v[186:189], v199 offset:18432
	ds_read_b128 v[190:193], v199 offset:19456
	ds_read_b128 v[200:203], v199 offset:20480
	ds_read_b128 v[204:207], v199 offset:21504
	ds_read_b128 v[208:211], v199 offset:22528
	ds_read_b128 v[212:215], v199 offset:23552
	global_load_lds_dwordx4 v[216:217], off
	s_add_i32 m0, s26, 0x2000
	s_add_u32 s26, s30, 0x2b0000
	v_lshl_add_u64 v[218:219], s[30:31], 0, v[166:167]
	s_addc_u32 s27, s31, 0
	s_add_i32 s56, s48, s36
	global_load_lds_dwordx4 v[218:219], off
	v_lshl_add_u64 v[220:221], s[26:27], 0, v[170:171]
	s_mov_b32 m0, s56
	v_lshl_add_u64 v[222:223], s[34:35], 0, v[168:169]
	global_load_lds_dwordx4 v[220:221], off
	v_lshl_add_u64 v[220:221], s[26:27], 0, v[166:167]
	s_add_i32 m0, s56, 0x2000
	s_nop 0
	global_load_lds_dwordx4 v[220:221], off
	v_lshl_add_u64 v[220:221], s[34:35], 0, v[172:173]
	s_mov_b32 m0, s39
	s_nop 0
	global_load_lds_dwordx4 v[220:221], off
	s_mov_b32 m0, s40
	s_nop 0
	global_load_lds_dwordx4 v[222:223], off
	s_waitcnt vmcnt(8)
	s_waitcnt lgkmcnt(0)
	s_setprio 1
	s_barrier
; #define PG8_STAGE(bufoff, gbase, voff) do { _Pragma("unroll") for (int _i = 0; _i < 2; ++_i) \
;         __builtin_amdgcn_global_load_lds((const unsigned*)((const char*)(gbase) + (voff)[_i]), (PG8_LAS unsigned*)(lds + (bufoff) + ldsw + _i * 8192), 16, 0, 0); } while (0)
; #define PG8_LDA(dst, b, h) do { _Pragma("unroll") for (int m = 0; m < 4; ++m) _Pragma("unroll") for (int k = 0; k < 2; ++k) dst[m][k] = *(const PG8_LAS bf16x8*)(lds + PG8_SA(b, h) + aoff + m * 2048 + k * 1024); } while (0)
; #define PG8_LDB(dst, b, h) do { _Pragma("unroll") for (int n = 0; n < 2; ++n) _Pragma("unroll") for (int k = 0; k < 2; ++k) dst[n][k] = *(const PG8_LAS bf16x8*)(lds + PG8_SB(b, h) + boff + n * 2048 + k * 1024); } while (0)
; #define PG8_WAIT_V(n) asm volatile("s_waitcnt vmcnt(" #n ")" ::: "memory")
; #define PG8_WAIT_L(n) asm volatile("s_waitcnt lgkmcnt(" #n ")" ::: "memory")
; #define PG8_BAR __builtin_amdgcn_s_barrier()
; #define PG8_SCHED __builtin_amdgcn_sched_barrier(0)
; template <class Epi, class Sched, bool ALIGN_EPI = false, bool SP2 = false, bool F8 = false>
; __device__ __forceinline__ void gemm_phase(PG8_LAS unsigned char* lds, const Gemm g, const Sched& S, const Epi& E) {
;     ...
;             PG8_WAIT_V(8); PG8_WAIT_L(0); PG8_BAR; PG8_MMA(1, 0, At, B0); PG8_MMA(1, 1, At, B1); PG8_BAR; PG8_SCHED;
;             PG8_LDB(B0, 1, 0); PG8_LDB(B1, 1, 1); PG8_SCHED; PG8_LDA(At, 1, 0); PG8_STAGE(PG8_SA(0, 1), a2 + hA, voffA);
;             PG8_WAIT_V(8); PG8_WAIT_L(0); PG8_BAR; PG8_MMA(0, 0, At, B0); PG8_MMA(0, 1, At, B1); PG8_BAR; PG8_SCHED;
	v_mfma_f32_16x16x32_bf16 v[62:65], v[130:133], v[162:165], v[62:65]
	v_mfma_f32_16x16x32_bf16 v[58:61], v[138:141], v[162:165], v[58:61]
	v_mfma_f32_16x16x32_bf16 v[50:53], v[130:133], v[186:189], v[50:53]
	v_mfma_f32_16x16x32_bf16 v[42:45], v[138:141], v[186:189], v[42:45]
	v_mfma_f32_16x16x32_bf16 v[34:37], v[130:133], v[200:203], v[34:37]
	v_mfma_f32_16x16x32_bf16 v[26:29], v[138:141], v[200:203], v[26:29]
	v_mfma_f32_16x16x32_bf16 v[18:21], v[130:133], v[208:211], v[18:21]
	v_mfma_f32_16x16x32_bf16 v[10:13], v[138:141], v[208:211], v[10:13]
	v_mfma_f32_16x16x32_bf16 v[62:65], v[134:137], v[182:185], v[62:65]
	v_mfma_f32_16x16x32_bf16 v[58:61], v[142:145], v[182:185], v[58:61]
	v_mfma_f32_16x16x32_bf16 v[50:53], v[134:137], v[190:193], v[50:53]
	v_mfma_f32_16x16x32_bf16 v[42:45], v[142:145], v[190:193], v[42:45]
	v_mfma_f32_16x16x32_bf16 v[34:37], v[134:137], v[204:207], v[34:37]
	v_mfma_f32_16x16x32_bf16 v[26:29], v[142:145], v[204:207], v[26:29]
	v_mfma_f32_16x16x32_bf16 v[18:21], v[134:137], v[212:215], v[18:21]
	v_mfma_f32_16x16x32_bf16 v[10:13], v[142:145], v[212:215], v[10:13]
	v_mfma_f32_16x16x32_bf16 v[54:57], v[146:149], v[162:165], v[54:57]
	v_mfma_f32_16x16x32_bf16 v[46:49], v[154:157], v[162:165], v[46:49]
	v_mfma_f32_16x16x32_bf16 v[38:41], v[146:149], v[186:189], v[38:41]
	v_mfma_f32_16x16x32_bf16 v[30:33], v[154:157], v[186:189], v[30:33]
	v_mfma_f32_16x16x32_bf16 v[22:25], v[146:149], v[200:203], v[22:25]
	v_mfma_f32_16x16x32_bf16 v[14:17], v[154:157], v[200:203], v[14:17]
	v_mfma_f32_16x16x32_bf16 v[6:9], v[146:149], v[208:211], v[6:9]
	v_mfma_f32_16x16x32_bf16 v[2:5], v[154:157], v[208:211], v[2:5]
	v_mfma_f32_16x16x32_bf16 v[54:57], v[150:153], v[182:185], v[54:57]
	v_mfma_f32_16x16x32_bf16 v[46:49], v[158:161], v[182:185], v[46:49]
	v_mfma_f32_16x16x32_bf16 v[38:41], v[150:153], v[190:193], v[38:41]
	v_mfma_f32_16x16x32_bf16 v[30:33], v[158:161], v[190:193], v[30:33]
	v_mfma_f32_16x16x32_bf16 v[22:25], v[150:153], v[204:207], v[22:25]
	v_mfma_f32_16x16x32_bf16 v[14:17], v[158:161], v[204:207], v[14:17]
	v_mfma_f32_16x16x32_bf16 v[6:9], v[150:153], v[212:215], v[6:9]
	v_mfma_f32_16x16x32_bf16 v[2:5], v[158:161], v[212:215], v[2:5]
	s_barrier
	s_setprio 0
	s_add_i32 s56, 0, 0x18000
	s_add_i32 s57, 0, 0x1c000
	v_add_u32_e32 v142, s56, v195
	v_add_u32_e32 v158, s57, v195
	ds_read_b128 v[130:133], v142
	ds_read_b128 v[134:137], v142 offset:1024
	ds_read_b128 v[138:141], v142 offset:2048
	ds_read_b128 v[142:145], v142 offset:3072
	ds_read_b128 v[146:149], v158
	ds_read_b128 v[150:153], v158 offset:1024
	ds_read_b128 v[154:157], v158 offset:2048
	ds_read_b128 v[158:161], v158 offset:3072
	s_add_u32 s26, s34, 0x2b0000
	s_addc_u32 s27, s35, 0
	s_mov_b32 m0, s41
	v_lshl_add_u64 v[224:225], s[26:27], 0, v[172:173]
	ds_read_b128 v[162:165], v199 offset:32768
	ds_read_b128 v[182:185], v199 offset:33792
	ds_read_b128 v[186:189], v199 offset:34816
	ds_read_b128 v[190:193], v199 offset:35840
	ds_read_b128 v[200:203], v199 offset:36864
	ds_read_b128 v[204:207], v199 offset:37888
	ds_read_b128 v[208:211], v199 offset:38912
	ds_read_b128 v[212:215], v199 offset:39936
	global_load_lds_dwordx4 v[224:225], off
	v_lshl_add_u64 v[224:225], s[26:27], 0, v[168:169]
	s_mov_b32 m0, s42
	s_nop 0
	global_load_lds_dwordx4 v[224:225], off
	s_waitcnt vmcnt(8)
	s_waitcnt lgkmcnt(0)
	s_setprio 1
	s_barrier
	v_mfma_f32_16x16x32_bf16 v[126:129], v[130:133], v[162:165], v[126:129]
	v_mfma_f32_16x16x32_bf16 v[122:125], v[138:141], v[162:165], v[122:125]
	v_mfma_f32_16x16x32_bf16 v[118:121], v[130:133], v[186:189], v[118:121]
	v_mfma_f32_16x16x32_bf16 v[106:109], v[138:141], v[186:189], v[106:109]
	v_mfma_f32_16x16x32_bf16 v[98:101], v[130:133], v[200:203], v[98:101]
	v_mfma_f32_16x16x32_bf16 v[90:93], v[138:141], v[200:203], v[90:93]
	v_mfma_f32_16x16x32_bf16 v[82:85], v[130:133], v[208:211], v[82:85]
	v_mfma_f32_16x16x32_bf16 v[74:77], v[138:141], v[208:211], v[74:77]
	v_mfma_f32_16x16x32_bf16 v[126:129], v[134:137], v[182:185], v[126:129]
	v_mfma_f32_16x16x32_bf16 v[122:125], v[142:145], v[182:185], v[122:125]
	v_mfma_f32_16x16x32_bf16 v[118:121], v[134:137], v[190:193], v[118:121]
	v_mfma_f32_16x16x32_bf16 v[106:109], v[142:145], v[190:193], v[106:109]
	v_mfma_f32_16x16x32_bf16 v[98:101], v[134:137], v[204:207], v[98:101]
	v_mfma_f32_16x16x32_bf16 v[90:93], v[142:145], v[204:207], v[90:93]
	v_mfma_f32_16x16x32_bf16 v[82:85], v[134:137], v[212:215], v[82:85]
	v_mfma_f32_16x16x32_bf16 v[74:77], v[142:145], v[212:215], v[74:77]
	v_mfma_f32_16x16x32_bf16 v[114:117], v[146:149], v[162:165], v[114:117]
	v_mfma_f32_16x16x32_bf16 v[110:113], v[154:157], v[162:165], v[110:113]
	v_mfma_f32_16x16x32_bf16 v[102:105], v[146:149], v[186:189], v[102:105]
	v_mfma_f32_16x16x32_bf16 v[94:97], v[154:157], v[186:189], v[94:97]
	v_mfma_f32_16x16x32_bf16 v[86:89], v[146:149], v[200:203], v[86:89]
	v_mfma_f32_16x16x32_bf16 v[78:81], v[154:157], v[200:203], v[78:81]
	v_mfma_f32_16x16x32_bf16 v[70:73], v[146:149], v[208:211], v[70:73]
	v_mfma_f32_16x16x32_bf16 v[66:69], v[154:157], v[208:211], v[66:69]
	v_mfma_f32_16x16x32_bf16 v[114:117], v[150:153], v[182:185], v[114:117]
	v_mfma_f32_16x16x32_bf16 v[110:113], v[158:161], v[182:185], v[110:113]
	v_mfma_f32_16x16x32_bf16 v[102:105], v[150:153], v[190:193], v[102:105]
	v_mfma_f32_16x16x32_bf16 v[94:97], v[158:161], v[190:193], v[94:97]
	v_mfma_f32_16x16x32_bf16 v[86:89], v[150:153], v[204:207], v[86:89]
	v_mfma_f32_16x16x32_bf16 v[78:81], v[158:161], v[204:207], v[78:81]
	v_mfma_f32_16x16x32_bf16 v[70:73], v[150:153], v[212:215], v[70:73]
	v_mfma_f32_16x16x32_bf16 v[66:69], v[158:161], v[212:215], v[66:69]
	s_barrier
; #define PG8_GAS __attribute__((address_space(1)))
; #define PG8_STAGE(bufoff, gbase, voff) do { _Pragma("unroll") for (int _i = 0; _i < 2; ++_i) \
;         __builtin_amdgcn_global_load_lds((const unsigned*)((const char*)(gbase) + (voff)[_i]), (PG8_LAS unsigned*)(lds + (bufoff) + ldsw + _i * 8192), 16, 0, 0); } while (0)
; #define PG8_LDA(dst, b, h) do { _Pragma("unroll") for (int m = 0; m < 4; ++m) _Pragma("unroll") for (int k = 0; k < 2; ++k) dst[m][k] = *(const PG8_LAS bf16x8*)(lds + PG8_SA(b, h) + aoff + m * 2048 + k * 1024); } while (0)
; #define PG8_WAIT_V(n) asm volatile("s_waitcnt vmcnt(" #n ")" ::: "memory")
; #define PG8_WAIT_L(n) asm volatile("s_waitcnt lgkmcnt(" #n ")" ::: "memory")
; #define PG8_BAR __builtin_amdgcn_s_barrier()
; #define PG8_SCHED __builtin_amdgcn_sched_barrier(0)
;     __device__ __forceinline__ void operator()(const f32x4 (&acc)[2][2][4][2], const Unit& un, int wr, int wc, int fr, int fq) const {
;         const int row0 = un.pm * BM + wr * 64 + fr, col0 = un.pn * BM + wc * 32 + 8 * fq;
;         u32x4 rr[2][4][2];
; #pragma unroll
;         for (int ai = 0; ai < 2; ++ai)
; #pragma unroll
;             for (int m = 0; m < 4; ++m)
; #pragma unroll
;                 for (int bj = 0; bj < 2; ++bj) rr[ai][m][bj] = *(const PG8_GAS u32x4*)((PG8_GAS bf16_t*)h + (size_t)(row0 + ai * HALF + m * 16) * 4096 + col0 + bj * HALF);
; template <class Epi, class Sched, bool ALIGN_EPI = false, bool SP2 = false, bool F8 = false>
; __device__ __forceinline__ void gemm_phase(PG8_LAS unsigned char* lds, const Gemm g, const Sched& S, const Epi& E) {
;     ...
;             PG8_LDA(At, 1, 1); PG8_STAGE(PG8_SB(1, 0), b3, voffB); PG8_STAGE(PG8_SB(1, 1), b3 + hB, voffB); PG8_STAGE(PG8_SA(1, 0), a3, voffA);
;             PG8_WAIT_V(8); PG8_WAIT_L(0); PG8_BAR; PG8_MMA(1, 0, At, B0); PG8_MMA(1, 1, At, B1); PG8_BAR; PG8_SCHED;
	s_setprio 0
	s_add_i32 s26, s56, s36
	v_lshl_add_u64 v[216:217], v[216:217], 0, s[14:15]
	s_mov_b32 m0, s26
	ds_read_b128 v[162:165], v199 offset:49152
	ds_read_b128 v[182:185], v199 offset:50176
	ds_read_b128 v[186:189], v199 offset:51200
	ds_read_b128 v[190:193], v199 offset:52224
	ds_read_b128 v[200:203], v199 offset:53248
	ds_read_b128 v[204:207], v199 offset:54272
	ds_read_b128 v[208:211], v199 offset:55296
	ds_read_b128 v[212:215], v199 offset:56320
	global_load_lds_dwordx4 v[216:217], off
	s_add_i32 m0, s26, 0x2000
	s_add_u32 s26, s30, 0x2b0080
	v_lshl_add_u64 v[216:217], v[218:219], 0, s[14:15]
	s_addc_u32 s27, s31, 0
	s_add_i32 s30, s57, s36
	global_load_lds_dwordx4 v[216:217], off
	v_lshl_add_u64 v[216:217], s[26:27], 0, v[170:171]
	s_mov_b32 m0, s30
	s_nop 0
	global_load_lds_dwordx4 v[216:217], off
	v_lshl_add_u64 v[216:217], s[26:27], 0, v[166:167]
	s_add_i32 m0, s30, 0x2000
	s_nop 0
	global_load_lds_dwordx4 v[216:217], off
	v_lshl_add_u64 v[216:217], v[220:221], 0, s[14:15]
	s_mov_b32 m0, s44
	s_nop 0
	global_load_lds_dwordx4 v[216:217], off
	v_lshl_add_u64 v[216:217], v[222:223], 0, s[14:15]
	s_mov_b32 m0, s45
	s_nop 0
	global_load_lds_dwordx4 v[216:217], off
	s_waitcnt vmcnt(8)
	s_waitcnt lgkmcnt(0)
	s_setprio 1
	s_barrier
	v_mfma_f32_16x16x32_bf16 v[62:65], v[130:133], v[162:165], v[62:65]
	v_mfma_f32_16x16x32_bf16 v[58:61], v[138:141], v[162:165], v[58:61]
	v_mfma_f32_16x16x32_bf16 v[50:53], v[130:133], v[186:189], v[50:53]
	v_mfma_f32_16x16x32_bf16 v[42:45], v[138:141], v[186:189], v[42:45]
	v_mfma_f32_16x16x32_bf16 v[34:37], v[130:133], v[200:203], v[34:37]
	v_mfma_f32_16x16x32_bf16 v[26:29], v[138:141], v[200:203], v[26:29]
	v_mfma_f32_16x16x32_bf16 v[18:21], v[130:133], v[208:211], v[18:21]
	v_mfma_f32_16x16x32_bf16 v[10:13], v[138:141], v[208:211], v[10:13]
	v_mfma_f32_16x16x32_bf16 v[62:65], v[134:137], v[182:185], v[62:65]
	v_mfma_f32_16x16x32_bf16 v[58:61], v[142:145], v[182:185], v[58:61]
	v_mfma_f32_16x16x32_bf16 v[50:53], v[134:137], v[190:193], v[50:53]
	v_mfma_f32_16x16x32_bf16 v[42:45], v[142:145], v[190:193], v[42:45]
	v_mfma_f32_16x16x32_bf16 v[34:37], v[134:137], v[204:207], v[34:37]
	v_mfma_f32_16x16x32_bf16 v[26:29], v[142:145], v[204:207], v[26:29]
	v_mfma_f32_16x16x32_bf16 v[18:21], v[134:137], v[212:215], v[18:21]
	v_mfma_f32_16x16x32_bf16 v[10:13], v[142:145], v[212:215], v[10:13]
	v_mfma_f32_16x16x32_bf16 v[54:57], v[146:149], v[162:165], v[54:57]
	v_mfma_f32_16x16x32_bf16 v[46:49], v[154:157], v[162:165], v[46:49]
	v_mfma_f32_16x16x32_bf16 v[38:41], v[146:149], v[186:189], v[38:41]
	v_mfma_f32_16x16x32_bf16 v[30:33], v[154:157], v[186:189], v[30:33]
	v_mfma_f32_16x16x32_bf16 v[22:25], v[146:149], v[200:203], v[22:25]
	v_mfma_f32_16x16x32_bf16 v[14:17], v[154:157], v[200:203], v[14:17]
	v_mfma_f32_16x16x32_bf16 v[6:9], v[146:149], v[208:211], v[6:9]
	v_mfma_f32_16x16x32_bf16 v[2:5], v[154:157], v[208:211], v[2:5]
	v_mfma_f32_16x16x32_bf16 v[54:57], v[150:153], v[182:185], v[54:57]
	v_mfma_f32_16x16x32_bf16 v[46:49], v[158:161], v[182:185], v[46:49]
	v_mfma_f32_16x16x32_bf16 v[38:41], v[150:153], v[190:193], v[38:41]
	v_mfma_f32_16x16x32_bf16 v[30:33], v[158:161], v[190:193], v[30:33]
	v_mfma_f32_16x16x32_bf16 v[22:25], v[150:153], v[204:207], v[22:25]
	v_mfma_f32_16x16x32_bf16 v[14:17], v[158:161], v[204:207], v[14:17]
	v_mfma_f32_16x16x32_bf16 v[6:9], v[150:153], v[212:215], v[6:9]
	v_mfma_f32_16x16x32_bf16 v[2:5], v[158:161], v[212:215], v[2:5]
	s_barrier
	s_setprio 0
	s_add_i32 s55, s55, 2
	s_add_u32 s53, s53, 0x100
	s_addc_u32 s54, s54, 0
	s_cmpk_gt_u32 s55, 0xa9
	s_mov_b64 s[26:27], s[28:29]
	s_cbranch_scc0 .LBB0_1078
	v_lshl_or_b32 v132, s52, 8, v196
	v_lshl_add_u32 v130, s51, 8, v194
	v_ashrrev_i32_e32 v133, 31, v132
	v_lshlrev_b64 v[182:183], 1, v[132:133]
	v_ashrrev_i32_e32 v131, 31, v130
	v_lshl_add_u64 v[132:133], s[12:13], 0, v[182:183]
	v_lshlrev_b64 v[134:135], 13, v[130:131]
	v_lshl_add_u64 v[136:137], v[132:133], 0, v[134:135]
	global_load_dwordx4 v[200:203], v[136:137], off
	global_load_dwordx4 v[204:207], v[136:137], off offset:256
	v_or_b32_e32 v136, 16, v130
	v_ashrrev_i32_e32 v137, 31, v136
	v_lshlrev_b64 v[228:229], 13, v[136:137]
	v_lshl_add_u64 v[136:137], v[132:133], 0, v[228:229]
	global_load_dwordx4 v[208:211], v[136:137], off
	global_load_dwordx4 v[212:215], v[136:137], off offset:256
	v_or_b32_e32 v138, 32, v130
	v_or_b32_e32 v130, 48, v130
	v_ashrrev_i32_e32 v139, 31, v138
	v_ashrrev_i32_e32 v131, 31, v130
	v_lshlrev_b64 v[230:231], 13, v[138:139]
	v_lshlrev_b64 v[192:193], 13, v[130:131]
	v_lshl_add_u64 v[190:191], v[134:135], 0, s[16:17]
	v_lshl_add_u64 v[188:189], v[134:135], 0, s[20:21]
	v_lshl_add_u64 v[186:187], v[134:135], 0, s[22:23]
	v_lshl_add_u64 v[184:185], v[134:135], 0, s[24:25]
	v_lshl_add_u64 v[130:131], s[12:13], 0, v[134:135]
	v_lshl_add_u64 v[134:135], v[132:133], 0, v[230:231]
	v_lshl_add_u64 v[136:137], v[132:133], 0, v[192:193]
	v_lshl_add_u64 v[138:139], v[132:133], 0, v[190:191]
	v_lshl_add_u64 v[140:141], v[132:133], 0, v[188:189]
	v_lshl_add_u64 v[232:233], v[132:133], 0, v[186:187]
	v_lshl_add_u64 v[132:133], v[132:133], 0, v[184:185]
	v_lshl_add_u64 v[234:235], v[130:131], 0, v[182:183]
	global_load_dwordx4 v[216:219], v[134:135], off
	global_load_dwordx4 v[220:223], v[134:135], off offset:256
	global_load_dwordx4 v[224:227], v[136:137], off
	global_load_dwordx4 v[162:165], v[136:137], off offset:256
	global_load_dwordx4 v[158:161], v[138:139], off
	global_load_dwordx4 v[154:157], v[138:139], off offset:256
	global_load_dwordx4 v[150:153], v[140:141], off
	global_load_dwordx4 v[146:149], v[140:141], off offset:256
	global_load_dwordx4 v[142:145], v[232:233], off
	s_nop 0
	global_load_dwordx4 v[138:141], v[232:233], off offset:256
	global_load_dwordx4 v[134:137], v[132:133], off
	s_nop 0
	global_load_dwordx4 v[130:133], v[132:133], off offset:256
	s_and_b64 vcc, exec, s[4:5]
	s_mov_b32 s52, s49
	s_mov_b32 s51, s50
	s_mov_b64 s[28:29], s[8:9]
	s_mov_b64 s[26:27], s[6:7]
	s_waitcnt vmcnt(0)
; #define PG8_GAS __attribute__((address_space(1)))
; __device__ __forceinline__ unsigned cvt_pk_bf16(float lo, float hi) { const f32x2c v = {lo, hi}; return __builtin_bit_cast(unsigned, __builtin_convertvector(v, bf16x2c)); }
; __device__ __forceinline__ float bf_lo(unsigned w) { return __uint_as_float(w << 16); }
; __device__ __forceinline__ float bf_hi(unsigned w) { return __uint_as_float(w & 0xffff0000u); }
;     __device__ __forceinline__ void operator()(const f32x4 (&acc)[2][2][4][2], const Unit& un, int wr, int wc, int fr, int fq) const {
;     ...
; #pragma unroll
;         for (int ai = 0; ai < 2; ++ai)
; #pragma unroll
;             for (int m = 0; m < 4; ++m)
; #pragma unroll
;                 for (int bj = 0; bj < 2; ++bj) { const u32x4 r = rr[ai][m][bj]; const f32x4 v0 = acc[ai][bj][m][0], v1 = acc[ai][bj][m][1];
;                     u32x4 w; w.x = cvt_pk_bf16(v0[0] + bf_lo(r.x), v0[1] + bf_hi(r.x)); w.y = cvt_pk_bf16(v0[2] + bf_lo(r.y), v0[3] + bf_hi(r.y));
;                     w.z = cvt_pk_bf16(v1[0] + bf_lo(r.z), v1[1] + bf_hi(r.z)); w.w = cvt_pk_bf16(v1[2] + bf_lo(r.w), v1[3] + bf_hi(r.w));
;                     *(PG8_GAS u32x4*)((PG8_GAS bf16_t*)h + (size_t)(row0 + ai * HALF + m * 16) * 4096 + col0 + bj * HALF) = w; }
	v_lshlrev_b32_e32 v232, 16, v200
	v_and_b32_e32 v233, 0xffff0000, v200
	v_lshlrev_b32_e32 v200, 16, v201
	v_and_b32_e32 v201, 0xffff0000, v201
	v_lshlrev_b32_e32 v236, 16, v202
	v_and_b32_e32 v237, 0xffff0000, v202
	v_lshlrev_b32_e32 v202, 16, v203
	v_and_b32_e32 v203, 0xffff0000, v203
	v_lshlrev_b32_e32 v238, 16, v204
	v_and_b32_e32 v239, 0xffff0000, v204
	v_lshlrev_b32_e32 v204, 16, v205
	v_and_b32_e32 v205, 0xffff0000, v205
	v_lshlrev_b32_e32 v240, 16, v206
	v_and_b32_e32 v241, 0xffff0000, v206
	v_lshlrev_b32_e32 v206, 16, v207
	v_and_b32_e32 v207, 0xffff0000, v207
	v_pk_add_f32 v[126:127], v[126:127], v[232:233]
	v_pk_add_f32 v[128:129], v[128:129], v[200:201]
	v_pk_add_f32 v[122:123], v[122:123], v[236:237]
	v_pk_add_f32 v[124:125], v[124:125], v[202:203]
	v_pk_add_f32 v[114:115], v[114:115], v[238:239]
	v_pk_add_f32 v[116:117], v[116:117], v[204:205]
	v_pk_add_f32 v[200:201], v[110:111], v[240:241]
	v_pk_add_f32 v[202:203], v[112:113], v[206:207]
	v_cvt_pk_bf16_f32 v110, v126, v127
	v_cvt_pk_bf16_f32 v111, v128, v129
	v_cvt_pk_bf16_f32 v112, v122, v123
	v_cvt_pk_bf16_f32 v113, v124, v125
	v_lshlrev_b32_e32 v242, 16, v208
	v_and_b32_e32 v243, 0xffff0000, v208
	v_lshlrev_b32_e32 v208, 16, v209
	v_and_b32_e32 v209, 0xffff0000, v209
	v_cvt_pk_bf16_f32 v114, v114, v115
	v_cvt_pk_bf16_f32 v115, v116, v117
	v_cvt_pk_bf16_f32 v116, v200, v201
	v_cvt_pk_bf16_f32 v117, v202, v203
	global_store_dwordx4 v[234:235], v[110:113], off
	global_store_dwordx4 v[234:235], v[114:117], off offset:256
	v_pk_add_f32 v[118:119], v[118:119], v[242:243]
	v_lshlrev_b32_e32 v110, 16, v210
	v_and_b32_e32 v111, 0xffff0000, v210
	v_pk_add_f32 v[120:121], v[120:121], v[208:209]
	v_pk_add_f32 v[106:107], v[106:107], v[110:111]
	v_cvt_pk_bf16_f32 v118, v118, v119
	v_cvt_pk_bf16_f32 v119, v120, v121
	v_cvt_pk_bf16_f32 v120, v106, v107
	v_lshlrev_b32_e32 v106, 16, v211
	v_and_b32_e32 v107, 0xffff0000, v211
	v_pk_add_f32 v[106:107], v[108:109], v[106:107]
	v_lshlrev_b32_e32 v108, 16, v212
	v_and_b32_e32 v109, 0xffff0000, v212
	v_pk_add_f32 v[102:103], v[102:103], v[108:109]
	v_lshlrev_b32_e32 v108, 16, v213
	v_and_b32_e32 v109, 0xffff0000, v213
	v_pk_add_f32 v[104:105], v[104:105], v[108:109]
	v_cvt_pk_bf16_f32 v102, v102, v103
	v_cvt_pk_bf16_f32 v103, v104, v105
	v_lshlrev_b32_e32 v104, 16, v214
	v_and_b32_e32 v105, 0xffff0000, v214
	v_pk_add_f32 v[94:95], v[94:95], v[104:105]
	v_cvt_pk_bf16_f32 v121, v106, v107
	v_cvt_pk_bf16_f32 v104, v94, v95
	v_lshlrev_b32_e32 v94, 16, v215
	v_and_b32_e32 v95, 0xffff0000, v215
	v_pk_add_f32 v[94:95], v[96:97], v[94:95]
	v_lshlrev_b32_e32 v96, 16, v217
	v_cvt_pk_bf16_f32 v105, v94, v95
	v_lshlrev_b32_e32 v94, 16, v216
	v_and_b32_e32 v95, 0xffff0000, v216
	v_and_b32_e32 v97, 0xffff0000, v217
	v_pk_add_f32 v[94:95], v[98:99], v[94:95]
	v_pk_add_f32 v[96:97], v[100:101], v[96:97]
	v_cvt_pk_bf16_f32 v94, v94, v95
	v_cvt_pk_bf16_f32 v95, v96, v97
	v_lshlrev_b32_e32 v96, 16, v218
	v_and_b32_e32 v97, 0xffff0000, v218
	v_pk_add_f32 v[90:91], v[90:91], v[96:97]
	v_lshl_add_u64 v[106:107], s[12:13], 0, v[228:229]
	v_cvt_pk_bf16_f32 v96, v90, v91
	v_lshlrev_b32_e32 v90, 16, v219
	v_and_b32_e32 v91, 0xffff0000, v219
	v_pk_add_f32 v[90:91], v[92:93], v[90:91]
	v_lshlrev_b32_e32 v92, 16, v220
	v_and_b32_e32 v93, 0xffff0000, v220
	v_pk_add_f32 v[86:87], v[86:87], v[92:93]
	v_lshlrev_b32_e32 v92, 16, v221
	v_and_b32_e32 v93, 0xffff0000, v221
	v_pk_add_f32 v[88:89], v[88:89], v[92:93]
	v_cvt_pk_bf16_f32 v86, v86, v87
	v_cvt_pk_bf16_f32 v87, v88, v89
	v_lshlrev_b32_e32 v88, 16, v222
	v_and_b32_e32 v89, 0xffff0000, v222
	v_pk_add_f32 v[78:79], v[78:79], v[88:89]
	v_cvt_pk_bf16_f32 v97, v90, v91
	v_cvt_pk_bf16_f32 v88, v78, v79
	v_lshlrev_b32_e32 v78, 16, v223
	v_and_b32_e32 v79, 0xffff0000, v223
	v_pk_add_f32 v[78:79], v[80:81], v[78:79]
	v_lshlrev_b32_e32 v80, 16, v225
	v_cvt_pk_bf16_f32 v89, v78, v79
	v_lshlrev_b32_e32 v78, 16, v224
	v_and_b32_e32 v79, 0xffff0000, v224
	v_and_b32_e32 v81, 0xffff0000, v225
	v_pk_add_f32 v[78:79], v[82:83], v[78:79]
	v_pk_add_f32 v[80:81], v[84:85], v[80:81]
	v_cvt_pk_bf16_f32 v78, v78, v79
	v_cvt_pk_bf16_f32 v79, v80, v81
	v_lshlrev_b32_e32 v80, 16, v226
	v_and_b32_e32 v81, 0xffff0000, v226
	v_pk_add_f32 v[74:75], v[74:75], v[80:81]
	v_lshl_add_u64 v[90:91], s[12:13], 0, v[230:231]
	v_cvt_pk_bf16_f32 v80, v74, v75
	v_lshlrev_b32_e32 v74, 16, v227
	v_and_b32_e32 v75, 0xffff0000, v227
	v_pk_add_f32 v[74:75], v[76:77], v[74:75]
	v_lshlrev_b32_e32 v76, 16, v162
	v_and_b32_e32 v77, 0xffff0000, v162
	v_pk_add_f32 v[70:71], v[70:71], v[76:77]
	v_lshlrev_b32_e32 v76, 16, v163
	v_and_b32_e32 v77, 0xffff0000, v163
	v_pk_add_f32 v[72:73], v[72:73], v[76:77]
	v_cvt_pk_bf16_f32 v70, v70, v71
	v_cvt_pk_bf16_f32 v71, v72, v73
	v_lshlrev_b32_e32 v72, 16, v164
	v_and_b32_e32 v73, 0xffff0000, v164
	v_pk_add_f32 v[66:67], v[66:67], v[72:73]
	v_cvt_pk_bf16_f32 v81, v74, v75
	v_cvt_pk_bf16_f32 v72, v66, v67
	v_lshlrev_b32_e32 v66, 16, v165
	v_and_b32_e32 v67, 0xffff0000, v165
	v_pk_add_f32 v[66:67], v[68:69], v[66:67]
	v_lshl_add_u64 v[74:75], s[12:13], 0, v[192:193]
	v_cvt_pk_bf16_f32 v73, v66, v67
	v_lshlrev_b32_e32 v66, 16, v158
	v_and_b32_e32 v67, 0xffff0000, v158
	v_pk_add_f32 v[62:63], v[62:63], v[66:67]
	v_lshlrev_b32_e32 v66, 16, v159
	v_and_b32_e32 v67, 0xffff0000, v159
	v_pk_add_f32 v[64:65], v[64:65], v[66:67]
	v_cvt_pk_bf16_f32 v62, v62, v63
	v_cvt_pk_bf16_f32 v63, v64, v65
	v_lshlrev_b32_e32 v64, 16, v160
	v_and_b32_e32 v65, 0xffff0000, v160
	v_pk_add_f32 v[58:59], v[58:59], v[64:65]
	v_lshl_add_u64 v[106:107], v[106:107], 0, v[182:183]
; #define PG8_GAS __attribute__((address_space(1)))
; __device__ __forceinline__ unsigned cvt_pk_bf16(float lo, float hi) { const f32x2c v = {lo, hi}; return __builtin_bit_cast(unsigned, __builtin_convertvector(v, bf16x2c)); }
; __device__ __forceinline__ float bf_lo(unsigned w) { return __uint_as_float(w << 16); }
; __device__ __forceinline__ float bf_hi(unsigned w) { return __uint_as_float(w & 0xffff0000u); }
;     __device__ __forceinline__ void operator()(const f32x4 (&acc)[2][2][4][2], const Unit& un, int wr, int wc, int fr, int fq) const {
;     ...
; #pragma unroll
;         for (int ai = 0; ai < 2; ++ai)
; #pragma unroll
;             for (int m = 0; m < 4; ++m)
; #pragma unroll
;                 for (int bj = 0; bj < 2; ++bj) { const u32x4 r = rr[ai][m][bj]; const f32x4 v0 = acc[ai][bj][m][0], v1 = acc[ai][bj][m][1];
;                     u32x4 w; w.x = cvt_pk_bf16(v0[0] + bf_lo(r.x), v0[1] + bf_hi(r.x)); w.y = cvt_pk_bf16(v0[2] + bf_lo(r.y), v0[3] + bf_hi(r.y));
;                     w.z = cvt_pk_bf16(v1[0] + bf_lo(r.z), v1[1] + bf_hi(r.z)); w.w = cvt_pk_bf16(v1[2] + bf_lo(r.w), v1[3] + bf_hi(r.w));
;                     *(PG8_GAS u32x4*)((PG8_GAS bf16_t*)h + (size_t)(row0 + ai * HALF + m * 16) * 4096 + col0 + bj * HALF) = w; }
	v_cvt_pk_bf16_f32 v64, v58, v59
	v_lshlrev_b32_e32 v58, 16, v161
	v_and_b32_e32 v59, 0xffff0000, v161
	v_pk_add_f32 v[58:59], v[60:61], v[58:59]
	v_lshlrev_b32_e32 v60, 16, v154
	v_and_b32_e32 v61, 0xffff0000, v154
	v_pk_add_f32 v[54:55], v[54:55], v[60:61]
	v_lshlrev_b32_e32 v60, 16, v155
	v_and_b32_e32 v61, 0xffff0000, v155
	v_pk_add_f32 v[56:57], v[56:57], v[60:61]
	v_cvt_pk_bf16_f32 v54, v54, v55
	v_cvt_pk_bf16_f32 v55, v56, v57
	v_lshlrev_b32_e32 v56, 16, v156
	v_and_b32_e32 v57, 0xffff0000, v156
	v_pk_add_f32 v[46:47], v[46:47], v[56:57]
	v_cvt_pk_bf16_f32 v65, v58, v59
	v_cvt_pk_bf16_f32 v56, v46, v47
	v_lshlrev_b32_e32 v46, 16, v157
	v_and_b32_e32 v47, 0xffff0000, v157
	v_pk_add_f32 v[46:47], v[48:49], v[46:47]
	v_lshlrev_b32_e32 v48, 16, v151
	v_cvt_pk_bf16_f32 v57, v46, v47
	v_lshlrev_b32_e32 v46, 16, v150
	v_and_b32_e32 v47, 0xffff0000, v150
	v_and_b32_e32 v49, 0xffff0000, v151
	v_pk_add_f32 v[46:47], v[50:51], v[46:47]
	v_pk_add_f32 v[48:49], v[52:53], v[48:49]
	v_cvt_pk_bf16_f32 v46, v46, v47
	v_cvt_pk_bf16_f32 v47, v48, v49
	v_lshlrev_b32_e32 v48, 16, v152
	v_and_b32_e32 v49, 0xffff0000, v152
	v_pk_add_f32 v[42:43], v[42:43], v[48:49]
	v_lshl_add_u64 v[58:59], s[12:13], 0, v[190:191]
	v_cvt_pk_bf16_f32 v48, v42, v43
	v_lshlrev_b32_e32 v42, 16, v153
	v_and_b32_e32 v43, 0xffff0000, v153
	v_pk_add_f32 v[42:43], v[44:45], v[42:43]
	v_lshlrev_b32_e32 v44, 16, v146
	v_and_b32_e32 v45, 0xffff0000, v146
	v_pk_add_f32 v[38:39], v[38:39], v[44:45]
	v_lshlrev_b32_e32 v44, 16, v147
	v_and_b32_e32 v45, 0xffff0000, v147
	v_pk_add_f32 v[40:41], v[40:41], v[44:45]
	v_cvt_pk_bf16_f32 v38, v38, v39
	v_cvt_pk_bf16_f32 v39, v40, v41
	v_lshlrev_b32_e32 v40, 16, v148
	v_and_b32_e32 v41, 0xffff0000, v148
	v_pk_add_f32 v[30:31], v[30:31], v[40:41]
	v_cvt_pk_bf16_f32 v49, v42, v43
	v_cvt_pk_bf16_f32 v40, v30, v31
	v_lshlrev_b32_e32 v30, 16, v149
	v_and_b32_e32 v31, 0xffff0000, v149
	v_pk_add_f32 v[30:31], v[32:33], v[30:31]
	v_lshlrev_b32_e32 v32, 16, v143
	v_cvt_pk_bf16_f32 v41, v30, v31
	v_lshlrev_b32_e32 v30, 16, v142
	v_and_b32_e32 v31, 0xffff0000, v142
	v_and_b32_e32 v33, 0xffff0000, v143
	v_pk_add_f32 v[30:31], v[34:35], v[30:31]
	v_pk_add_f32 v[32:33], v[36:37], v[32:33]
	v_cvt_pk_bf16_f32 v30, v30, v31
	v_cvt_pk_bf16_f32 v31, v32, v33
	v_lshlrev_b32_e32 v32, 16, v144
	v_and_b32_e32 v33, 0xffff0000, v144
	v_pk_add_f32 v[26:27], v[26:27], v[32:33]
	v_lshl_add_u64 v[42:43], s[12:13], 0, v[188:189]
	v_cvt_pk_bf16_f32 v32, v26, v27
	v_lshlrev_b32_e32 v26, 16, v145
	v_and_b32_e32 v27, 0xffff0000, v145
	v_pk_add_f32 v[26:27], v[28:29], v[26:27]
	v_lshlrev_b32_e32 v28, 16, v138
	v_and_b32_e32 v29, 0xffff0000, v138
	v_pk_add_f32 v[22:23], v[22:23], v[28:29]
	v_lshlrev_b32_e32 v28, 16, v139
	v_and_b32_e32 v29, 0xffff0000, v139
	v_pk_add_f32 v[24:25], v[24:25], v[28:29]
	v_cvt_pk_bf16_f32 v22, v22, v23
	v_cvt_pk_bf16_f32 v23, v24, v25
	v_lshlrev_b32_e32 v24, 16, v140
	v_and_b32_e32 v25, 0xffff0000, v140
	v_pk_add_f32 v[14:15], v[14:15], v[24:25]
	v_cvt_pk_bf16_f32 v33, v26, v27
	v_cvt_pk_bf16_f32 v24, v14, v15
	v_lshlrev_b32_e32 v14, 16, v141
	v_and_b32_e32 v15, 0xffff0000, v141
	v_pk_add_f32 v[14:15], v[16:17], v[14:15]
	v_lshlrev_b32_e32 v16, 16, v135
	v_cvt_pk_bf16_f32 v25, v14, v15
	v_lshlrev_b32_e32 v14, 16, v134
	v_and_b32_e32 v15, 0xffff0000, v134
	v_and_b32_e32 v17, 0xffff0000, v135
	v_pk_add_f32 v[14:15], v[18:19], v[14:15]
	v_pk_add_f32 v[16:17], v[20:21], v[16:17]
	v_cvt_pk_bf16_f32 v14, v14, v15
	v_cvt_pk_bf16_f32 v15, v16, v17
	v_lshlrev_b32_e32 v16, 16, v136
	v_and_b32_e32 v17, 0xffff0000, v136
	v_pk_add_f32 v[10:11], v[10:11], v[16:17]
	v_lshl_add_u64 v[26:27], s[12:13], 0, v[186:187]
	v_cvt_pk_bf16_f32 v16, v10, v11
	v_lshlrev_b32_e32 v10, 16, v137
	v_and_b32_e32 v11, 0xffff0000, v137
	v_pk_add_f32 v[10:11], v[12:13], v[10:11]
	v_lshlrev_b32_e32 v12, 16, v130
	v_and_b32_e32 v13, 0xffff0000, v130
	v_pk_add_f32 v[6:7], v[6:7], v[12:13]
	v_lshlrev_b32_e32 v12, 16, v131
	v_and_b32_e32 v13, 0xffff0000, v131
	v_pk_add_f32 v[8:9], v[8:9], v[12:13]
	v_cvt_pk_bf16_f32 v6, v6, v7
	v_cvt_pk_bf16_f32 v7, v8, v9
	v_lshlrev_b32_e32 v8, 16, v132
	v_and_b32_e32 v9, 0xffff0000, v132
	v_pk_add_f32 v[2:3], v[2:3], v[8:9]
	v_cvt_pk_bf16_f32 v17, v10, v11
	v_cvt_pk_bf16_f32 v8, v2, v3
	v_lshlrev_b32_e32 v2, 16, v133
	v_and_b32_e32 v3, 0xffff0000, v133
	v_lshl_add_u64 v[10:11], s[12:13], 0, v[184:185]
	v_pk_add_f32 v[2:3], v[4:5], v[2:3]
	v_lshl_add_u64 v[90:91], v[90:91], 0, v[182:183]
	v_lshl_add_u64 v[74:75], v[74:75], 0, v[182:183]
	v_lshl_add_u64 v[58:59], v[58:59], 0, v[182:183]
	v_lshl_add_u64 v[42:43], v[42:43], 0, v[182:183]
	v_lshl_add_u64 v[26:27], v[26:27], 0, v[182:183]
	v_lshl_add_u64 v[10:11], v[10:11], 0, v[182:183]
	v_cvt_pk_bf16_f32 v9, v2, v3
	global_store_dwordx4 v[106:107], v[118:121], off
	global_store_dwordx4 v[106:107], v[102:105], off offset:256
	global_store_dwordx4 v[90:91], v[94:97], off
	global_store_dwordx4 v[90:91], v[86:89], off offset:256
	global_store_dwordx4 v[74:75], v[78:81], off
	global_store_dwordx4 v[74:75], v[70:73], off offset:256
	global_store_dwordx4 v[58:59], v[62:65], off
	global_store_dwordx4 v[58:59], v[54:57], off offset:256
	global_store_dwordx4 v[42:43], v[46:49], off
	global_store_dwordx4 v[42:43], v[38:41], off offset:256
	global_store_dwordx4 v[26:27], v[30:33], off
	global_store_dwordx4 v[26:27], v[22:25], off offset:256
	global_store_dwordx4 v[10:11], v[14:17], off
	global_store_dwordx4 v[10:11], v[6:9], off offset:256
	s_cbranch_vccz .LBB0_1071
	s_waitcnt vmcnt(0)
	s_cmpk_gt_u32 s18, 0xff
	s_cbranch_scc1 .LBB0_1082
	s_barrier
